# GEMM load phases: LDS-DMA loads issued first, ds_read_b128 group last within each phase
# speedup vs baseline: 1.0001x; 1.0001x over previous
; #define PG8_STAGE(bufoff, gbase, voff) do { _Pragma("unroll") for (int _i = 0; _i < 2; ++_i) \
;         __builtin_amdgcn_global_load_lds((const unsigned*)((const char*)(gbase) + (voff)[_i]), (PG8_LAS unsigned*)(lds + (bufoff) + ldsw + _i * 8192), 16, 0, 0); } while (0)
; #define PG8_LDA(dst, b, h) do { _Pragma("unroll") for (int m = 0; m < 4; ++m) _Pragma("unroll") for (int k = 0; k < 2; ++k) dst[m][k] = *(const PG8_LAS bf16x8*)(lds + PG8_SA(b, h) + aoff + m * 2048 + k * 1024); } while (0)
; #define PG8_LDB(dst, b, h) do { _Pragma("unroll") for (int n = 0; n < 2; ++n) _Pragma("unroll") for (int k = 0; k < 2; ++k) dst[n][k] = *(const PG8_LAS bf16x8*)(lds + PG8_SB(b, h) + boff + n * 2048 + k * 1024); } while (0)
; #define PG8_MMA(ai, bj, At, Bt) do { __builtin_amdgcn_s_setprio(1); _Pragma("unroll") for (int m = 0; m < 4; ++m) _Pragma("unroll") for (int n = 0; n < 2; ++n) _Pragma("unroll") for (int k = 0; k < 2; ++k) \
;         acc[ai][bj][m][n] = __builtin_amdgcn_mfma_f32_16x16x32_bf16(Bt[n][k], At[m][k], acc[ai][bj][m][n], 0, 0, 0); __builtin_amdgcn_s_setprio(0); } while (0)
; #define PG8_WAIT_V(n) asm volatile("s_waitcnt vmcnt(" #n ")" ::: "memory")
; #define PG8_WAIT_L(n) asm volatile("s_waitcnt lgkmcnt(" #n ")" ::: "memory")
; template <class Epi, class Sched, bool ALIGN_EPI = false, bool SP2 = false>
; __device__ __forceinline__ void gemm_phase(PG8_LAS unsigned char* lds, const Gemm g, const Sched& S, const Epi& E) {
;     ...
;             const bool last = (t == nt - 2);
;             const char* a1 = cA + (size_t)(t + 1) * kstep;
;             const char* a2 = last ? nA : cA + (size_t)(t + 2) * kstep; const char* b2 = last ? nB : cB + (size_t)(t + 2) * kstep;
;             const char* a3 = a2 + kstep; const char* b3 = b2 + kstep;
;             if (last && has_next) S.a_ready(nxt);
;             if constexpr (SP2) {
;             PG8_LDB(B0, 0, 0); PG8_LDB(B1, 0, 1); PG8_SCHED; PG8_LDA(At, 0, 0); PG8_STAGE(PG8_SA(1, 1), a1 + hstepA, voffA);
;             PG8_WAIT_V(8); PG8_WAIT_L(0); PG8_BAR; PG8_MMA(0, 0, At, B0); PG8_MMA(0, 1, At, B1); PG8_BAR; PG8_SCHED;
;             PG8_LDA(At, 0, 1); PG8_STAGE(PG8_SB(0, 0), b2, voffB); PG8_STAGE(PG8_SB(0, 1), b2 + hstepB, voffB); PG8_STAGE(PG8_SA(0, 0), a2, voffA);
;             PG8_WAIT_V(8); PG8_WAIT_L(0); PG8_BAR; PG8_MMA(1, 0, At, B0); PG8_MMA(1, 1, At, B1); PG8_BAR; PG8_SCHED;
.LBB0_135:
	s_add_u32 s22, s20, 0xfffc0080
	s_addc_u32 s23, s21, -1
	s_add_i32 s28, 0, 0x10000
	s_cmp_eq_u32 s53, 12
	s_cselect_b32 s25, s12, s23
	s_cselect_b32 s24, s14, s22
	v_add_u32_e32 v138, s28, v141
	s_cselect_b32 s23, s15, s45
	s_cselect_b32 s22, s38, s43
	s_add_i32 s29, 0, 0x14000
	ds_read_b128 v[144:147], v138
	ds_read_b128 v[148:151], v138 offset:1024
	ds_read_b128 v[152:155], v138 offset:2048
	ds_read_b128 v[156:159], v138 offset:3072
	v_add_u32_e32 v138, s29, v141
	ds_read_b128 v[160:163], v138
	ds_read_b128 v[164:167], v138 offset:1024
	ds_read_b128 v[168:171], v138 offset:2048
	ds_read_b128 v[172:175], v138 offset:3072
	s_add_i32 m0, s26, 0xc000
	ds_read_b128 v[176:179], v143
	ds_read_b128 v[180:183], v143 offset:1024
	ds_read_b128 v[184:187], v143 offset:2048
	ds_read_b128 v[188:191], v143 offset:3072
	ds_read_b128 v[192:195], v143 offset:4096
	ds_read_b128 v[196:199], v143 offset:5120
	ds_read_b128 v[200:203], v143 offset:6144
	ds_read_b128 v[204:207], v143 offset:7168
	global_load_lds_dwordx4 v134, s[20:21]
	s_add_i32 m0, s26, 0xe000
	s_nop 0
	global_load_lds_dwordx4 v136, s[20:21]
	s_waitcnt vmcnt(8)
	s_waitcnt lgkmcnt(0)
	s_barrier
	s_waitcnt lgkmcnt(0)
	v_mfma_f32_16x16x32_bf16 v[124:127], v[144:147], v[176:179], v[124:127]
	v_mfma_f32_16x16x32_bf16 v[120:123], v[152:155], v[176:179], v[120:123]
	v_mfma_f32_16x16x32_bf16 v[108:111], v[144:147], v[184:187], v[108:111]
	v_mfma_f32_16x16x32_bf16 v[104:107], v[152:155], v[184:187], v[104:107]
	v_mfma_f32_16x16x32_bf16 v[92:95], v[144:147], v[192:195], v[92:95]
	v_mfma_f32_16x16x32_bf16 v[88:91], v[152:155], v[192:195], v[88:91]
	v_mfma_f32_16x16x32_bf16 v[76:79], v[144:147], v[200:203], v[76:79]
	v_mfma_f32_16x16x32_bf16 v[72:75], v[152:155], v[200:203], v[72:75]
	v_mfma_f32_16x16x32_bf16 v[124:127], v[148:151], v[180:183], v[124:127]
	v_mfma_f32_16x16x32_bf16 v[120:123], v[156:159], v[180:183], v[120:123]
	v_mfma_f32_16x16x32_bf16 v[108:111], v[148:151], v[188:191], v[108:111]
	v_mfma_f32_16x16x32_bf16 v[104:107], v[156:159], v[188:191], v[104:107]
	v_mfma_f32_16x16x32_bf16 v[92:95], v[148:151], v[196:199], v[92:95]
	v_mfma_f32_16x16x32_bf16 v[88:91], v[156:159], v[196:199], v[88:91]
	v_mfma_f32_16x16x32_bf16 v[76:79], v[148:151], v[204:207], v[76:79]
	v_mfma_f32_16x16x32_bf16 v[72:75], v[156:159], v[204:207], v[72:75]
	v_mfma_f32_16x16x32_bf16 v[116:119], v[160:163], v[176:179], v[116:119]
	v_mfma_f32_16x16x32_bf16 v[112:115], v[168:171], v[176:179], v[112:115]
	v_mfma_f32_16x16x32_bf16 v[100:103], v[160:163], v[184:187], v[100:103]
	v_mfma_f32_16x16x32_bf16 v[96:99], v[168:171], v[184:187], v[96:99]
	v_mfma_f32_16x16x32_bf16 v[84:87], v[160:163], v[192:195], v[84:87]
	v_mfma_f32_16x16x32_bf16 v[80:83], v[168:171], v[192:195], v[80:83]
	v_mfma_f32_16x16x32_bf16 v[68:71], v[160:163], v[200:203], v[68:71]
	v_mfma_f32_16x16x32_bf16 v[64:67], v[168:171], v[200:203], v[64:67]
	v_mfma_f32_16x16x32_bf16 v[116:119], v[164:167], v[180:183], v[116:119]
	v_mfma_f32_16x16x32_bf16 v[112:115], v[172:175], v[180:183], v[112:115]
	v_mfma_f32_16x16x32_bf16 v[100:103], v[164:167], v[188:191], v[100:103]
	v_mfma_f32_16x16x32_bf16 v[96:99], v[172:175], v[188:191], v[96:99]
	v_mfma_f32_16x16x32_bf16 v[84:87], v[164:167], v[196:199], v[84:87]
	v_mfma_f32_16x16x32_bf16 v[80:83], v[172:175], v[196:199], v[80:83]
	v_mfma_f32_16x16x32_bf16 v[68:71], v[164:167], v[204:207], v[68:71]
	v_mfma_f32_16x16x32_bf16 v[64:67], v[172:175], v[204:207], v[64:67]
	s_barrier
	s_add_i32 s28, s28, s18
	v_lshl_add_u64 v[138:139], s[22:23], 0, v[208:209]
	s_mov_b32 m0, s28
	s_nop 0
	global_load_lds_dwordx4 v208, s[22:23]
	s_add_i32 m0, s28, 0x2000
	s_add_u32 s54, s22, 0x40000
	v_lshl_add_u64 v[210:211], s[22:23], 0, v[128:129]
	s_addc_u32 s55, s23, 0
	s_add_i32 s28, s29, s18
	global_load_lds_dwordx4 v128, s[22:23]
	s_mov_b32 m0, s28
	v_lshl_add_u64 v[222:223], s[24:25], 0, v[130:131]
	global_load_lds_dwordx4 v208, s[54:55]
	s_add_i32 m0, s28, 0x2000
	s_nop 0
	global_load_lds_dwordx4 v128, s[54:55]
	v_lshl_add_u64 v[212:213], s[24:25], 0, v[132:133]
	s_mov_b32 m0, s26
	s_nop 0
	global_load_lds_dwordx4 v132, s[24:25]
	s_mov_b32 m0, s34
	s_nop 0
	global_load_lds_dwordx4 v130, s[24:25]
	ds_read_b128 v[176:179], v143 offset:16384
	ds_read_b128 v[180:183], v143 offset:17408
	ds_read_b128 v[184:187], v143 offset:18432
	ds_read_b128 v[188:191], v143 offset:19456
	ds_read_b128 v[192:195], v143 offset:20480
	ds_read_b128 v[196:199], v143 offset:21504
	ds_read_b128 v[200:203], v143 offset:22528
	ds_read_b128 v[204:207], v143 offset:23552
	s_waitcnt vmcnt(8)
	s_waitcnt lgkmcnt(0)
	s_barrier
; #define PG8_STAGE(bufoff, gbase, voff) do { _Pragma("unroll") for (int _i = 0; _i < 2; ++_i) \
;         __builtin_amdgcn_global_load_lds((const unsigned*)((const char*)(gbase) + (voff)[_i]), (PG8_LAS unsigned*)(lds + (bufoff) + ldsw + _i * 8192), 16, 0, 0); } while (0)
; #define PG8_LDA(dst, b, h) do { _Pragma("unroll") for (int m = 0; m < 4; ++m) _Pragma("unroll") for (int k = 0; k < 2; ++k) dst[m][k] = *(const PG8_LAS bf16x8*)(lds + PG8_SA(b, h) + aoff + m * 2048 + k * 1024); } while (0)
; #define PG8_LDB(dst, b, h) do { _Pragma("unroll") for (int n = 0; n < 2; ++n) _Pragma("unroll") for (int k = 0; k < 2; ++k) dst[n][k] = *(const PG8_LAS bf16x8*)(lds + PG8_SB(b, h) + boff + n * 2048 + k * 1024); } while (0)
; #define PG8_MMA(ai, bj, At, Bt) do { __builtin_amdgcn_s_setprio(1); _Pragma("unroll") for (int m = 0; m < 4; ++m) _Pragma("unroll") for (int n = 0; n < 2; ++n) _Pragma("unroll") for (int k = 0; k < 2; ++k) \
;         acc[ai][bj][m][n] = __builtin_amdgcn_mfma_f32_16x16x32_bf16(Bt[n][k], At[m][k], acc[ai][bj][m][n], 0, 0, 0); __builtin_amdgcn_s_setprio(0); } while (0)
; #define PG8_WAIT_V(n) asm volatile("s_waitcnt vmcnt(" #n ")" ::: "memory")
; #define PG8_WAIT_L(n) asm volatile("s_waitcnt lgkmcnt(" #n ")" ::: "memory")
; #define PG8_BAR __builtin_amdgcn_s_barrier()
; #define PG8_SCHED __builtin_amdgcn_sched_barrier(0)
; template <class Epi, class Sched, bool ALIGN_EPI = false, bool SP2 = false>
; __device__ __forceinline__ void gemm_phase(PG8_LAS unsigned char* lds, const Gemm g, const Sched& S, const Epi& E) {
;     ...
;             PG8_WAIT_V(8); PG8_WAIT_L(0); PG8_BAR; PG8_MMA(0, 0, At, B0); PG8_MMA(0, 1, At, B1); PG8_BAR; PG8_SCHED;
;             PG8_LDA(At, 0, 1); PG8_STAGE(PG8_SB(0, 0), b2, voffB); PG8_STAGE(PG8_SB(0, 1), b2 + hstepB, voffB); PG8_STAGE(PG8_SA(0, 0), a2, voffA);
;             PG8_WAIT_V(8); PG8_WAIT_L(0); PG8_BAR; PG8_MMA(1, 0, At, B0); PG8_MMA(1, 1, At, B1); PG8_BAR; PG8_SCHED;
;             PG8_LDB(B0, 1, 0); PG8_LDB(B1, 1, 1); PG8_SCHED; PG8_LDA(At, 1, 0); PG8_STAGE(PG8_SA(0, 1), a2 + hstepA, voffA);
;             PG8_WAIT_V(8); PG8_WAIT_L(0); PG8_BAR; PG8_MMA(0, 0, At, B0); PG8_MMA(0, 1, At, B1); PG8_BAR; PG8_SCHED;
	s_waitcnt lgkmcnt(0)
	v_mfma_f32_16x16x32_bf16 v[60:63], v[144:147], v[176:179], v[60:63]
	v_mfma_f32_16x16x32_bf16 v[56:59], v[152:155], v[176:179], v[56:59]
	v_mfma_f32_16x16x32_bf16 v[44:47], v[144:147], v[184:187], v[44:47]
	v_mfma_f32_16x16x32_bf16 v[40:43], v[152:155], v[184:187], v[40:43]
	v_mfma_f32_16x16x32_bf16 v[28:31], v[144:147], v[192:195], v[28:31]
	v_mfma_f32_16x16x32_bf16 v[24:27], v[152:155], v[192:195], v[24:27]
	v_mfma_f32_16x16x32_bf16 v[12:15], v[144:147], v[200:203], v[12:15]
	v_mfma_f32_16x16x32_bf16 v[8:11], v[152:155], v[200:203], v[8:11]
	v_mfma_f32_16x16x32_bf16 v[60:63], v[148:151], v[180:183], v[60:63]
	v_mfma_f32_16x16x32_bf16 v[56:59], v[156:159], v[180:183], v[56:59]
	v_mfma_f32_16x16x32_bf16 v[44:47], v[148:151], v[188:191], v[44:47]
	v_mfma_f32_16x16x32_bf16 v[40:43], v[156:159], v[188:191], v[40:43]
	v_mfma_f32_16x16x32_bf16 v[28:31], v[148:151], v[196:199], v[28:31]
	v_mfma_f32_16x16x32_bf16 v[24:27], v[156:159], v[196:199], v[24:27]
	v_mfma_f32_16x16x32_bf16 v[12:15], v[148:151], v[204:207], v[12:15]
	v_mfma_f32_16x16x32_bf16 v[8:11], v[156:159], v[204:207], v[8:11]
	v_mfma_f32_16x16x32_bf16 v[52:55], v[160:163], v[176:179], v[52:55]
	v_mfma_f32_16x16x32_bf16 v[48:51], v[168:171], v[176:179], v[48:51]
	v_mfma_f32_16x16x32_bf16 v[36:39], v[160:163], v[184:187], v[36:39]
	v_mfma_f32_16x16x32_bf16 v[32:35], v[168:171], v[184:187], v[32:35]
	v_mfma_f32_16x16x32_bf16 v[20:23], v[160:163], v[192:195], v[20:23]
	v_mfma_f32_16x16x32_bf16 v[16:19], v[168:171], v[192:195], v[16:19]
	v_mfma_f32_16x16x32_bf16 v[4:7], v[160:163], v[200:203], v[4:7]
	v_mfma_f32_16x16x32_bf16 v[0:3], v[168:171], v[200:203], v[0:3]
	v_mfma_f32_16x16x32_bf16 v[52:55], v[164:167], v[180:183], v[52:55]
	v_mfma_f32_16x16x32_bf16 v[48:51], v[172:175], v[180:183], v[48:51]
	v_mfma_f32_16x16x32_bf16 v[36:39], v[164:167], v[188:191], v[36:39]
	v_mfma_f32_16x16x32_bf16 v[32:35], v[172:175], v[188:191], v[32:35]
	v_mfma_f32_16x16x32_bf16 v[20:23], v[164:167], v[196:199], v[20:23]
	v_mfma_f32_16x16x32_bf16 v[16:19], v[172:175], v[196:199], v[16:19]
	v_mfma_f32_16x16x32_bf16 v[4:7], v[164:167], v[204:207], v[4:7]
	v_mfma_f32_16x16x32_bf16 v[0:3], v[172:175], v[204:207], v[0:3]
	s_barrier
	s_add_i32 s28, 0, 0x18000
	s_add_i32 s29, 0, 0x1c000
	s_add_u32 s24, s24, 0x40000
	s_addc_u32 s25, s25, 0
	s_mov_b32 m0, s35
	s_nop 0
	global_load_lds_dwordx4 v132, s[24:25]
	v_lshl_add_u64 v[224:225], s[24:25], 0, v[130:131]
	s_mov_b32 m0, s39
	s_nop 0
	global_load_lds_dwordx4 v130, s[24:25]
	v_add_u32_e32 v156, s28, v141
	v_add_u32_e32 v172, s29, v141
	ds_read_b128 v[144:147], v156
	ds_read_b128 v[148:151], v156 offset:1024
	ds_read_b128 v[152:155], v156 offset:2048
	ds_read_b128 v[156:159], v156 offset:3072
	ds_read_b128 v[160:163], v172
	ds_read_b128 v[164:167], v172 offset:1024
	ds_read_b128 v[168:171], v172 offset:2048
	ds_read_b128 v[172:175], v172 offset:3072
	ds_read_b128 v[176:179], v143 offset:32768
	ds_read_b128 v[180:183], v143 offset:33792
	ds_read_b128 v[184:187], v143 offset:34816
	ds_read_b128 v[188:191], v143 offset:35840
	ds_read_b128 v[192:195], v143 offset:36864
	ds_read_b128 v[196:199], v143 offset:37888
	ds_read_b128 v[200:203], v143 offset:38912
	ds_read_b128 v[204:207], v143 offset:39936
	s_waitcnt vmcnt(8)
	s_waitcnt lgkmcnt(0)
	s_barrier
	s_waitcnt lgkmcnt(0)
	v_mfma_f32_16x16x32_bf16 v[124:127], v[144:147], v[176:179], v[124:127]
	v_mfma_f32_16x16x32_bf16 v[120:123], v[152:155], v[176:179], v[120:123]
	v_mfma_f32_16x16x32_bf16 v[108:111], v[144:147], v[184:187], v[108:111]
	v_mfma_f32_16x16x32_bf16 v[104:107], v[152:155], v[184:187], v[104:107]
	v_mfma_f32_16x16x32_bf16 v[92:95], v[144:147], v[192:195], v[92:95]
	v_mfma_f32_16x16x32_bf16 v[88:91], v[152:155], v[192:195], v[88:91]
	v_mfma_f32_16x16x32_bf16 v[76:79], v[144:147], v[200:203], v[76:79]
	v_mfma_f32_16x16x32_bf16 v[72:75], v[152:155], v[200:203], v[72:75]
	v_mfma_f32_16x16x32_bf16 v[124:127], v[148:151], v[180:183], v[124:127]
	v_mfma_f32_16x16x32_bf16 v[120:123], v[156:159], v[180:183], v[120:123]
	v_mfma_f32_16x16x32_bf16 v[108:111], v[148:151], v[188:191], v[108:111]
	v_mfma_f32_16x16x32_bf16 v[104:107], v[156:159], v[188:191], v[104:107]
	v_mfma_f32_16x16x32_bf16 v[92:95], v[148:151], v[196:199], v[92:95]
	v_mfma_f32_16x16x32_bf16 v[88:91], v[156:159], v[196:199], v[88:91]
	v_mfma_f32_16x16x32_bf16 v[76:79], v[148:151], v[204:207], v[76:79]
	v_mfma_f32_16x16x32_bf16 v[72:75], v[156:159], v[204:207], v[72:75]
	v_mfma_f32_16x16x32_bf16 v[116:119], v[160:163], v[176:179], v[116:119]
	v_mfma_f32_16x16x32_bf16 v[112:115], v[168:171], v[176:179], v[112:115]
	v_mfma_f32_16x16x32_bf16 v[100:103], v[160:163], v[184:187], v[100:103]
	v_mfma_f32_16x16x32_bf16 v[96:99], v[168:171], v[184:187], v[96:99]
	v_mfma_f32_16x16x32_bf16 v[84:87], v[160:163], v[192:195], v[84:87]
	v_mfma_f32_16x16x32_bf16 v[80:83], v[168:171], v[192:195], v[80:83]
	v_mfma_f32_16x16x32_bf16 v[68:71], v[160:163], v[200:203], v[68:71]
	v_mfma_f32_16x16x32_bf16 v[64:67], v[168:171], v[200:203], v[64:67]
	v_mfma_f32_16x16x32_bf16 v[116:119], v[164:167], v[180:183], v[116:119]
	v_mfma_f32_16x16x32_bf16 v[112:115], v[172:175], v[180:183], v[112:115]
	v_mfma_f32_16x16x32_bf16 v[100:103], v[164:167], v[188:191], v[100:103]
	v_mfma_f32_16x16x32_bf16 v[96:99], v[172:175], v[188:191], v[96:99]
	v_mfma_f32_16x16x32_bf16 v[84:87], v[164:167], v[196:199], v[84:87]
	v_mfma_f32_16x16x32_bf16 v[80:83], v[172:175], v[196:199], v[80:83]
	v_mfma_f32_16x16x32_bf16 v[68:71], v[164:167], v[204:207], v[68:71]
	v_mfma_f32_16x16x32_bf16 v[64:67], v[172:175], v[204:207], v[64:67]
	s_barrier
; #define PG8_STAGE(bufoff, gbase, voff) do { _Pragma("unroll") for (int _i = 0; _i < 2; ++_i) \
;         __builtin_amdgcn_global_load_lds((const unsigned*)((const char*)(gbase) + (voff)[_i]), (PG8_LAS unsigned*)(lds + (bufoff) + ldsw + _i * 8192), 16, 0, 0); } while (0)
; #define PG8_LDA(dst, b, h) do { _Pragma("unroll") for (int m = 0; m < 4; ++m) _Pragma("unroll") for (int k = 0; k < 2; ++k) dst[m][k] = *(const PG8_LAS bf16x8*)(lds + PG8_SA(b, h) + aoff + m * 2048 + k * 1024); } while (0)
; #define PG8_MMA(ai, bj, At, Bt) do { __builtin_amdgcn_s_setprio(1); _Pragma("unroll") for (int m = 0; m < 4; ++m) _Pragma("unroll") for (int n = 0; n < 2; ++n) _Pragma("unroll") for (int k = 0; k < 2; ++k) \
;         acc[ai][bj][m][n] = __builtin_amdgcn_mfma_f32_16x16x32_bf16(Bt[n][k], At[m][k], acc[ai][bj][m][n], 0, 0, 0); __builtin_amdgcn_s_setprio(0); } while (0)
; #define PG8_WAIT_V(n) asm volatile("s_waitcnt vmcnt(" #n ")" ::: "memory")
; #define PG8_WAIT_L(n) asm volatile("s_waitcnt lgkmcnt(" #n ")" ::: "memory")
; #define PG8_BAR __builtin_amdgcn_s_barrier()
; #define PG8_SCHED __builtin_amdgcn_sched_barrier(0)
; template <class Epi, class Sched, bool ALIGN_EPI = false, bool SP2 = false>
; __device__ __forceinline__ void gemm_phase(PG8_LAS unsigned char* lds, const Gemm g, const Sched& S, const Epi& E) {
;     ...
;             PG8_WAIT_V(8); PG8_WAIT_L(0); PG8_BAR; PG8_MMA(0, 0, At, B0); PG8_MMA(0, 1, At, B1); PG8_BAR; PG8_SCHED;
;             PG8_LDA(At, 1, 1); PG8_STAGE(PG8_SB(1, 0), b3, voffB); PG8_STAGE(PG8_SB(1, 1), b3 + hstepB, voffB); PG8_STAGE(PG8_SA(1, 0), a3, voffA);
;             PG8_WAIT_V(8); PG8_WAIT_L(0); PG8_BAR; PG8_MMA(1, 0, At, B0); PG8_MMA(1, 1, At, B1); PG8_BAR; PG8_SCHED;
;     ...
;         if constexpr (ALIGN_EPI) { if (wr == 0) PG8_BAR; }
	s_add_i32 s24, s28, s18
	v_lshl_add_u64 v[138:139], v[138:139], 0, s[10:11]
	s_mov_b32 m0, s24
	s_nop 0
	global_load_lds_dwordx4 v[138:139], off
	s_add_i32 m0, s24, 0x2000
	s_add_u32 s22, s22, 0x40080
	v_lshl_add_u64 v[138:139], v[210:211], 0, s[10:11]
	s_addc_u32 s23, s23, 0
	s_add_i32 s24, s29, s18
	global_load_lds_dwordx4 v[138:139], off
	s_mov_b32 m0, s24
	s_nop 0
	global_load_lds_dwordx4 v208, s[22:23]
	s_add_i32 m0, s24, 0x2000
	s_nop 0
	global_load_lds_dwordx4 v128, s[22:23]
	v_lshl_add_u64 v[138:139], v[212:213], 0, s[10:11]
	s_mov_b32 m0, s50
	s_nop 0
	global_load_lds_dwordx4 v[138:139], off
	v_lshl_add_u64 v[138:139], v[222:223], 0, s[10:11]
	s_mov_b32 m0, s51
	s_nop 0
	global_load_lds_dwordx4 v[138:139], off
	ds_read_b128 v[176:179], v143 offset:49152
	ds_read_b128 v[180:183], v143 offset:50176
	ds_read_b128 v[184:187], v143 offset:51200
	ds_read_b128 v[188:191], v143 offset:52224
	ds_read_b128 v[192:195], v143 offset:53248
	ds_read_b128 v[196:199], v143 offset:54272
	ds_read_b128 v[200:203], v143 offset:55296
	ds_read_b128 v[204:207], v143 offset:56320
	s_waitcnt vmcnt(8)
	s_waitcnt lgkmcnt(0)
	s_barrier
	s_waitcnt lgkmcnt(0)
	v_mfma_f32_16x16x32_bf16 v[60:63], v[144:147], v[176:179], v[60:63]
	v_mfma_f32_16x16x32_bf16 v[56:59], v[152:155], v[176:179], v[56:59]
	v_mfma_f32_16x16x32_bf16 v[44:47], v[144:147], v[184:187], v[44:47]
	v_mfma_f32_16x16x32_bf16 v[40:43], v[152:155], v[184:187], v[40:43]
	v_mfma_f32_16x16x32_bf16 v[28:31], v[144:147], v[192:195], v[28:31]
	v_mfma_f32_16x16x32_bf16 v[24:27], v[152:155], v[192:195], v[24:27]
	v_mfma_f32_16x16x32_bf16 v[12:15], v[144:147], v[200:203], v[12:15]
	v_mfma_f32_16x16x32_bf16 v[8:11], v[152:155], v[200:203], v[8:11]
	v_mfma_f32_16x16x32_bf16 v[60:63], v[148:151], v[180:183], v[60:63]
	v_mfma_f32_16x16x32_bf16 v[56:59], v[156:159], v[180:183], v[56:59]
	v_mfma_f32_16x16x32_bf16 v[44:47], v[148:151], v[188:191], v[44:47]
	v_mfma_f32_16x16x32_bf16 v[40:43], v[156:159], v[188:191], v[40:43]
	v_mfma_f32_16x16x32_bf16 v[28:31], v[148:151], v[196:199], v[28:31]
	v_mfma_f32_16x16x32_bf16 v[24:27], v[156:159], v[196:199], v[24:27]
	v_mfma_f32_16x16x32_bf16 v[12:15], v[148:151], v[204:207], v[12:15]
	v_mfma_f32_16x16x32_bf16 v[8:11], v[156:159], v[204:207], v[8:11]
	v_mfma_f32_16x16x32_bf16 v[52:55], v[160:163], v[176:179], v[52:55]
	v_mfma_f32_16x16x32_bf16 v[48:51], v[168:171], v[176:179], v[48:51]
	v_mfma_f32_16x16x32_bf16 v[36:39], v[160:163], v[184:187], v[36:39]
	v_mfma_f32_16x16x32_bf16 v[32:35], v[168:171], v[184:187], v[32:35]
	v_mfma_f32_16x16x32_bf16 v[20:23], v[160:163], v[192:195], v[20:23]
	v_mfma_f32_16x16x32_bf16 v[16:19], v[168:171], v[192:195], v[16:19]
	v_mfma_f32_16x16x32_bf16 v[4:7], v[160:163], v[200:203], v[4:7]
	v_mfma_f32_16x16x32_bf16 v[0:3], v[168:171], v[200:203], v[0:3]
	v_mfma_f32_16x16x32_bf16 v[52:55], v[164:167], v[180:183], v[52:55]
	v_mfma_f32_16x16x32_bf16 v[48:51], v[172:175], v[180:183], v[48:51]
	v_mfma_f32_16x16x32_bf16 v[36:39], v[164:167], v[188:191], v[36:39]
	v_mfma_f32_16x16x32_bf16 v[32:35], v[172:175], v[188:191], v[32:35]
	v_mfma_f32_16x16x32_bf16 v[20:23], v[164:167], v[196:199], v[20:23]
	v_mfma_f32_16x16x32_bf16 v[16:19], v[172:175], v[196:199], v[16:19]
	v_mfma_f32_16x16x32_bf16 v[4:7], v[164:167], v[204:207], v[4:7]
	v_mfma_f32_16x16x32_bf16 v[0:3], v[172:175], v[204:207], v[0:3]
	s_barrier
	s_add_i32 s53, s53, 2
	s_add_u32 s20, s20, 0x100
	s_addc_u32 s21, s21, 0
	s_add_u32 s43, s43, 0x100
	s_addc_u32 s45, s45, 0
	s_cmp_gt_u32 s53, 13
	s_cbranch_scc0 .LBB0_135
	s_and_b64 vcc, exec, s[6:7]
	s_cbranch_vccz .LBB0_138
	s_barrier

; #define PG8_STAGE(bufoff, gbase, voff) do { _Pragma("unroll") for (int _i = 0; _i < 2; ++_i) \
;         __builtin_amdgcn_global_load_lds((const unsigned*)((const char*)(gbase) + (voff)[_i]), (PG8_LAS unsigned*)(lds + (bufoff) + ldsw + _i * 8192), 16, 0, 0); } while (0)
; #define PG8_LDA(dst, b, h) do { _Pragma("unroll") for (int m = 0; m < 4; ++m) _Pragma("unroll") for (int k = 0; k < 2; ++k) dst[m][k] = *(const PG8_LAS bf16x8*)(lds + PG8_SA(b, h) + aoff + m * 2048 + k * 1024); } while (0)
; #define PG8_LDB(dst, b, h) do { _Pragma("unroll") for (int n = 0; n < 2; ++n) _Pragma("unroll") for (int k = 0; k < 2; ++k) dst[n][k] = *(const PG8_LAS bf16x8*)(lds + PG8_SB(b, h) + boff + n * 2048 + k * 1024); } while (0)
; #define PG8_MMA(ai, bj, At, Bt) do { __builtin_amdgcn_s_setprio(1); _Pragma("unroll") for (int m = 0; m < 4; ++m) _Pragma("unroll") for (int n = 0; n < 2; ++n) _Pragma("unroll") for (int k = 0; k < 2; ++k) \
;         acc[ai][bj][m][n] = __builtin_amdgcn_mfma_f32_16x16x32_bf16(Bt[n][k], At[m][k], acc[ai][bj][m][n], 0, 0, 0); __builtin_amdgcn_s_setprio(0); } while (0)
; #define PG8_WAIT_V(n) asm volatile("s_waitcnt vmcnt(" #n ")" ::: "memory")
; #define PG8_WAIT_L(n) asm volatile("s_waitcnt lgkmcnt(" #n ")" ::: "memory")
; template <class Epi, class Sched, bool ALIGN_EPI = false, bool SP2 = false>
; __device__ __forceinline__ void gemm_phase(PG8_LAS unsigned char* lds, const Gemm g, const Sched& S, const Epi& E) {
;     ...
;             const bool last = (t == nt - 2);
;             const char* a1 = cA + (size_t)(t + 1) * kstep;
;             const char* a2 = last ? nA : cA + (size_t)(t + 2) * kstep; const char* b2 = last ? nB : cB + (size_t)(t + 2) * kstep;
;             const char* a3 = a2 + kstep; const char* b3 = b2 + kstep;
;             if (last && has_next) S.a_ready(nxt);
;             if constexpr (SP2) {
;             PG8_LDB(B0, 0, 0); PG8_LDB(B1, 0, 1); PG8_SCHED; PG8_LDA(At, 0, 0); PG8_STAGE(PG8_SA(1, 1), a1 + hstepA, voffA);
;             PG8_WAIT_V(8); PG8_WAIT_L(0); PG8_BAR; PG8_MMA(0, 0, At, B0); PG8_MMA(0, 1, At, B1); PG8_BAR; PG8_SCHED;
;             PG8_LDA(At, 0, 1); PG8_STAGE(PG8_SB(0, 0), b2, voffB); PG8_STAGE(PG8_SB(0, 1), b2 + hstepB, voffB); PG8_STAGE(PG8_SA(0, 0), a2, voffA);
;             PG8_WAIT_V(8); PG8_WAIT_L(0); PG8_BAR; PG8_MMA(1, 0, At, B0); PG8_MMA(1, 1, At, B1); PG8_BAR; PG8_SCHED;
.LBB0_215:
	s_add_u32 s20, s0, 0x100
	s_addc_u32 s21, s1, 0
	s_add_i32 s28, 0, 0x10000
	s_cmp_eq_u32 s51, 40
	s_cselect_b32 s25, s5, s21
	s_cselect_b32 s24, s4, s20
	v_add_u32_e32 v138, s28, v141
	s_cselect_b32 s23, s45, s15
	s_cselect_b32 s22, s44, s14
	s_add_i32 s29, 0, 0x14000
	ds_read_b128 v[134:137], v138
	ds_read_b128 v[144:147], v138 offset:1024
	ds_read_b128 v[148:151], v138 offset:2048
	ds_read_b128 v[152:155], v138 offset:3072
	v_add_u32_e32 v138, s29, v141
	ds_read_b128 v[156:159], v138
	ds_read_b128 v[160:163], v138 offset:1024
	ds_read_b128 v[164:167], v138 offset:2048
	ds_read_b128 v[168:171], v138 offset:3072
	v_lshl_add_u64 v[138:139], s[0:1], 0, v[130:131]
	s_add_i32 m0, s26, 0xc000
	ds_read_b128 v[172:175], v143
	ds_read_b128 v[176:179], v143 offset:1024
	ds_read_b128 v[180:183], v143 offset:2048
	ds_read_b128 v[184:187], v143 offset:3072
	ds_read_b128 v[188:191], v143 offset:4096
	ds_read_b128 v[192:195], v143 offset:5120
	ds_read_b128 v[196:199], v143 offset:6144
	ds_read_b128 v[200:203], v143 offset:7168
	global_load_lds_dwordx4 v[138:139], off
	v_lshl_add_u64 v[138:139], s[0:1], 0, v[132:133]
	s_add_i32 m0, s26, 0xe000
	s_nop 0
	global_load_lds_dwordx4 v[138:139], off
	s_waitcnt vmcnt(8)
	s_waitcnt lgkmcnt(0)
	s_barrier
	s_waitcnt lgkmcnt(0)
	v_mfma_f32_16x16x32_bf16 v[124:127], v[134:137], v[172:175], v[124:127]
	v_mfma_f32_16x16x32_bf16 v[120:123], v[148:151], v[172:175], v[120:123]
	v_mfma_f32_16x16x32_bf16 v[116:119], v[134:137], v[180:183], v[116:119]
	v_mfma_f32_16x16x32_bf16 v[112:115], v[148:151], v[180:183], v[112:115]
	v_mfma_f32_16x16x32_bf16 v[108:111], v[134:137], v[188:191], v[108:111]
	v_mfma_f32_16x16x32_bf16 v[100:103], v[148:151], v[188:191], v[100:103]
	v_mfma_f32_16x16x32_bf16 v[92:95], v[134:137], v[196:199], v[92:95]
	v_mfma_f32_16x16x32_bf16 v[80:83], v[148:151], v[196:199], v[80:83]
	v_mfma_f32_16x16x32_bf16 v[124:127], v[144:147], v[176:179], v[124:127]
	v_mfma_f32_16x16x32_bf16 v[120:123], v[152:155], v[176:179], v[120:123]
	v_mfma_f32_16x16x32_bf16 v[116:119], v[144:147], v[184:187], v[116:119]
	v_mfma_f32_16x16x32_bf16 v[112:115], v[152:155], v[184:187], v[112:115]
	v_mfma_f32_16x16x32_bf16 v[108:111], v[144:147], v[192:195], v[108:111]
	v_mfma_f32_16x16x32_bf16 v[100:103], v[152:155], v[192:195], v[100:103]
	v_mfma_f32_16x16x32_bf16 v[92:95], v[144:147], v[200:203], v[92:95]
	v_mfma_f32_16x16x32_bf16 v[80:83], v[152:155], v[200:203], v[80:83]
	v_mfma_f32_16x16x32_bf16 v[104:107], v[156:159], v[172:175], v[104:107]
	v_mfma_f32_16x16x32_bf16 v[96:99], v[164:167], v[172:175], v[96:99]
	v_mfma_f32_16x16x32_bf16 v[88:91], v[156:159], v[180:183], v[88:91]
	v_mfma_f32_16x16x32_bf16 v[84:87], v[164:167], v[180:183], v[84:87]
	v_mfma_f32_16x16x32_bf16 v[76:79], v[156:159], v[188:191], v[76:79]
	v_mfma_f32_16x16x32_bf16 v[72:75], v[164:167], v[188:191], v[72:75]
	v_mfma_f32_16x16x32_bf16 v[68:71], v[156:159], v[196:199], v[68:71]
	v_mfma_f32_16x16x32_bf16 v[64:67], v[164:167], v[196:199], v[64:67]
	v_mfma_f32_16x16x32_bf16 v[104:107], v[160:163], v[176:179], v[104:107]
	v_mfma_f32_16x16x32_bf16 v[96:99], v[168:171], v[176:179], v[96:99]
	v_mfma_f32_16x16x32_bf16 v[88:91], v[160:163], v[184:187], v[88:91]
	v_mfma_f32_16x16x32_bf16 v[84:87], v[168:171], v[184:187], v[84:87]
	v_mfma_f32_16x16x32_bf16 v[76:79], v[160:163], v[192:195], v[76:79]
	v_mfma_f32_16x16x32_bf16 v[72:75], v[168:171], v[192:195], v[72:75]
	v_mfma_f32_16x16x32_bf16 v[68:71], v[160:163], v[200:203], v[68:71]
	v_mfma_f32_16x16x32_bf16 v[64:67], v[168:171], v[200:203], v[64:67]
	s_barrier
	s_add_i32 s0, s28, s19
	v_lshl_add_u64 v[138:139], s[22:23], 0, v[208:209]
	s_mov_b32 m0, s0
	s_nop 0
	global_load_lds_dwordx4 v208, s[22:23]
	s_add_i32 m0, s0, 0x2000
	s_add_u32 s0, s22, 0xb0000
	v_lshl_add_u64 v[204:205], s[22:23], 0, v[128:129]
	s_addc_u32 s1, s23, 0
	s_add_i32 s28, s29, s19
	global_load_lds_dwordx4 v128, s[22:23]
	s_mov_b32 m0, s28
	v_lshl_add_u64 v[210:211], s[24:25], 0, v[128:129]
	global_load_lds_dwordx4 v208, s[0:1]
	s_add_i32 m0, s28, 0x2000
	s_nop 0
	global_load_lds_dwordx4 v128, s[0:1]
	v_lshl_add_u64 v[206:207], s[24:25], 0, v[208:209]
	s_mov_b32 m0, s26
	s_nop 0
	global_load_lds_dwordx4 v208, s[24:25]
	s_mov_b32 m0, s34
	s_nop 0
	global_load_lds_dwordx4 v128, s[24:25]
	ds_read_b128 v[172:175], v143 offset:16384
	ds_read_b128 v[176:179], v143 offset:17408
	ds_read_b128 v[180:183], v143 offset:18432
	ds_read_b128 v[184:187], v143 offset:19456
	ds_read_b128 v[188:191], v143 offset:20480
	ds_read_b128 v[192:195], v143 offset:21504
	ds_read_b128 v[196:199], v143 offset:22528
	ds_read_b128 v[200:203], v143 offset:23552
	s_waitcnt vmcnt(8)
	s_waitcnt lgkmcnt(0)
	s_barrier
; #define PG8_STAGE(bufoff, gbase, voff) do { _Pragma("unroll") for (int _i = 0; _i < 2; ++_i) \
;         __builtin_amdgcn_global_load_lds((const unsigned*)((const char*)(gbase) + (voff)[_i]), (PG8_LAS unsigned*)(lds + (bufoff) + ldsw + _i * 8192), 16, 0, 0); } while (0)
; #define PG8_LDA(dst, b, h) do { _Pragma("unroll") for (int m = 0; m < 4; ++m) _Pragma("unroll") for (int k = 0; k < 2; ++k) dst[m][k] = *(const PG8_LAS bf16x8*)(lds + PG8_SA(b, h) + aoff + m * 2048 + k * 1024); } while (0)
; #define PG8_LDB(dst, b, h) do { _Pragma("unroll") for (int n = 0; n < 2; ++n) _Pragma("unroll") for (int k = 0; k < 2; ++k) dst[n][k] = *(const PG8_LAS bf16x8*)(lds + PG8_SB(b, h) + boff + n * 2048 + k * 1024); } while (0)
; #define PG8_MMA(ai, bj, At, Bt) do { __builtin_amdgcn_s_setprio(1); _Pragma("unroll") for (int m = 0; m < 4; ++m) _Pragma("unroll") for (int n = 0; n < 2; ++n) _Pragma("unroll") for (int k = 0; k < 2; ++k) \
;         acc[ai][bj][m][n] = __builtin_amdgcn_mfma_f32_16x16x32_bf16(Bt[n][k], At[m][k], acc[ai][bj][m][n], 0, 0, 0); __builtin_amdgcn_s_setprio(0); } while (0)
; #define PG8_WAIT_V(n) asm volatile("s_waitcnt vmcnt(" #n ")" ::: "memory")
; #define PG8_WAIT_L(n) asm volatile("s_waitcnt lgkmcnt(" #n ")" ::: "memory")
; #define PG8_BAR __builtin_amdgcn_s_barrier()
; #define PG8_SCHED __builtin_amdgcn_sched_barrier(0)
; template <class Epi, class Sched, bool ALIGN_EPI = false, bool SP2 = false>
; __device__ __forceinline__ void gemm_phase(PG8_LAS unsigned char* lds, const Gemm g, const Sched& S, const Epi& E) {
;     ...
;             PG8_WAIT_V(8); PG8_WAIT_L(0); PG8_BAR; PG8_MMA(1, 0, At, B0); PG8_MMA(1, 1, At, B1); PG8_BAR; PG8_SCHED;
;             PG8_LDB(B0, 1, 0); PG8_LDB(B1, 1, 1); PG8_SCHED; PG8_LDA(At, 1, 0); PG8_STAGE(PG8_SA(0, 1), a2 + hstepA, voffA);
;             PG8_WAIT_V(8); PG8_WAIT_L(0); PG8_BAR; PG8_MMA(0, 0, At, B0); PG8_MMA(0, 1, At, B1); PG8_BAR; PG8_SCHED;
	s_waitcnt lgkmcnt(0)
	v_mfma_f32_16x16x32_bf16 v[60:63], v[134:137], v[172:175], v[60:63]
	v_mfma_f32_16x16x32_bf16 v[56:59], v[148:151], v[172:175], v[56:59]
	v_mfma_f32_16x16x32_bf16 v[52:55], v[134:137], v[180:183], v[52:55]
	v_mfma_f32_16x16x32_bf16 v[48:51], v[148:151], v[180:183], v[48:51]
	v_mfma_f32_16x16x32_bf16 v[44:47], v[134:137], v[188:191], v[44:47]
	v_mfma_f32_16x16x32_bf16 v[32:35], v[148:151], v[188:191], v[32:35]
	v_mfma_f32_16x16x32_bf16 v[16:19], v[134:137], v[196:199], v[16:19]
	v_mfma_f32_16x16x32_bf16 v[8:11], v[148:151], v[196:199], v[8:11]
	v_mfma_f32_16x16x32_bf16 v[60:63], v[144:147], v[176:179], v[60:63]
	v_mfma_f32_16x16x32_bf16 v[56:59], v[152:155], v[176:179], v[56:59]
	v_mfma_f32_16x16x32_bf16 v[52:55], v[144:147], v[184:187], v[52:55]
	v_mfma_f32_16x16x32_bf16 v[48:51], v[152:155], v[184:187], v[48:51]
	v_mfma_f32_16x16x32_bf16 v[44:47], v[144:147], v[192:195], v[44:47]
	v_mfma_f32_16x16x32_bf16 v[32:35], v[152:155], v[192:195], v[32:35]
	v_mfma_f32_16x16x32_bf16 v[16:19], v[144:147], v[200:203], v[16:19]
	v_mfma_f32_16x16x32_bf16 v[8:11], v[152:155], v[200:203], v[8:11]
	v_mfma_f32_16x16x32_bf16 v[40:43], v[156:159], v[172:175], v[40:43]
	v_mfma_f32_16x16x32_bf16 v[36:39], v[164:167], v[172:175], v[36:39]
	v_mfma_f32_16x16x32_bf16 v[28:31], v[156:159], v[180:183], v[28:31]
	v_mfma_f32_16x16x32_bf16 v[24:27], v[164:167], v[180:183], v[24:27]
	v_mfma_f32_16x16x32_bf16 v[20:23], v[156:159], v[188:191], v[20:23]
	v_mfma_f32_16x16x32_bf16 v[12:15], v[164:167], v[188:191], v[12:15]
	v_mfma_f32_16x16x32_bf16 v[4:7], v[156:159], v[196:199], v[4:7]
	v_mfma_f32_16x16x32_bf16 v[0:3], v[164:167], v[196:199], v[0:3]
	v_mfma_f32_16x16x32_bf16 v[40:43], v[160:163], v[176:179], v[40:43]
	v_mfma_f32_16x16x32_bf16 v[36:39], v[168:171], v[176:179], v[36:39]
	v_mfma_f32_16x16x32_bf16 v[28:31], v[160:163], v[184:187], v[28:31]
	v_mfma_f32_16x16x32_bf16 v[24:27], v[168:171], v[184:187], v[24:27]
	v_mfma_f32_16x16x32_bf16 v[20:23], v[160:163], v[192:195], v[20:23]
	v_mfma_f32_16x16x32_bf16 v[12:15], v[168:171], v[192:195], v[12:15]
	v_mfma_f32_16x16x32_bf16 v[4:7], v[160:163], v[200:203], v[4:7]
	v_mfma_f32_16x16x32_bf16 v[0:3], v[168:171], v[200:203], v[0:3]
	s_barrier
	s_add_i32 s28, 0, 0x18000
	s_add_i32 s29, 0, 0x1c000
	s_add_u32 s0, s24, 0xb0000
	s_addc_u32 s1, s25, 0
	s_mov_b32 m0, s35
	s_nop 0
	global_load_lds_dwordx4 v208, s[0:1]
	s_mov_b32 m0, s39
	s_nop 0
	global_load_lds_dwordx4 v128, s[0:1]
	v_add_u32_e32 v152, s28, v141
	v_add_u32_e32 v168, s29, v141
	ds_read_b128 v[134:137], v152
	ds_read_b128 v[144:147], v152 offset:1024
	ds_read_b128 v[148:151], v152 offset:2048
	ds_read_b128 v[152:155], v152 offset:3072
	ds_read_b128 v[156:159], v168
	ds_read_b128 v[160:163], v168 offset:1024
	ds_read_b128 v[164:167], v168 offset:2048
	ds_read_b128 v[168:171], v168 offset:3072
	ds_read_b128 v[172:175], v143 offset:32768
	ds_read_b128 v[176:179], v143 offset:33792
	ds_read_b128 v[180:183], v143 offset:34816
	ds_read_b128 v[184:187], v143 offset:35840
	ds_read_b128 v[188:191], v143 offset:36864
	ds_read_b128 v[192:195], v143 offset:37888
	ds_read_b128 v[196:199], v143 offset:38912
	ds_read_b128 v[200:203], v143 offset:39936
	s_waitcnt vmcnt(8)
	s_waitcnt lgkmcnt(0)
	s_barrier
	s_waitcnt lgkmcnt(0)
	v_mfma_f32_16x16x32_bf16 v[124:127], v[134:137], v[172:175], v[124:127]
	v_mfma_f32_16x16x32_bf16 v[120:123], v[148:151], v[172:175], v[120:123]
	v_mfma_f32_16x16x32_bf16 v[116:119], v[134:137], v[180:183], v[116:119]
	v_mfma_f32_16x16x32_bf16 v[112:115], v[148:151], v[180:183], v[112:115]
	v_mfma_f32_16x16x32_bf16 v[108:111], v[134:137], v[188:191], v[108:111]
	v_mfma_f32_16x16x32_bf16 v[100:103], v[148:151], v[188:191], v[100:103]
	v_mfma_f32_16x16x32_bf16 v[92:95], v[134:137], v[196:199], v[92:95]
	v_mfma_f32_16x16x32_bf16 v[80:83], v[148:151], v[196:199], v[80:83]
	v_mfma_f32_16x16x32_bf16 v[124:127], v[144:147], v[176:179], v[124:127]
	v_mfma_f32_16x16x32_bf16 v[120:123], v[152:155], v[176:179], v[120:123]
	v_mfma_f32_16x16x32_bf16 v[116:119], v[144:147], v[184:187], v[116:119]
	v_mfma_f32_16x16x32_bf16 v[112:115], v[152:155], v[184:187], v[112:115]
	v_mfma_f32_16x16x32_bf16 v[108:111], v[144:147], v[192:195], v[108:111]
	v_mfma_f32_16x16x32_bf16 v[100:103], v[152:155], v[192:195], v[100:103]
	v_mfma_f32_16x16x32_bf16 v[92:95], v[144:147], v[200:203], v[92:95]
	v_mfma_f32_16x16x32_bf16 v[80:83], v[152:155], v[200:203], v[80:83]
	v_mfma_f32_16x16x32_bf16 v[104:107], v[156:159], v[172:175], v[104:107]
	v_mfma_f32_16x16x32_bf16 v[96:99], v[164:167], v[172:175], v[96:99]
	v_mfma_f32_16x16x32_bf16 v[88:91], v[156:159], v[180:183], v[88:91]
	v_mfma_f32_16x16x32_bf16 v[84:87], v[164:167], v[180:183], v[84:87]
	v_mfma_f32_16x16x32_bf16 v[76:79], v[156:159], v[188:191], v[76:79]
	v_mfma_f32_16x16x32_bf16 v[72:75], v[164:167], v[188:191], v[72:75]
	v_mfma_f32_16x16x32_bf16 v[68:71], v[156:159], v[196:199], v[68:71]
	v_mfma_f32_16x16x32_bf16 v[64:67], v[164:167], v[196:199], v[64:67]
	v_mfma_f32_16x16x32_bf16 v[104:107], v[160:163], v[176:179], v[104:107]
	v_mfma_f32_16x16x32_bf16 v[96:99], v[168:171], v[176:179], v[96:99]
	v_mfma_f32_16x16x32_bf16 v[88:91], v[160:163], v[184:187], v[88:91]
	v_mfma_f32_16x16x32_bf16 v[84:87], v[168:171], v[184:187], v[84:87]
	v_mfma_f32_16x16x32_bf16 v[76:79], v[160:163], v[192:195], v[76:79]
	v_mfma_f32_16x16x32_bf16 v[72:75], v[168:171], v[192:195], v[72:75]
	v_mfma_f32_16x16x32_bf16 v[68:71], v[160:163], v[200:203], v[68:71]
	v_mfma_f32_16x16x32_bf16 v[64:67], v[168:171], v[200:203], v[64:67]
	s_barrier
; #define PG8_STAGE(bufoff, gbase, voff) do { _Pragma("unroll") for (int _i = 0; _i < 2; ++_i) \
;         __builtin_amdgcn_global_load_lds((const unsigned*)((const char*)(gbase) + (voff)[_i]), (PG8_LAS unsigned*)(lds + (bufoff) + ldsw + _i * 8192), 16, 0, 0); } while (0)
; #define PG8_LDA(dst, b, h) do { _Pragma("unroll") for (int m = 0; m < 4; ++m) _Pragma("unroll") for (int k = 0; k < 2; ++k) dst[m][k] = *(const PG8_LAS bf16x8*)(lds + PG8_SA(b, h) + aoff + m * 2048 + k * 1024); } while (0)
; #define PG8_MMA(ai, bj, At, Bt) do { __builtin_amdgcn_s_setprio(1); _Pragma("unroll") for (int m = 0; m < 4; ++m) _Pragma("unroll") for (int n = 0; n < 2; ++n) _Pragma("unroll") for (int k = 0; k < 2; ++k) \
;         acc[ai][bj][m][n] = __builtin_amdgcn_mfma_f32_16x16x32_bf16(Bt[n][k], At[m][k], acc[ai][bj][m][n], 0, 0, 0); __builtin_amdgcn_s_setprio(0); } while (0)
; #define PG8_WAIT_V(n) asm volatile("s_waitcnt vmcnt(" #n ")" ::: "memory")
; #define PG8_WAIT_L(n) asm volatile("s_waitcnt lgkmcnt(" #n ")" ::: "memory")
; #define PG8_BAR __builtin_amdgcn_s_barrier()
; #define PG8_SCHED __builtin_amdgcn_sched_barrier(0)
; template <class Epi, class Sched, bool ALIGN_EPI = false, bool SP2 = false>
; __device__ __forceinline__ void gemm_phase(PG8_LAS unsigned char* lds, const Gemm g, const Sched& S, const Epi& E) {
;     ...
;             PG8_WAIT_V(8); PG8_WAIT_L(0); PG8_BAR; PG8_MMA(0, 0, At, B0); PG8_MMA(0, 1, At, B1); PG8_BAR; PG8_SCHED;
;             PG8_LDA(At, 1, 1); PG8_STAGE(PG8_SB(1, 0), b3, voffB); PG8_STAGE(PG8_SB(1, 1), b3 + hstepB, voffB); PG8_STAGE(PG8_SA(1, 0), a3, voffA);
;             PG8_WAIT_V(8); PG8_WAIT_L(0); PG8_BAR; PG8_MMA(1, 0, At, B0); PG8_MMA(1, 1, At, B1); PG8_BAR; PG8_SCHED;
;     ...
;         if constexpr (ALIGN_EPI) { if (wr == 0) PG8_BAR; }
	s_add_i32 s0, s28, s19
	v_lshl_add_u64 v[138:139], v[138:139], 0, s[10:11]
	s_mov_b32 m0, s0
	s_nop 0
	global_load_lds_dwordx4 v[138:139], off
	s_add_i32 m0, s0, 0x2000
	s_add_u32 s0, s22, 0xb0080
	v_lshl_add_u64 v[138:139], v[204:205], 0, s[10:11]
	s_addc_u32 s1, s23, 0
	s_add_i32 s22, s29, s19
	global_load_lds_dwordx4 v[138:139], off
	s_mov_b32 m0, s22
	s_nop 0
	global_load_lds_dwordx4 v208, s[0:1]
	s_add_i32 m0, s22, 0x2000
	s_nop 0
	global_load_lds_dwordx4 v128, s[0:1]
	v_lshl_add_u64 v[138:139], v[206:207], 0, s[10:11]
	s_mov_b32 m0, s46
	s_nop 0
	global_load_lds_dwordx4 v[138:139], off
	v_lshl_add_u64 v[138:139], v[210:211], 0, s[10:11]
	s_mov_b32 m0, s47
	s_nop 0
	global_load_lds_dwordx4 v[138:139], off
	ds_read_b128 v[172:175], v143 offset:49152
	ds_read_b128 v[176:179], v143 offset:50176
	ds_read_b128 v[180:183], v143 offset:51200
	ds_read_b128 v[184:187], v143 offset:52224
	ds_read_b128 v[188:191], v143 offset:53248
	ds_read_b128 v[192:195], v143 offset:54272
	ds_read_b128 v[196:199], v143 offset:55296
	ds_read_b128 v[200:203], v143 offset:56320
	s_waitcnt vmcnt(8)
	s_waitcnt lgkmcnt(0)
	s_barrier
	s_waitcnt lgkmcnt(0)
	v_mfma_f32_16x16x32_bf16 v[60:63], v[134:137], v[172:175], v[60:63]
	v_mfma_f32_16x16x32_bf16 v[56:59], v[148:151], v[172:175], v[56:59]
	v_mfma_f32_16x16x32_bf16 v[52:55], v[134:137], v[180:183], v[52:55]
	v_mfma_f32_16x16x32_bf16 v[48:51], v[148:151], v[180:183], v[48:51]
	v_mfma_f32_16x16x32_bf16 v[44:47], v[134:137], v[188:191], v[44:47]
	v_mfma_f32_16x16x32_bf16 v[32:35], v[148:151], v[188:191], v[32:35]
	v_mfma_f32_16x16x32_bf16 v[16:19], v[134:137], v[196:199], v[16:19]
	v_mfma_f32_16x16x32_bf16 v[8:11], v[148:151], v[196:199], v[8:11]
	v_mfma_f32_16x16x32_bf16 v[60:63], v[144:147], v[176:179], v[60:63]
	v_mfma_f32_16x16x32_bf16 v[56:59], v[152:155], v[176:179], v[56:59]
	v_mfma_f32_16x16x32_bf16 v[52:55], v[144:147], v[184:187], v[52:55]
	v_mfma_f32_16x16x32_bf16 v[48:51], v[152:155], v[184:187], v[48:51]
	v_mfma_f32_16x16x32_bf16 v[44:47], v[144:147], v[192:195], v[44:47]
	v_mfma_f32_16x16x32_bf16 v[32:35], v[152:155], v[192:195], v[32:35]
	v_mfma_f32_16x16x32_bf16 v[16:19], v[144:147], v[200:203], v[16:19]
	v_mfma_f32_16x16x32_bf16 v[8:11], v[152:155], v[200:203], v[8:11]
	v_mfma_f32_16x16x32_bf16 v[40:43], v[156:159], v[172:175], v[40:43]
	v_mfma_f32_16x16x32_bf16 v[36:39], v[164:167], v[172:175], v[36:39]
	v_mfma_f32_16x16x32_bf16 v[28:31], v[156:159], v[180:183], v[28:31]
	v_mfma_f32_16x16x32_bf16 v[24:27], v[164:167], v[180:183], v[24:27]
	v_mfma_f32_16x16x32_bf16 v[20:23], v[156:159], v[188:191], v[20:23]
	v_mfma_f32_16x16x32_bf16 v[12:15], v[164:167], v[188:191], v[12:15]
	v_mfma_f32_16x16x32_bf16 v[4:7], v[156:159], v[196:199], v[4:7]
	v_mfma_f32_16x16x32_bf16 v[0:3], v[164:167], v[196:199], v[0:3]
	v_mfma_f32_16x16x32_bf16 v[40:43], v[160:163], v[176:179], v[40:43]
	v_mfma_f32_16x16x32_bf16 v[36:39], v[168:171], v[176:179], v[36:39]
	v_mfma_f32_16x16x32_bf16 v[28:31], v[160:163], v[184:187], v[28:31]
	v_mfma_f32_16x16x32_bf16 v[24:27], v[168:171], v[184:187], v[24:27]
	v_mfma_f32_16x16x32_bf16 v[20:23], v[160:163], v[192:195], v[20:23]
	v_mfma_f32_16x16x32_bf16 v[12:15], v[168:171], v[192:195], v[12:15]
	v_mfma_f32_16x16x32_bf16 v[4:7], v[160:163], v[200:203], v[4:7]
	v_mfma_f32_16x16x32_bf16 v[0:3], v[168:171], v[200:203], v[0:3]
	s_barrier
	s_add_i32 s51, s51, 2
	s_add_u32 s14, s14, 0x100
	s_addc_u32 s15, s15, 0
	s_cmp_gt_u32 s51, 41
	s_mov_b64 s[0:1], s[20:21]
	s_cbranch_scc0 .LBB0_215
	s_and_b64 vcc, exec, s[42:43]
	s_cbranch_vccz .LBB0_218
	s_barrier

; #define PG8_STAGE(bufoff, gbase, voff) do { _Pragma("unroll") for (int _i = 0; _i < 2; ++_i) \
;         __builtin_amdgcn_global_load_lds((const unsigned*)((const char*)(gbase) + (voff)[_i]), (PG8_LAS unsigned*)(lds + (bufoff) + ldsw + _i * 8192), 16, 0, 0); } while (0)
; #define PG8_LDA(dst, b, h) do { _Pragma("unroll") for (int m = 0; m < 4; ++m) _Pragma("unroll") for (int k = 0; k < 2; ++k) dst[m][k] = *(const PG8_LAS bf16x8*)(lds + PG8_SA(b, h) + aoff + m * 2048 + k * 1024); } while (0)
; #define PG8_LDB(dst, b, h) do { _Pragma("unroll") for (int n = 0; n < 2; ++n) _Pragma("unroll") for (int k = 0; k < 2; ++k) dst[n][k] = *(const PG8_LAS bf16x8*)(lds + PG8_SB(b, h) + boff + n * 2048 + k * 1024); } while (0)
; #define PG8_MMA(ai, bj, At, Bt) do { __builtin_amdgcn_s_setprio(1); _Pragma("unroll") for (int m = 0; m < 4; ++m) _Pragma("unroll") for (int n = 0; n < 2; ++n) _Pragma("unroll") for (int k = 0; k < 2; ++k) \
;         acc[ai][bj][m][n] = __builtin_amdgcn_mfma_f32_16x16x32_bf16(Bt[n][k], At[m][k], acc[ai][bj][m][n], 0, 0, 0); __builtin_amdgcn_s_setprio(0); } while (0)
; #define PG8_WAIT_V(n) asm volatile("s_waitcnt vmcnt(" #n ")" ::: "memory")
; #define PG8_WAIT_L(n) asm volatile("s_waitcnt lgkmcnt(" #n ")" ::: "memory")
; template <class Epi, class Sched, bool ALIGN_EPI = false, bool SP2 = false>
; __device__ __forceinline__ void gemm_phase(PG8_LAS unsigned char* lds, const Gemm g, const Sched& S, const Epi& E) {
;     ...
;             const bool last = (t == nt - 2);
;             const char* a1 = cA + (size_t)(t + 1) * kstep;
;             const char* a2 = last ? nA : cA + (size_t)(t + 2) * kstep; const char* b2 = last ? nB : cB + (size_t)(t + 2) * kstep;
;             const char* a3 = a2 + kstep; const char* b3 = b2 + kstep;
;             if (last && has_next) S.a_ready(nxt);
;             if constexpr (SP2) {
;             PG8_LDB(B0, 0, 0); PG8_LDB(B1, 0, 1); PG8_SCHED; PG8_LDA(At, 0, 0); PG8_STAGE(PG8_SA(1, 1), a1 + hstepA, voffA);
;             PG8_WAIT_V(8); PG8_WAIT_L(0); PG8_BAR; PG8_MMA(0, 0, At, B0); PG8_MMA(0, 1, At, B1); PG8_BAR; PG8_SCHED;
;             PG8_LDA(At, 0, 1); PG8_STAGE(PG8_SB(0, 0), b2, voffB); PG8_STAGE(PG8_SB(0, 1), b2 + hstepB, voffB); PG8_STAGE(PG8_SA(0, 0), a2, voffA);
;             PG8_WAIT_V(8); PG8_WAIT_L(0); PG8_BAR; PG8_MMA(1, 0, At, B0); PG8_MMA(1, 1, At, B1); PG8_BAR; PG8_SCHED;
.LBB0_338:
	s_add_u32 s22, s0, 0xfffc0080
	s_addc_u32 s23, s1, -1
	s_add_i32 s28, 0, 0x10000
	s_cmp_eq_u32 s51, 12
	s_cselect_b32 s25, s14, s23
	s_cselect_b32 s24, s15, s22
	v_add_u32_e32 v138, s28, v142
	s_cselect_b32 s23, s21, s50
	s_cselect_b32 s22, s41, s49
	s_add_i32 s29, 0, 0x14000
	ds_read_b128 v[146:149], v138
	ds_read_b128 v[150:153], v138 offset:1024
	ds_read_b128 v[154:157], v138 offset:2048
	ds_read_b128 v[158:161], v138 offset:3072
	v_add_u32_e32 v138, s29, v142
	ds_read_b128 v[162:165], v138
	ds_read_b128 v[166:169], v138 offset:1024
	ds_read_b128 v[170:173], v138 offset:2048
	ds_read_b128 v[174:177], v138 offset:3072
	s_add_i32 m0, s26, 0xc000
	ds_read_b128 v[178:181], v144
	ds_read_b128 v[182:185], v144 offset:1024
	ds_read_b128 v[186:189], v144 offset:2048
	ds_read_b128 v[190:193], v144 offset:3072
	ds_read_b128 v[194:197], v144 offset:4096
	ds_read_b128 v[198:201], v144 offset:5120
	ds_read_b128 v[202:205], v144 offset:6144
	ds_read_b128 v[210:213], v144 offset:7168
	global_load_lds_dwordx4 v134, s[0:1]
	s_add_i32 m0, s26, 0xe000
	s_nop 0
	global_load_lds_dwordx4 v136, s[0:1]
	s_waitcnt vmcnt(8)
	s_waitcnt lgkmcnt(0)
	s_barrier
	s_waitcnt lgkmcnt(0)
	v_mfma_f32_16x16x32_bf16 v[124:127], v[146:149], v[178:181], v[124:127]
	v_mfma_f32_16x16x32_bf16 v[120:123], v[154:157], v[178:181], v[120:123]
	v_mfma_f32_16x16x32_bf16 v[116:119], v[146:149], v[186:189], v[116:119]
	v_mfma_f32_16x16x32_bf16 v[108:111], v[154:157], v[186:189], v[108:111]
	v_mfma_f32_16x16x32_bf16 v[100:103], v[146:149], v[194:197], v[100:103]
	v_mfma_f32_16x16x32_bf16 v[92:95], v[154:157], v[194:197], v[92:95]
	v_mfma_f32_16x16x32_bf16 v[84:87], v[146:149], v[202:205], v[84:87]
	v_mfma_f32_16x16x32_bf16 v[76:79], v[154:157], v[202:205], v[76:79]
	v_mfma_f32_16x16x32_bf16 v[124:127], v[150:153], v[182:185], v[124:127]
	v_mfma_f32_16x16x32_bf16 v[120:123], v[158:161], v[182:185], v[120:123]
	v_mfma_f32_16x16x32_bf16 v[116:119], v[150:153], v[190:193], v[116:119]
	v_mfma_f32_16x16x32_bf16 v[108:111], v[158:161], v[190:193], v[108:111]
	v_mfma_f32_16x16x32_bf16 v[100:103], v[150:153], v[198:201], v[100:103]
	v_mfma_f32_16x16x32_bf16 v[92:95], v[158:161], v[198:201], v[92:95]
	v_mfma_f32_16x16x32_bf16 v[84:87], v[150:153], v[210:213], v[84:87]
	v_mfma_f32_16x16x32_bf16 v[76:79], v[158:161], v[210:213], v[76:79]
	v_mfma_f32_16x16x32_bf16 v[112:115], v[162:165], v[178:181], v[112:115]
	v_mfma_f32_16x16x32_bf16 v[104:107], v[170:173], v[178:181], v[104:107]
	v_mfma_f32_16x16x32_bf16 v[96:99], v[162:165], v[186:189], v[96:99]
	v_mfma_f32_16x16x32_bf16 v[88:91], v[170:173], v[186:189], v[88:91]
	v_mfma_f32_16x16x32_bf16 v[80:83], v[162:165], v[194:197], v[80:83]
	v_mfma_f32_16x16x32_bf16 v[72:75], v[170:173], v[194:197], v[72:75]
	v_mfma_f32_16x16x32_bf16 v[68:71], v[162:165], v[202:205], v[68:71]
	v_mfma_f32_16x16x32_bf16 v[64:67], v[170:173], v[202:205], v[64:67]
	v_mfma_f32_16x16x32_bf16 v[112:115], v[166:169], v[182:185], v[112:115]
	v_mfma_f32_16x16x32_bf16 v[104:107], v[174:177], v[182:185], v[104:107]
	v_mfma_f32_16x16x32_bf16 v[96:99], v[166:169], v[190:193], v[96:99]
	v_mfma_f32_16x16x32_bf16 v[88:91], v[174:177], v[190:193], v[88:91]
	v_mfma_f32_16x16x32_bf16 v[80:83], v[166:169], v[198:201], v[80:83]
	v_mfma_f32_16x16x32_bf16 v[72:75], v[174:177], v[198:201], v[72:75]
	v_mfma_f32_16x16x32_bf16 v[68:71], v[166:169], v[210:213], v[68:71]
	v_mfma_f32_16x16x32_bf16 v[64:67], v[174:177], v[210:213], v[64:67]
	s_barrier
	s_add_i32 s28, s28, s18
	v_lshl_add_u64 v[140:141], s[22:23], 0, v[208:209]
	s_mov_b32 m0, s28
	s_nop 0
	global_load_lds_dwordx4 v208, s[22:23]
	s_add_i32 m0, s28, 0x2000
	s_add_u32 s52, s22, 0x40000
	v_lshl_add_u64 v[206:207], s[22:23], 0, v[128:129]
	s_addc_u32 s53, s23, 0
	s_add_i32 s28, s29, s18
	global_load_lds_dwordx4 v128, s[22:23]
	s_mov_b32 m0, s28
	v_lshl_add_u64 v[224:225], s[24:25], 0, v[130:131]
	global_load_lds_dwordx4 v208, s[52:53]
	s_add_i32 m0, s28, 0x2000
	s_nop 0
	global_load_lds_dwordx4 v128, s[52:53]
	v_lshl_add_u64 v[222:223], s[24:25], 0, v[132:133]
	s_mov_b32 m0, s26
	s_nop 0
	global_load_lds_dwordx4 v132, s[24:25]
	s_mov_b32 m0, s34
	s_nop 0
	global_load_lds_dwordx4 v130, s[24:25]
	ds_read_b128 v[178:181], v144 offset:16384
	ds_read_b128 v[182:185], v144 offset:17408
	ds_read_b128 v[186:189], v144 offset:18432
	ds_read_b128 v[190:193], v144 offset:19456
	ds_read_b128 v[194:197], v144 offset:20480
	ds_read_b128 v[198:201], v144 offset:21504
	ds_read_b128 v[202:205], v144 offset:22528
	ds_read_b128 v[210:213], v144 offset:23552
	s_waitcnt vmcnt(8)
	s_waitcnt lgkmcnt(0)
	s_barrier
; #define PG8_STAGE(bufoff, gbase, voff) do { _Pragma("unroll") for (int _i = 0; _i < 2; ++_i) \
;         __builtin_amdgcn_global_load_lds((const unsigned*)((const char*)(gbase) + (voff)[_i]), (PG8_LAS unsigned*)(lds + (bufoff) + ldsw + _i * 8192), 16, 0, 0); } while (0)
; #define PG8_LDA(dst, b, h) do { _Pragma("unroll") for (int m = 0; m < 4; ++m) _Pragma("unroll") for (int k = 0; k < 2; ++k) dst[m][k] = *(const PG8_LAS bf16x8*)(lds + PG8_SA(b, h) + aoff + m * 2048 + k * 1024); } while (0)
; #define PG8_LDB(dst, b, h) do { _Pragma("unroll") for (int n = 0; n < 2; ++n) _Pragma("unroll") for (int k = 0; k < 2; ++k) dst[n][k] = *(const PG8_LAS bf16x8*)(lds + PG8_SB(b, h) + boff + n * 2048 + k * 1024); } while (0)
; #define PG8_MMA(ai, bj, At, Bt) do { __builtin_amdgcn_s_setprio(1); _Pragma("unroll") for (int m = 0; m < 4; ++m) _Pragma("unroll") for (int n = 0; n < 2; ++n) _Pragma("unroll") for (int k = 0; k < 2; ++k) \
;         acc[ai][bj][m][n] = __builtin_amdgcn_mfma_f32_16x16x32_bf16(Bt[n][k], At[m][k], acc[ai][bj][m][n], 0, 0, 0); __builtin_amdgcn_s_setprio(0); } while (0)
; #define PG8_WAIT_V(n) asm volatile("s_waitcnt vmcnt(" #n ")" ::: "memory")
; #define PG8_WAIT_L(n) asm volatile("s_waitcnt lgkmcnt(" #n ")" ::: "memory")
; #define PG8_BAR __builtin_amdgcn_s_barrier()
; #define PG8_SCHED __builtin_amdgcn_sched_barrier(0)
; template <class Epi, class Sched, bool ALIGN_EPI = false, bool SP2 = false>
; __device__ __forceinline__ void gemm_phase(PG8_LAS unsigned char* lds, const Gemm g, const Sched& S, const Epi& E) {
;     ...
;             PG8_WAIT_V(8); PG8_WAIT_L(0); PG8_BAR; PG8_MMA(0, 0, At, B0); PG8_MMA(0, 1, At, B1); PG8_BAR; PG8_SCHED;
;             PG8_LDA(At, 0, 1); PG8_STAGE(PG8_SB(0, 0), b2, voffB); PG8_STAGE(PG8_SB(0, 1), b2 + hstepB, voffB); PG8_STAGE(PG8_SA(0, 0), a2, voffA);
;             PG8_WAIT_V(8); PG8_WAIT_L(0); PG8_BAR; PG8_MMA(1, 0, At, B0); PG8_MMA(1, 1, At, B1); PG8_BAR; PG8_SCHED;
;             PG8_LDB(B0, 1, 0); PG8_LDB(B1, 1, 1); PG8_SCHED; PG8_LDA(At, 1, 0); PG8_STAGE(PG8_SA(0, 1), a2 + hstepA, voffA);
;             PG8_WAIT_V(8); PG8_WAIT_L(0); PG8_BAR; PG8_MMA(0, 0, At, B0); PG8_MMA(0, 1, At, B1); PG8_BAR; PG8_SCHED;
	s_waitcnt lgkmcnt(0)
	v_mfma_f32_16x16x32_bf16 v[60:63], v[146:149], v[178:181], v[60:63]
	v_mfma_f32_16x16x32_bf16 v[56:59], v[154:157], v[178:181], v[56:59]
	v_mfma_f32_16x16x32_bf16 v[52:55], v[146:149], v[186:189], v[52:55]
	v_mfma_f32_16x16x32_bf16 v[44:47], v[154:157], v[186:189], v[44:47]
	v_mfma_f32_16x16x32_bf16 v[36:39], v[146:149], v[194:197], v[36:39]
	v_mfma_f32_16x16x32_bf16 v[28:31], v[154:157], v[194:197], v[28:31]
	v_mfma_f32_16x16x32_bf16 v[20:23], v[146:149], v[202:205], v[20:23]
	v_mfma_f32_16x16x32_bf16 v[12:15], v[154:157], v[202:205], v[12:15]
	v_mfma_f32_16x16x32_bf16 v[60:63], v[150:153], v[182:185], v[60:63]
	v_mfma_f32_16x16x32_bf16 v[56:59], v[158:161], v[182:185], v[56:59]
	v_mfma_f32_16x16x32_bf16 v[52:55], v[150:153], v[190:193], v[52:55]
	v_mfma_f32_16x16x32_bf16 v[44:47], v[158:161], v[190:193], v[44:47]
	v_mfma_f32_16x16x32_bf16 v[36:39], v[150:153], v[198:201], v[36:39]
	v_mfma_f32_16x16x32_bf16 v[28:31], v[158:161], v[198:201], v[28:31]
	v_mfma_f32_16x16x32_bf16 v[20:23], v[150:153], v[210:213], v[20:23]
	v_mfma_f32_16x16x32_bf16 v[12:15], v[158:161], v[210:213], v[12:15]
	v_mfma_f32_16x16x32_bf16 v[48:51], v[162:165], v[178:181], v[48:51]
	v_mfma_f32_16x16x32_bf16 v[40:43], v[170:173], v[178:181], v[40:43]
	v_mfma_f32_16x16x32_bf16 v[32:35], v[162:165], v[186:189], v[32:35]
	v_mfma_f32_16x16x32_bf16 v[24:27], v[170:173], v[186:189], v[24:27]
	v_mfma_f32_16x16x32_bf16 v[16:19], v[162:165], v[194:197], v[16:19]
	v_mfma_f32_16x16x32_bf16 v[8:11], v[170:173], v[194:197], v[8:11]
	v_mfma_f32_16x16x32_bf16 v[4:7], v[162:165], v[202:205], v[4:7]
	v_mfma_f32_16x16x32_bf16 v[0:3], v[170:173], v[202:205], v[0:3]
	v_mfma_f32_16x16x32_bf16 v[48:51], v[166:169], v[182:185], v[48:51]
	v_mfma_f32_16x16x32_bf16 v[40:43], v[174:177], v[182:185], v[40:43]
	v_mfma_f32_16x16x32_bf16 v[32:35], v[166:169], v[190:193], v[32:35]
	v_mfma_f32_16x16x32_bf16 v[24:27], v[174:177], v[190:193], v[24:27]
	v_mfma_f32_16x16x32_bf16 v[16:19], v[166:169], v[198:201], v[16:19]
	v_mfma_f32_16x16x32_bf16 v[8:11], v[174:177], v[198:201], v[8:11]
	v_mfma_f32_16x16x32_bf16 v[4:7], v[166:169], v[210:213], v[4:7]
	v_mfma_f32_16x16x32_bf16 v[0:3], v[174:177], v[210:213], v[0:3]
	s_barrier
	s_add_i32 s28, 0, 0x18000
	v_add_u32_e32 v138, s28, v142
	s_add_i32 s29, 0, 0x1c000
	ds_read_b128 v[146:149], v138
	ds_read_b128 v[150:153], v138 offset:1024
	ds_read_b128 v[154:157], v138 offset:2048
	ds_read_b128 v[158:161], v138 offset:3072
	v_add_u32_e32 v138, s29, v142
	ds_read_b128 v[162:165], v138
	ds_read_b128 v[166:169], v138 offset:1024
	ds_read_b128 v[170:173], v138 offset:2048
	ds_read_b128 v[174:177], v138 offset:3072
	s_add_u32 s24, s24, 0x40000
	s_addc_u32 s25, s25, 0
	s_mov_b32 m0, s35
	ds_read_b128 v[178:181], v144 offset:32768
	ds_read_b128 v[182:185], v144 offset:33792
	ds_read_b128 v[186:189], v144 offset:34816
	ds_read_b128 v[190:193], v144 offset:35840
	ds_read_b128 v[194:197], v144 offset:36864
	ds_read_b128 v[198:201], v144 offset:37888
	ds_read_b128 v[202:205], v144 offset:38912
	ds_read_b128 v[210:213], v144 offset:39936
	global_load_lds_dwordx4 v132, s[24:25]
	v_lshl_add_u64 v[226:227], s[24:25], 0, v[130:131]
	s_mov_b32 m0, s39
	s_nop 0
	global_load_lds_dwordx4 v130, s[24:25]
	s_waitcnt vmcnt(8)
	s_waitcnt lgkmcnt(0)
	s_barrier
	s_waitcnt lgkmcnt(0)
	v_mfma_f32_16x16x32_bf16 v[124:127], v[146:149], v[178:181], v[124:127]
	v_mfma_f32_16x16x32_bf16 v[120:123], v[154:157], v[178:181], v[120:123]
	v_mfma_f32_16x16x32_bf16 v[116:119], v[146:149], v[186:189], v[116:119]
	v_mfma_f32_16x16x32_bf16 v[108:111], v[154:157], v[186:189], v[108:111]
	v_mfma_f32_16x16x32_bf16 v[100:103], v[146:149], v[194:197], v[100:103]
	v_mfma_f32_16x16x32_bf16 v[92:95], v[154:157], v[194:197], v[92:95]
	v_mfma_f32_16x16x32_bf16 v[84:87], v[146:149], v[202:205], v[84:87]
	v_mfma_f32_16x16x32_bf16 v[76:79], v[154:157], v[202:205], v[76:79]
	v_mfma_f32_16x16x32_bf16 v[124:127], v[150:153], v[182:185], v[124:127]
	v_mfma_f32_16x16x32_bf16 v[120:123], v[158:161], v[182:185], v[120:123]
	v_mfma_f32_16x16x32_bf16 v[116:119], v[150:153], v[190:193], v[116:119]
	v_mfma_f32_16x16x32_bf16 v[108:111], v[158:161], v[190:193], v[108:111]
	v_mfma_f32_16x16x32_bf16 v[100:103], v[150:153], v[198:201], v[100:103]
	v_mfma_f32_16x16x32_bf16 v[92:95], v[158:161], v[198:201], v[92:95]
	v_mfma_f32_16x16x32_bf16 v[84:87], v[150:153], v[210:213], v[84:87]
	v_mfma_f32_16x16x32_bf16 v[76:79], v[158:161], v[210:213], v[76:79]
	v_mfma_f32_16x16x32_bf16 v[112:115], v[162:165], v[178:181], v[112:115]
	v_mfma_f32_16x16x32_bf16 v[104:107], v[170:173], v[178:181], v[104:107]
	v_mfma_f32_16x16x32_bf16 v[96:99], v[162:165], v[186:189], v[96:99]
	v_mfma_f32_16x16x32_bf16 v[88:91], v[170:173], v[186:189], v[88:91]
	v_mfma_f32_16x16x32_bf16 v[80:83], v[162:165], v[194:197], v[80:83]
	v_mfma_f32_16x16x32_bf16 v[72:75], v[170:173], v[194:197], v[72:75]
	v_mfma_f32_16x16x32_bf16 v[68:71], v[162:165], v[202:205], v[68:71]
	v_mfma_f32_16x16x32_bf16 v[64:67], v[170:173], v[202:205], v[64:67]
	v_mfma_f32_16x16x32_bf16 v[112:115], v[166:169], v[182:185], v[112:115]
	v_mfma_f32_16x16x32_bf16 v[104:107], v[174:177], v[182:185], v[104:107]
	v_mfma_f32_16x16x32_bf16 v[96:99], v[166:169], v[190:193], v[96:99]
	v_mfma_f32_16x16x32_bf16 v[88:91], v[174:177], v[190:193], v[88:91]
	v_mfma_f32_16x16x32_bf16 v[80:83], v[166:169], v[198:201], v[80:83]
	v_mfma_f32_16x16x32_bf16 v[72:75], v[174:177], v[198:201], v[72:75]
	v_mfma_f32_16x16x32_bf16 v[68:71], v[166:169], v[210:213], v[68:71]
	v_mfma_f32_16x16x32_bf16 v[64:67], v[174:177], v[210:213], v[64:67]
	s_barrier
; #define PG8_STAGE(bufoff, gbase, voff) do { _Pragma("unroll") for (int _i = 0; _i < 2; ++_i) \
;         __builtin_amdgcn_global_load_lds((const unsigned*)((const char*)(gbase) + (voff)[_i]), (PG8_LAS unsigned*)(lds + (bufoff) + ldsw + _i * 8192), 16, 0, 0); } while (0)
; #define PG8_LDA(dst, b, h) do { _Pragma("unroll") for (int m = 0; m < 4; ++m) _Pragma("unroll") for (int k = 0; k < 2; ++k) dst[m][k] = *(const PG8_LAS bf16x8*)(lds + PG8_SA(b, h) + aoff + m * 2048 + k * 1024); } while (0)
; #define PG8_MMA(ai, bj, At, Bt) do { __builtin_amdgcn_s_setprio(1); _Pragma("unroll") for (int m = 0; m < 4; ++m) _Pragma("unroll") for (int n = 0; n < 2; ++n) _Pragma("unroll") for (int k = 0; k < 2; ++k) \
;         acc[ai][bj][m][n] = __builtin_amdgcn_mfma_f32_16x16x32_bf16(Bt[n][k], At[m][k], acc[ai][bj][m][n], 0, 0, 0); __builtin_amdgcn_s_setprio(0); } while (0)
; #define PG8_WAIT_V(n) asm volatile("s_waitcnt vmcnt(" #n ")" ::: "memory")
; #define PG8_WAIT_L(n) asm volatile("s_waitcnt lgkmcnt(" #n ")" ::: "memory")
; #define PG8_BAR __builtin_amdgcn_s_barrier()
; #define PG8_SCHED __builtin_amdgcn_sched_barrier(0)
; template <class Epi, class Sched, bool ALIGN_EPI = false, bool SP2 = false>
; __device__ __forceinline__ void gemm_phase(PG8_LAS unsigned char* lds, const Gemm g, const Sched& S, const Epi& E) {
;     ...
;             PG8_WAIT_V(8); PG8_WAIT_L(0); PG8_BAR; PG8_MMA(0, 0, At, B0); PG8_MMA(0, 1, At, B1); PG8_BAR; PG8_SCHED;
;             PG8_LDA(At, 1, 1); PG8_STAGE(PG8_SB(1, 0), b3, voffB); PG8_STAGE(PG8_SB(1, 1), b3 + hstepB, voffB); PG8_STAGE(PG8_SA(1, 0), a3, voffA);
;             PG8_WAIT_V(8); PG8_WAIT_L(0); PG8_BAR; PG8_MMA(1, 0, At, B0); PG8_MMA(1, 1, At, B1); PG8_BAR; PG8_SCHED;
;     ...
;         if constexpr (ALIGN_EPI) { if (wr == 0) PG8_BAR; }
	s_add_i32 s24, s28, s18
	v_lshl_add_u64 v[140:141], v[140:141], 0, s[10:11]
	s_mov_b32 m0, s24
	s_nop 0
	global_load_lds_dwordx4 v[140:141], off
	s_add_i32 m0, s24, 0x2000
	s_add_u32 s22, s22, 0x40080
	v_lshl_add_u64 v[140:141], v[206:207], 0, s[10:11]
	s_addc_u32 s23, s23, 0
	s_add_i32 s24, s29, s18
	global_load_lds_dwordx4 v[140:141], off
	s_mov_b32 m0, s24
	s_nop 0
	global_load_lds_dwordx4 v208, s[22:23]
	s_add_i32 m0, s24, 0x2000
	s_nop 0
	global_load_lds_dwordx4 v128, s[22:23]
	v_lshl_add_u64 v[140:141], v[222:223], 0, s[10:11]
	s_mov_b32 m0, s12
	s_nop 0
	global_load_lds_dwordx4 v[140:141], off
	v_lshl_add_u64 v[140:141], v[224:225], 0, s[10:11]
	s_mov_b32 m0, s43
	s_nop 0
	global_load_lds_dwordx4 v[140:141], off
	ds_read_b128 v[178:181], v144 offset:49152
	ds_read_b128 v[182:185], v144 offset:50176
	ds_read_b128 v[186:189], v144 offset:51200
	ds_read_b128 v[190:193], v144 offset:52224
	ds_read_b128 v[194:197], v144 offset:53248
	ds_read_b128 v[198:201], v144 offset:54272
	ds_read_b128 v[202:205], v144 offset:55296
	ds_read_b128 v[210:213], v144 offset:56320
	s_waitcnt vmcnt(8)
	s_waitcnt lgkmcnt(0)
	s_barrier
	s_waitcnt lgkmcnt(0)
	v_mfma_f32_16x16x32_bf16 v[60:63], v[146:149], v[178:181], v[60:63]
	v_mfma_f32_16x16x32_bf16 v[56:59], v[154:157], v[178:181], v[56:59]
	v_mfma_f32_16x16x32_bf16 v[52:55], v[146:149], v[186:189], v[52:55]
	v_mfma_f32_16x16x32_bf16 v[44:47], v[154:157], v[186:189], v[44:47]
	v_mfma_f32_16x16x32_bf16 v[36:39], v[146:149], v[194:197], v[36:39]
	v_mfma_f32_16x16x32_bf16 v[28:31], v[154:157], v[194:197], v[28:31]
	v_mfma_f32_16x16x32_bf16 v[20:23], v[146:149], v[202:205], v[20:23]
	v_mfma_f32_16x16x32_bf16 v[12:15], v[154:157], v[202:205], v[12:15]
	v_mfma_f32_16x16x32_bf16 v[60:63], v[150:153], v[182:185], v[60:63]
	v_mfma_f32_16x16x32_bf16 v[56:59], v[158:161], v[182:185], v[56:59]
	v_mfma_f32_16x16x32_bf16 v[52:55], v[150:153], v[190:193], v[52:55]
	v_mfma_f32_16x16x32_bf16 v[44:47], v[158:161], v[190:193], v[44:47]
	v_mfma_f32_16x16x32_bf16 v[36:39], v[150:153], v[198:201], v[36:39]
	v_mfma_f32_16x16x32_bf16 v[28:31], v[158:161], v[198:201], v[28:31]
	v_mfma_f32_16x16x32_bf16 v[20:23], v[150:153], v[210:213], v[20:23]
	v_mfma_f32_16x16x32_bf16 v[12:15], v[158:161], v[210:213], v[12:15]
	v_mfma_f32_16x16x32_bf16 v[48:51], v[162:165], v[178:181], v[48:51]
	v_mfma_f32_16x16x32_bf16 v[40:43], v[170:173], v[178:181], v[40:43]
	v_mfma_f32_16x16x32_bf16 v[32:35], v[162:165], v[186:189], v[32:35]
	v_mfma_f32_16x16x32_bf16 v[24:27], v[170:173], v[186:189], v[24:27]
	v_mfma_f32_16x16x32_bf16 v[16:19], v[162:165], v[194:197], v[16:19]
	v_mfma_f32_16x16x32_bf16 v[8:11], v[170:173], v[194:197], v[8:11]
	v_mfma_f32_16x16x32_bf16 v[4:7], v[162:165], v[202:205], v[4:7]
	v_mfma_f32_16x16x32_bf16 v[0:3], v[170:173], v[202:205], v[0:3]
	v_mfma_f32_16x16x32_bf16 v[48:51], v[166:169], v[182:185], v[48:51]
	v_mfma_f32_16x16x32_bf16 v[40:43], v[174:177], v[182:185], v[40:43]
	v_mfma_f32_16x16x32_bf16 v[32:35], v[166:169], v[190:193], v[32:35]
	v_mfma_f32_16x16x32_bf16 v[24:27], v[174:177], v[190:193], v[24:27]
	v_mfma_f32_16x16x32_bf16 v[16:19], v[166:169], v[198:201], v[16:19]
	v_mfma_f32_16x16x32_bf16 v[8:11], v[174:177], v[198:201], v[8:11]
	v_mfma_f32_16x16x32_bf16 v[4:7], v[166:169], v[210:213], v[4:7]
	v_mfma_f32_16x16x32_bf16 v[0:3], v[174:177], v[210:213], v[0:3]
	s_barrier
	s_add_i32 s51, s51, 2
	s_add_u32 s0, s0, 0x100
	s_addc_u32 s1, s1, 0
	s_add_u32 s49, s49, 0x100
	s_addc_u32 s50, s50, 0
	s_cmp_gt_u32 s51, 13
	s_cbranch_scc0 .LBB0_338
	s_and_b64 vcc, exec, s[8:9]
	s_cbranch_vccz .LBB0_341
	s_barrier

; #define PG8_STAGE(bufoff, gbase, voff) do { _Pragma("unroll") for (int _i = 0; _i < 2; ++_i) \
;         __builtin_amdgcn_global_load_lds((const unsigned*)((const char*)(gbase) + (voff)[_i]), (PG8_LAS unsigned*)(lds + (bufoff) + ldsw + _i * 8192), 16, 0, 0); } while (0)
; #define PG8_LDA(dst, b, h) do { _Pragma("unroll") for (int m = 0; m < 4; ++m) _Pragma("unroll") for (int k = 0; k < 2; ++k) dst[m][k] = *(const PG8_LAS bf16x8*)(lds + PG8_SA(b, h) + aoff + m * 2048 + k * 1024); } while (0)
; #define PG8_LDB(dst, b, h) do { _Pragma("unroll") for (int n = 0; n < 2; ++n) _Pragma("unroll") for (int k = 0; k < 2; ++k) dst[n][k] = *(const PG8_LAS bf16x8*)(lds + PG8_SB(b, h) + boff + n * 2048 + k * 1024); } while (0)
; #define PG8_MMA(ai, bj, At, Bt) do { __builtin_amdgcn_s_setprio(1); _Pragma("unroll") for (int m = 0; m < 4; ++m) _Pragma("unroll") for (int n = 0; n < 2; ++n) _Pragma("unroll") for (int k = 0; k < 2; ++k) \
;         acc[ai][bj][m][n] = __builtin_amdgcn_mfma_f32_16x16x32_bf16(Bt[n][k], At[m][k], acc[ai][bj][m][n], 0, 0, 0); __builtin_amdgcn_s_setprio(0); } while (0)
; #define PG8_WAIT_V(n) asm volatile("s_waitcnt vmcnt(" #n ")" ::: "memory")
; #define PG8_WAIT_L(n) asm volatile("s_waitcnt lgkmcnt(" #n ")" ::: "memory")
; template <class Epi, class Sched, bool ALIGN_EPI = false, bool SP2 = false>
; __device__ __forceinline__ void gemm_phase(PG8_LAS unsigned char* lds, const Gemm g, const Sched& S, const Epi& E) {
;     ...
;             const bool last = (t == nt - 2);
;             const char* a1 = cA + (size_t)(t + 1) * kstep;
;             const char* a2 = last ? nA : cA + (size_t)(t + 2) * kstep; const char* b2 = last ? nB : cB + (size_t)(t + 2) * kstep;
;             const char* a3 = a2 + kstep; const char* b3 = b2 + kstep;
;             if (last && has_next) S.a_ready(nxt);
;             if constexpr (SP2) {
;             PG8_LDB(B0, 0, 0); PG8_LDB(B1, 0, 1); PG8_SCHED; PG8_LDA(At, 0, 0); PG8_STAGE(PG8_SA(1, 1), a1 + hstepA, voffA);
;             PG8_WAIT_V(8); PG8_WAIT_L(0); PG8_BAR; PG8_MMA(0, 0, At, B0); PG8_MMA(0, 1, At, B1); PG8_BAR; PG8_SCHED;
;             PG8_LDA(At, 0, 1); PG8_STAGE(PG8_SB(0, 0), b2, voffB); PG8_STAGE(PG8_SB(0, 1), b2 + hstepB, voffB); PG8_STAGE(PG8_SA(0, 0), a2, voffA);
;             PG8_WAIT_V(8); PG8_WAIT_L(0); PG8_BAR; PG8_MMA(1, 0, At, B0); PG8_MMA(1, 1, At, B1); PG8_BAR; PG8_SCHED;
.LBB0_354:
	s_add_u32 s22, s44, 0xfffc0080
	s_addc_u32 s23, s45, -1
	s_add_i32 s28, 0, 0x10000
	s_cmp_eq_u32 s51, 12
	s_cselect_b32 s47, s14, s23
	s_cselect_b32 s46, s15, s22
	s_cselect_b32 s23, s1, s50
	s_cselect_b32 s22, s41, s49
	s_add_i32 s29, 0, 0x14000
	s_add_i32 m0, s21, 0xc000
	s_nop 0
	global_load_lds_dwordx4 v134, s[44:45]
	s_add_i32 m0, s21, 0xe000
	s_nop 0
	global_load_lds_dwordx4 v136, s[44:45]
	v_add_u32_e32 v154, s28, v139
	v_add_u32_e32 v170, s29, v139
	ds_read_b128 v[142:145], v154
	ds_read_b128 v[146:149], v154 offset:1024
	ds_read_b128 v[150:153], v154 offset:2048
	ds_read_b128 v[154:157], v154 offset:3072
	ds_read_b128 v[158:161], v170
	ds_read_b128 v[162:165], v170 offset:1024
	ds_read_b128 v[166:169], v170 offset:2048
	ds_read_b128 v[170:173], v170 offset:3072
	ds_read_b128 v[174:177], v141
	ds_read_b128 v[178:181], v141 offset:1024
	ds_read_b128 v[182:185], v141 offset:2048
	ds_read_b128 v[186:189], v141 offset:3072
	ds_read_b128 v[190:193], v141 offset:4096
	ds_read_b128 v[194:197], v141 offset:5120
	ds_read_b128 v[198:201], v141 offset:6144
	ds_read_b128 v[202:205], v141 offset:7168
	s_waitcnt vmcnt(8)
	s_waitcnt lgkmcnt(0)
	s_barrier
	s_waitcnt lgkmcnt(0)
	v_mfma_f32_16x16x32_bf16 v[124:127], v[142:145], v[174:177], v[124:127]
	v_mfma_f32_16x16x32_bf16 v[120:123], v[150:153], v[174:177], v[120:123]
	v_mfma_f32_16x16x32_bf16 v[116:119], v[142:145], v[182:185], v[116:119]
	v_mfma_f32_16x16x32_bf16 v[112:115], v[150:153], v[182:185], v[112:115]
	v_mfma_f32_16x16x32_bf16 v[100:103], v[142:145], v[190:193], v[100:103]
	v_mfma_f32_16x16x32_bf16 v[96:99], v[150:153], v[190:193], v[96:99]
	v_mfma_f32_16x16x32_bf16 v[84:87], v[142:145], v[198:201], v[84:87]
	v_mfma_f32_16x16x32_bf16 v[80:83], v[150:153], v[198:201], v[80:83]
	v_mfma_f32_16x16x32_bf16 v[124:127], v[146:149], v[178:181], v[124:127]
	v_mfma_f32_16x16x32_bf16 v[120:123], v[154:157], v[178:181], v[120:123]
	v_mfma_f32_16x16x32_bf16 v[116:119], v[146:149], v[186:189], v[116:119]
	v_mfma_f32_16x16x32_bf16 v[112:115], v[154:157], v[186:189], v[112:115]
	v_mfma_f32_16x16x32_bf16 v[100:103], v[146:149], v[194:197], v[100:103]
	v_mfma_f32_16x16x32_bf16 v[96:99], v[154:157], v[194:197], v[96:99]
	v_mfma_f32_16x16x32_bf16 v[84:87], v[146:149], v[202:205], v[84:87]
	v_mfma_f32_16x16x32_bf16 v[80:83], v[154:157], v[202:205], v[80:83]
	v_mfma_f32_16x16x32_bf16 v[108:111], v[158:161], v[174:177], v[108:111]
	v_mfma_f32_16x16x32_bf16 v[104:107], v[166:169], v[174:177], v[104:107]
	v_mfma_f32_16x16x32_bf16 v[92:95], v[158:161], v[182:185], v[92:95]
	v_mfma_f32_16x16x32_bf16 v[88:91], v[166:169], v[182:185], v[88:91]
	v_mfma_f32_16x16x32_bf16 v[76:79], v[158:161], v[190:193], v[76:79]
	v_mfma_f32_16x16x32_bf16 v[72:75], v[166:169], v[190:193], v[72:75]
	v_mfma_f32_16x16x32_bf16 v[68:71], v[158:161], v[198:201], v[68:71]
	v_mfma_f32_16x16x32_bf16 v[64:67], v[166:169], v[198:201], v[64:67]
	v_mfma_f32_16x16x32_bf16 v[108:111], v[162:165], v[178:181], v[108:111]
	v_mfma_f32_16x16x32_bf16 v[104:107], v[170:173], v[178:181], v[104:107]
	v_mfma_f32_16x16x32_bf16 v[92:95], v[162:165], v[186:189], v[92:95]
	v_mfma_f32_16x16x32_bf16 v[88:91], v[170:173], v[186:189], v[88:91]
	v_mfma_f32_16x16x32_bf16 v[76:79], v[162:165], v[194:197], v[76:79]
	v_mfma_f32_16x16x32_bf16 v[72:75], v[170:173], v[194:197], v[72:75]
	v_mfma_f32_16x16x32_bf16 v[68:71], v[162:165], v[202:205], v[68:71]
	v_mfma_f32_16x16x32_bf16 v[64:67], v[170:173], v[202:205], v[64:67]
	s_barrier
	s_add_i32 s28, s28, s18
	v_lshl_add_u64 v[206:207], s[22:23], 0, v[208:209]
	s_mov_b32 m0, s28
	s_nop 0
	global_load_lds_dwordx4 v208, s[22:23]
	s_add_i32 m0, s28, 0x2000
	s_add_u32 s52, s22, 0x40000
	v_lshl_add_u64 v[210:211], s[22:23], 0, v[128:129]
	s_addc_u32 s53, s23, 0
	s_add_i32 s28, s29, s18
	global_load_lds_dwordx4 v128, s[22:23]
	s_mov_b32 m0, s28
	v_lshl_add_u64 v[222:223], s[46:47], 0, v[130:131]
	global_load_lds_dwordx4 v208, s[52:53]
	s_add_i32 m0, s28, 0x2000
	s_nop 0
	global_load_lds_dwordx4 v128, s[52:53]
	v_lshl_add_u64 v[212:213], s[46:47], 0, v[132:133]
	s_mov_b32 m0, s21
	s_nop 0
	global_load_lds_dwordx4 v132, s[46:47]
	s_mov_b32 m0, s12
	s_nop 0
	global_load_lds_dwordx4 v130, s[46:47]
	ds_read_b128 v[174:177], v141 offset:16384
	ds_read_b128 v[178:181], v141 offset:17408
	ds_read_b128 v[182:185], v141 offset:18432
	ds_read_b128 v[186:189], v141 offset:19456
	ds_read_b128 v[190:193], v141 offset:20480
	ds_read_b128 v[194:197], v141 offset:21504
	ds_read_b128 v[198:201], v141 offset:22528
	ds_read_b128 v[202:205], v141 offset:23552
	s_waitcnt vmcnt(8)
	s_waitcnt lgkmcnt(0)
	s_barrier
; #define PG8_STAGE(bufoff, gbase, voff) do { _Pragma("unroll") for (int _i = 0; _i < 2; ++_i) \
;         __builtin_amdgcn_global_load_lds((const unsigned*)((const char*)(gbase) + (voff)[_i]), (PG8_LAS unsigned*)(lds + (bufoff) + ldsw + _i * 8192), 16, 0, 0); } while (0)
; #define PG8_LDA(dst, b, h) do { _Pragma("unroll") for (int m = 0; m < 4; ++m) _Pragma("unroll") for (int k = 0; k < 2; ++k) dst[m][k] = *(const PG8_LAS bf16x8*)(lds + PG8_SA(b, h) + aoff + m * 2048 + k * 1024); } while (0)
; #define PG8_LDB(dst, b, h) do { _Pragma("unroll") for (int n = 0; n < 2; ++n) _Pragma("unroll") for (int k = 0; k < 2; ++k) dst[n][k] = *(const PG8_LAS bf16x8*)(lds + PG8_SB(b, h) + boff + n * 2048 + k * 1024); } while (0)
; #define PG8_MMA(ai, bj, At, Bt) do { __builtin_amdgcn_s_setprio(1); _Pragma("unroll") for (int m = 0; m < 4; ++m) _Pragma("unroll") for (int n = 0; n < 2; ++n) _Pragma("unroll") for (int k = 0; k < 2; ++k) \
;         acc[ai][bj][m][n] = __builtin_amdgcn_mfma_f32_16x16x32_bf16(Bt[n][k], At[m][k], acc[ai][bj][m][n], 0, 0, 0); __builtin_amdgcn_s_setprio(0); } while (0)
; #define PG8_WAIT_V(n) asm volatile("s_waitcnt vmcnt(" #n ")" ::: "memory")
; #define PG8_WAIT_L(n) asm volatile("s_waitcnt lgkmcnt(" #n ")" ::: "memory")
; #define PG8_BAR __builtin_amdgcn_s_barrier()
; #define PG8_SCHED __builtin_amdgcn_sched_barrier(0)
; template <class Epi, class Sched, bool ALIGN_EPI = false, bool SP2 = false>
; __device__ __forceinline__ void gemm_phase(PG8_LAS unsigned char* lds, const Gemm g, const Sched& S, const Epi& E) {
;     ...
;             PG8_WAIT_V(8); PG8_WAIT_L(0); PG8_BAR; PG8_MMA(0, 0, At, B0); PG8_MMA(0, 1, At, B1); PG8_BAR; PG8_SCHED;
;             PG8_LDA(At, 0, 1); PG8_STAGE(PG8_SB(0, 0), b2, voffB); PG8_STAGE(PG8_SB(0, 1), b2 + hstepB, voffB); PG8_STAGE(PG8_SA(0, 0), a2, voffA);
;             PG8_WAIT_V(8); PG8_WAIT_L(0); PG8_BAR; PG8_MMA(1, 0, At, B0); PG8_MMA(1, 1, At, B1); PG8_BAR; PG8_SCHED;
;             PG8_LDB(B0, 1, 0); PG8_LDB(B1, 1, 1); PG8_SCHED; PG8_LDA(At, 1, 0); PG8_STAGE(PG8_SA(0, 1), a2 + hstepA, voffA);
;             PG8_WAIT_V(8); PG8_WAIT_L(0); PG8_BAR; PG8_MMA(0, 0, At, B0); PG8_MMA(0, 1, At, B1); PG8_BAR; PG8_SCHED;
	s_waitcnt lgkmcnt(0)
	v_mfma_f32_16x16x32_bf16 v[60:63], v[142:145], v[174:177], v[60:63]
	v_mfma_f32_16x16x32_bf16 v[56:59], v[150:153], v[174:177], v[56:59]
	v_mfma_f32_16x16x32_bf16 v[52:55], v[142:145], v[182:185], v[52:55]
	v_mfma_f32_16x16x32_bf16 v[48:51], v[150:153], v[182:185], v[48:51]
	v_mfma_f32_16x16x32_bf16 v[36:39], v[142:145], v[190:193], v[36:39]
	v_mfma_f32_16x16x32_bf16 v[32:35], v[150:153], v[190:193], v[32:35]
	v_mfma_f32_16x16x32_bf16 v[20:23], v[142:145], v[198:201], v[20:23]
	v_mfma_f32_16x16x32_bf16 v[16:19], v[150:153], v[198:201], v[16:19]
	v_mfma_f32_16x16x32_bf16 v[60:63], v[146:149], v[178:181], v[60:63]
	v_mfma_f32_16x16x32_bf16 v[56:59], v[154:157], v[178:181], v[56:59]
	v_mfma_f32_16x16x32_bf16 v[52:55], v[146:149], v[186:189], v[52:55]
	v_mfma_f32_16x16x32_bf16 v[48:51], v[154:157], v[186:189], v[48:51]
	v_mfma_f32_16x16x32_bf16 v[36:39], v[146:149], v[194:197], v[36:39]
	v_mfma_f32_16x16x32_bf16 v[32:35], v[154:157], v[194:197], v[32:35]
	v_mfma_f32_16x16x32_bf16 v[20:23], v[146:149], v[202:205], v[20:23]
	v_mfma_f32_16x16x32_bf16 v[16:19], v[154:157], v[202:205], v[16:19]
	v_mfma_f32_16x16x32_bf16 v[44:47], v[158:161], v[174:177], v[44:47]
	v_mfma_f32_16x16x32_bf16 v[40:43], v[166:169], v[174:177], v[40:43]
	v_mfma_f32_16x16x32_bf16 v[28:31], v[158:161], v[182:185], v[28:31]
	v_mfma_f32_16x16x32_bf16 v[24:27], v[166:169], v[182:185], v[24:27]
	v_mfma_f32_16x16x32_bf16 v[12:15], v[158:161], v[190:193], v[12:15]
	v_mfma_f32_16x16x32_bf16 v[8:11], v[166:169], v[190:193], v[8:11]
	v_mfma_f32_16x16x32_bf16 v[4:7], v[158:161], v[198:201], v[4:7]
	v_mfma_f32_16x16x32_bf16 v[0:3], v[166:169], v[198:201], v[0:3]
	v_mfma_f32_16x16x32_bf16 v[44:47], v[162:165], v[178:181], v[44:47]
	v_mfma_f32_16x16x32_bf16 v[40:43], v[170:173], v[178:181], v[40:43]
	v_mfma_f32_16x16x32_bf16 v[28:31], v[162:165], v[186:189], v[28:31]
	v_mfma_f32_16x16x32_bf16 v[24:27], v[170:173], v[186:189], v[24:27]
	v_mfma_f32_16x16x32_bf16 v[12:15], v[162:165], v[194:197], v[12:15]
	v_mfma_f32_16x16x32_bf16 v[8:11], v[170:173], v[194:197], v[8:11]
	v_mfma_f32_16x16x32_bf16 v[4:7], v[162:165], v[202:205], v[4:7]
	v_mfma_f32_16x16x32_bf16 v[0:3], v[170:173], v[202:205], v[0:3]
	s_barrier
	s_add_i32 s28, 0, 0x18000
	s_add_i32 s29, 0, 0x1c000
	s_add_u32 s46, s46, 0x40000
	s_addc_u32 s47, s47, 0
	s_mov_b32 m0, s26
	s_nop 0
	global_load_lds_dwordx4 v132, s[46:47]
	v_lshl_add_u64 v[224:225], s[46:47], 0, v[130:131]
	s_mov_b32 m0, s34
	s_nop 0
	global_load_lds_dwordx4 v130, s[46:47]
	v_add_u32_e32 v154, s28, v139
	v_add_u32_e32 v170, s29, v139
	ds_read_b128 v[142:145], v154
	ds_read_b128 v[146:149], v154 offset:1024
	ds_read_b128 v[150:153], v154 offset:2048
	ds_read_b128 v[154:157], v154 offset:3072
	ds_read_b128 v[158:161], v170
	ds_read_b128 v[162:165], v170 offset:1024
	ds_read_b128 v[166:169], v170 offset:2048
	ds_read_b128 v[170:173], v170 offset:3072
	ds_read_b128 v[174:177], v141 offset:32768
	ds_read_b128 v[178:181], v141 offset:33792
	ds_read_b128 v[182:185], v141 offset:34816
	ds_read_b128 v[186:189], v141 offset:35840
	ds_read_b128 v[190:193], v141 offset:36864
	ds_read_b128 v[194:197], v141 offset:37888
	ds_read_b128 v[198:201], v141 offset:38912
	ds_read_b128 v[202:205], v141 offset:39936
	s_waitcnt vmcnt(8)
	s_waitcnt lgkmcnt(0)
	s_barrier
	s_waitcnt lgkmcnt(0)
	v_mfma_f32_16x16x32_bf16 v[124:127], v[142:145], v[174:177], v[124:127]
	v_mfma_f32_16x16x32_bf16 v[120:123], v[150:153], v[174:177], v[120:123]
	v_mfma_f32_16x16x32_bf16 v[116:119], v[142:145], v[182:185], v[116:119]
	v_mfma_f32_16x16x32_bf16 v[112:115], v[150:153], v[182:185], v[112:115]
	v_mfma_f32_16x16x32_bf16 v[100:103], v[142:145], v[190:193], v[100:103]
	v_mfma_f32_16x16x32_bf16 v[96:99], v[150:153], v[190:193], v[96:99]
	v_mfma_f32_16x16x32_bf16 v[84:87], v[142:145], v[198:201], v[84:87]
	v_mfma_f32_16x16x32_bf16 v[80:83], v[150:153], v[198:201], v[80:83]
	v_mfma_f32_16x16x32_bf16 v[124:127], v[146:149], v[178:181], v[124:127]
	v_mfma_f32_16x16x32_bf16 v[120:123], v[154:157], v[178:181], v[120:123]
	v_mfma_f32_16x16x32_bf16 v[116:119], v[146:149], v[186:189], v[116:119]
	v_mfma_f32_16x16x32_bf16 v[112:115], v[154:157], v[186:189], v[112:115]
	v_mfma_f32_16x16x32_bf16 v[100:103], v[146:149], v[194:197], v[100:103]
	v_mfma_f32_16x16x32_bf16 v[96:99], v[154:157], v[194:197], v[96:99]
	v_mfma_f32_16x16x32_bf16 v[84:87], v[146:149], v[202:205], v[84:87]
	v_mfma_f32_16x16x32_bf16 v[80:83], v[154:157], v[202:205], v[80:83]
	v_mfma_f32_16x16x32_bf16 v[108:111], v[158:161], v[174:177], v[108:111]
	v_mfma_f32_16x16x32_bf16 v[104:107], v[166:169], v[174:177], v[104:107]
	v_mfma_f32_16x16x32_bf16 v[92:95], v[158:161], v[182:185], v[92:95]
	v_mfma_f32_16x16x32_bf16 v[88:91], v[166:169], v[182:185], v[88:91]
	v_mfma_f32_16x16x32_bf16 v[76:79], v[158:161], v[190:193], v[76:79]
	v_mfma_f32_16x16x32_bf16 v[72:75], v[166:169], v[190:193], v[72:75]
	v_mfma_f32_16x16x32_bf16 v[68:71], v[158:161], v[198:201], v[68:71]
	v_mfma_f32_16x16x32_bf16 v[64:67], v[166:169], v[198:201], v[64:67]
	v_mfma_f32_16x16x32_bf16 v[108:111], v[162:165], v[178:181], v[108:111]
	v_mfma_f32_16x16x32_bf16 v[104:107], v[170:173], v[178:181], v[104:107]
	v_mfma_f32_16x16x32_bf16 v[92:95], v[162:165], v[186:189], v[92:95]
	v_mfma_f32_16x16x32_bf16 v[88:91], v[170:173], v[186:189], v[88:91]
	v_mfma_f32_16x16x32_bf16 v[76:79], v[162:165], v[194:197], v[76:79]
	v_mfma_f32_16x16x32_bf16 v[72:75], v[170:173], v[194:197], v[72:75]
	v_mfma_f32_16x16x32_bf16 v[68:71], v[162:165], v[202:205], v[68:71]
	v_mfma_f32_16x16x32_bf16 v[64:67], v[170:173], v[202:205], v[64:67]
	s_barrier
; #define PG8_STAGE(bufoff, gbase, voff) do { _Pragma("unroll") for (int _i = 0; _i < 2; ++_i) \
;         __builtin_amdgcn_global_load_lds((const unsigned*)((const char*)(gbase) + (voff)[_i]), (PG8_LAS unsigned*)(lds + (bufoff) + ldsw + _i * 8192), 16, 0, 0); } while (0)
; #define PG8_LDA(dst, b, h) do { _Pragma("unroll") for (int m = 0; m < 4; ++m) _Pragma("unroll") for (int k = 0; k < 2; ++k) dst[m][k] = *(const PG8_LAS bf16x8*)(lds + PG8_SA(b, h) + aoff + m * 2048 + k * 1024); } while (0)
; #define PG8_MMA(ai, bj, At, Bt) do { __builtin_amdgcn_s_setprio(1); _Pragma("unroll") for (int m = 0; m < 4; ++m) _Pragma("unroll") for (int n = 0; n < 2; ++n) _Pragma("unroll") for (int k = 0; k < 2; ++k) \
;         acc[ai][bj][m][n] = __builtin_amdgcn_mfma_f32_16x16x32_bf16(Bt[n][k], At[m][k], acc[ai][bj][m][n], 0, 0, 0); __builtin_amdgcn_s_setprio(0); } while (0)
; #define PG8_WAIT_V(n) asm volatile("s_waitcnt vmcnt(" #n ")" ::: "memory")
; #define PG8_WAIT_L(n) asm volatile("s_waitcnt lgkmcnt(" #n ")" ::: "memory")
; #define PG8_BAR __builtin_amdgcn_s_barrier()
; #define PG8_SCHED __builtin_amdgcn_sched_barrier(0)
; template <class Epi, class Sched, bool ALIGN_EPI = false, bool SP2 = false>
; __device__ __forceinline__ void gemm_phase(PG8_LAS unsigned char* lds, const Gemm g, const Sched& S, const Epi& E) {
;     ...
;             PG8_WAIT_V(8); PG8_WAIT_L(0); PG8_BAR; PG8_MMA(0, 0, At, B0); PG8_MMA(0, 1, At, B1); PG8_BAR; PG8_SCHED;
;             PG8_LDA(At, 1, 1); PG8_STAGE(PG8_SB(1, 0), b3, voffB); PG8_STAGE(PG8_SB(1, 1), b3 + hstepB, voffB); PG8_STAGE(PG8_SA(1, 0), a3, voffA);
;             PG8_WAIT_V(8); PG8_WAIT_L(0); PG8_BAR; PG8_MMA(1, 0, At, B0); PG8_MMA(1, 1, At, B1); PG8_BAR; PG8_SCHED;
;     ...
;         if constexpr (ALIGN_EPI) { if (wr == 0) PG8_BAR; }
	s_add_i32 s28, s28, s18
	v_lshl_add_u64 v[206:207], v[206:207], 0, s[10:11]
	s_mov_b32 m0, s28
	s_nop 0
	global_load_lds_dwordx4 v[206:207], off
	s_add_i32 m0, s28, 0x2000
	s_add_u32 s22, s22, 0x40080
	v_lshl_add_u64 v[206:207], v[210:211], 0, s[10:11]
	s_addc_u32 s23, s23, 0
	s_add_i32 s28, s29, s18
	global_load_lds_dwordx4 v[206:207], off
	s_mov_b32 m0, s28
	s_nop 0
	global_load_lds_dwordx4 v208, s[22:23]
	s_add_i32 m0, s28, 0x2000
	s_nop 0
	global_load_lds_dwordx4 v128, s[22:23]
	v_lshl_add_u64 v[206:207], v[212:213], 0, s[10:11]
	s_mov_b32 m0, s35
	s_nop 0
	global_load_lds_dwordx4 v[206:207], off
	v_lshl_add_u64 v[206:207], v[222:223], 0, s[10:11]
	s_mov_b32 m0, s39
	s_nop 0
	global_load_lds_dwordx4 v[206:207], off
	ds_read_b128 v[174:177], v141 offset:49152
	ds_read_b128 v[178:181], v141 offset:50176
	ds_read_b128 v[182:185], v141 offset:51200
	ds_read_b128 v[186:189], v141 offset:52224
	ds_read_b128 v[190:193], v141 offset:53248
	ds_read_b128 v[194:197], v141 offset:54272
	ds_read_b128 v[198:201], v141 offset:55296
	ds_read_b128 v[202:205], v141 offset:56320
	s_waitcnt vmcnt(8)
	s_waitcnt lgkmcnt(0)
	s_barrier
	s_waitcnt lgkmcnt(0)
	v_mfma_f32_16x16x32_bf16 v[60:63], v[142:145], v[174:177], v[60:63]
	v_mfma_f32_16x16x32_bf16 v[56:59], v[150:153], v[174:177], v[56:59]
	v_mfma_f32_16x16x32_bf16 v[52:55], v[142:145], v[182:185], v[52:55]
	v_mfma_f32_16x16x32_bf16 v[48:51], v[150:153], v[182:185], v[48:51]
	v_mfma_f32_16x16x32_bf16 v[36:39], v[142:145], v[190:193], v[36:39]
	v_mfma_f32_16x16x32_bf16 v[32:35], v[150:153], v[190:193], v[32:35]
	v_mfma_f32_16x16x32_bf16 v[20:23], v[142:145], v[198:201], v[20:23]
	v_mfma_f32_16x16x32_bf16 v[16:19], v[150:153], v[198:201], v[16:19]
	v_mfma_f32_16x16x32_bf16 v[60:63], v[146:149], v[178:181], v[60:63]
	v_mfma_f32_16x16x32_bf16 v[56:59], v[154:157], v[178:181], v[56:59]
	v_mfma_f32_16x16x32_bf16 v[52:55], v[146:149], v[186:189], v[52:55]
	v_mfma_f32_16x16x32_bf16 v[48:51], v[154:157], v[186:189], v[48:51]
	v_mfma_f32_16x16x32_bf16 v[36:39], v[146:149], v[194:197], v[36:39]
	v_mfma_f32_16x16x32_bf16 v[32:35], v[154:157], v[194:197], v[32:35]
	v_mfma_f32_16x16x32_bf16 v[20:23], v[146:149], v[202:205], v[20:23]
	v_mfma_f32_16x16x32_bf16 v[16:19], v[154:157], v[202:205], v[16:19]
	v_mfma_f32_16x16x32_bf16 v[44:47], v[158:161], v[174:177], v[44:47]
	v_mfma_f32_16x16x32_bf16 v[40:43], v[166:169], v[174:177], v[40:43]
	v_mfma_f32_16x16x32_bf16 v[28:31], v[158:161], v[182:185], v[28:31]
	v_mfma_f32_16x16x32_bf16 v[24:27], v[166:169], v[182:185], v[24:27]
	v_mfma_f32_16x16x32_bf16 v[12:15], v[158:161], v[190:193], v[12:15]
	v_mfma_f32_16x16x32_bf16 v[8:11], v[166:169], v[190:193], v[8:11]
	v_mfma_f32_16x16x32_bf16 v[4:7], v[158:161], v[198:201], v[4:7]
	v_mfma_f32_16x16x32_bf16 v[0:3], v[166:169], v[198:201], v[0:3]
	v_mfma_f32_16x16x32_bf16 v[44:47], v[162:165], v[178:181], v[44:47]
	v_mfma_f32_16x16x32_bf16 v[40:43], v[170:173], v[178:181], v[40:43]
	v_mfma_f32_16x16x32_bf16 v[28:31], v[162:165], v[186:189], v[28:31]
	v_mfma_f32_16x16x32_bf16 v[24:27], v[170:173], v[186:189], v[24:27]
	v_mfma_f32_16x16x32_bf16 v[12:15], v[162:165], v[194:197], v[12:15]
	v_mfma_f32_16x16x32_bf16 v[8:11], v[170:173], v[194:197], v[8:11]
	v_mfma_f32_16x16x32_bf16 v[4:7], v[162:165], v[202:205], v[4:7]
	v_mfma_f32_16x16x32_bf16 v[0:3], v[170:173], v[202:205], v[0:3]
	s_barrier
	s_add_i32 s51, s51, 2
	s_add_u32 s44, s44, 0x100
	s_addc_u32 s45, s45, 0
	s_add_u32 s49, s49, 0x100
	s_addc_u32 s50, s50, 0
	s_cmp_gt_u32 s51, 13
	s_cbranch_scc0 .LBB0_354
	s_and_b64 vcc, exec, s[8:9]
	s_cbranch_vccz .LBB0_357
	s_barrier

; #define PG8_STAGE(bufoff, gbase, voff) do { _Pragma("unroll") for (int _i = 0; _i < 2; ++_i) \
;         __builtin_amdgcn_global_load_lds((const unsigned*)((const char*)(gbase) + (voff)[_i]), (PG8_LAS unsigned*)(lds + (bufoff) + ldsw + _i * 8192), 16, 0, 0); } while (0)
; #define PG8_LDA(dst, b, h) do { _Pragma("unroll") for (int m = 0; m < 4; ++m) _Pragma("unroll") for (int k = 0; k < 2; ++k) dst[m][k] = *(const PG8_LAS bf16x8*)(lds + PG8_SA(b, h) + aoff + m * 2048 + k * 1024); } while (0)
; #define PG8_LDB(dst, b, h) do { _Pragma("unroll") for (int n = 0; n < 2; ++n) _Pragma("unroll") for (int k = 0; k < 2; ++k) dst[n][k] = *(const PG8_LAS bf16x8*)(lds + PG8_SB(b, h) + boff + n * 2048 + k * 1024); } while (0)
; #define PG8_MMA(ai, bj, At, Bt) do { __builtin_amdgcn_s_setprio(1); _Pragma("unroll") for (int m = 0; m < 4; ++m) _Pragma("unroll") for (int n = 0; n < 2; ++n) _Pragma("unroll") for (int k = 0; k < 2; ++k) \
;         acc[ai][bj][m][n] = __builtin_amdgcn_mfma_f32_16x16x32_bf16(Bt[n][k], At[m][k], acc[ai][bj][m][n], 0, 0, 0); __builtin_amdgcn_s_setprio(0); } while (0)
; #define PG8_WAIT_V(n) asm volatile("s_waitcnt vmcnt(" #n ")" ::: "memory")
; #define PG8_WAIT_L(n) asm volatile("s_waitcnt lgkmcnt(" #n ")" ::: "memory")
; template <class Epi, class Sched, bool ALIGN_EPI = false, bool SP2 = false>
; __device__ __forceinline__ void gemm_phase(PG8_LAS unsigned char* lds, const Gemm g, const Sched& S, const Epi& E) {
;     ...
;             const bool last = (t == nt - 2);
;             const char* a1 = cA + (size_t)(t + 1) * kstep;
;             const char* a2 = last ? nA : cA + (size_t)(t + 2) * kstep; const char* b2 = last ? nB : cB + (size_t)(t + 2) * kstep;
;             const char* a3 = a2 + kstep; const char* b3 = b2 + kstep;
;             if (last && has_next) S.a_ready(nxt);
;             if constexpr (SP2) {
;             PG8_LDB(B0, 0, 0); PG8_LDB(B1, 0, 1); PG8_SCHED; PG8_LDA(At, 0, 0); PG8_STAGE(PG8_SA(1, 1), a1 + hstepA, voffA);
;             PG8_WAIT_V(8); PG8_WAIT_L(0); PG8_BAR; PG8_MMA(0, 0, At, B0); PG8_MMA(0, 1, At, B1); PG8_BAR; PG8_SCHED;
;             PG8_LDA(At, 0, 1); PG8_STAGE(PG8_SB(0, 0), b2, voffB); PG8_STAGE(PG8_SB(0, 1), b2 + hstepB, voffB); PG8_STAGE(PG8_SA(0, 0), a2, voffA);
;             PG8_WAIT_V(8); PG8_WAIT_L(0); PG8_BAR; PG8_MMA(1, 0, At, B0); PG8_MMA(1, 1, At, B1); PG8_BAR; PG8_SCHED;
.LBB0_607:
	s_add_u32 s22, s0, 0xfffc0080
	s_addc_u32 s23, s1, -1
	s_add_i32 s28, 0, 0x10000
	s_cmp_eq_u32 s51, 12
	s_cselect_b32 s25, s14, s23
	s_cselect_b32 s24, s15, s22
	s_cselect_b32 s23, s9, s50
	s_cselect_b32 s22, s38, s43
	s_add_i32 s29, 0, 0x14000
	s_add_i32 m0, s21, 0xc000
	s_nop 0
	global_load_lds_dwordx4 v134, s[0:1]
	s_add_i32 m0, s21, 0xe000
	s_nop 0
	global_load_lds_dwordx4 v136, s[0:1]
	v_add_u32_e32 v154, s28, v143
	v_add_u32_e32 v170, s29, v143
	ds_read_b128 v[138:141], v154
	ds_read_b128 v[146:149], v154 offset:1024
	ds_read_b128 v[150:153], v154 offset:2048
	ds_read_b128 v[154:157], v154 offset:3072
	ds_read_b128 v[158:161], v170
	ds_read_b128 v[162:165], v170 offset:1024
	ds_read_b128 v[166:169], v170 offset:2048
	ds_read_b128 v[170:173], v170 offset:3072
	ds_read_b128 v[174:177], v145
	ds_read_b128 v[178:181], v145 offset:1024
	ds_read_b128 v[182:185], v145 offset:2048
	ds_read_b128 v[186:189], v145 offset:3072
	ds_read_b128 v[190:193], v145 offset:4096
	ds_read_b128 v[194:197], v145 offset:5120
	ds_read_b128 v[198:201], v145 offset:6144
	ds_read_b128 v[202:205], v145 offset:7168
	s_waitcnt vmcnt(8)
	s_waitcnt lgkmcnt(0)
	s_barrier
	s_waitcnt lgkmcnt(0)
	v_mfma_f32_16x16x32_bf16 v[124:127], v[138:141], v[174:177], v[124:127]
	v_mfma_f32_16x16x32_bf16 v[120:123], v[150:153], v[174:177], v[120:123]
	v_mfma_f32_16x16x32_bf16 v[108:111], v[138:141], v[182:185], v[108:111]
	v_mfma_f32_16x16x32_bf16 v[104:107], v[150:153], v[182:185], v[104:107]
	v_mfma_f32_16x16x32_bf16 v[92:95], v[138:141], v[190:193], v[92:95]
	v_mfma_f32_16x16x32_bf16 v[88:91], v[150:153], v[190:193], v[88:91]
	v_mfma_f32_16x16x32_bf16 v[76:79], v[138:141], v[198:201], v[76:79]
	v_mfma_f32_16x16x32_bf16 v[72:75], v[150:153], v[198:201], v[72:75]
	v_mfma_f32_16x16x32_bf16 v[124:127], v[146:149], v[178:181], v[124:127]
	v_mfma_f32_16x16x32_bf16 v[120:123], v[154:157], v[178:181], v[120:123]
	v_mfma_f32_16x16x32_bf16 v[108:111], v[146:149], v[186:189], v[108:111]
	v_mfma_f32_16x16x32_bf16 v[104:107], v[154:157], v[186:189], v[104:107]
	v_mfma_f32_16x16x32_bf16 v[92:95], v[146:149], v[194:197], v[92:95]
	v_mfma_f32_16x16x32_bf16 v[88:91], v[154:157], v[194:197], v[88:91]
	v_mfma_f32_16x16x32_bf16 v[76:79], v[146:149], v[202:205], v[76:79]
	v_mfma_f32_16x16x32_bf16 v[72:75], v[154:157], v[202:205], v[72:75]
	v_mfma_f32_16x16x32_bf16 v[116:119], v[158:161], v[174:177], v[116:119]
	v_mfma_f32_16x16x32_bf16 v[112:115], v[166:169], v[174:177], v[112:115]
	v_mfma_f32_16x16x32_bf16 v[100:103], v[158:161], v[182:185], v[100:103]
	v_mfma_f32_16x16x32_bf16 v[96:99], v[166:169], v[182:185], v[96:99]
	v_mfma_f32_16x16x32_bf16 v[84:87], v[158:161], v[190:193], v[84:87]
	v_mfma_f32_16x16x32_bf16 v[80:83], v[166:169], v[190:193], v[80:83]
	v_mfma_f32_16x16x32_bf16 v[68:71], v[158:161], v[198:201], v[68:71]
	v_mfma_f32_16x16x32_bf16 v[64:67], v[166:169], v[198:201], v[64:67]
	v_mfma_f32_16x16x32_bf16 v[116:119], v[162:165], v[178:181], v[116:119]
	v_mfma_f32_16x16x32_bf16 v[112:115], v[170:173], v[178:181], v[112:115]
	v_mfma_f32_16x16x32_bf16 v[100:103], v[162:165], v[186:189], v[100:103]
	v_mfma_f32_16x16x32_bf16 v[96:99], v[170:173], v[186:189], v[96:99]
	v_mfma_f32_16x16x32_bf16 v[84:87], v[162:165], v[194:197], v[84:87]
	v_mfma_f32_16x16x32_bf16 v[80:83], v[170:173], v[194:197], v[80:83]
	v_mfma_f32_16x16x32_bf16 v[68:71], v[162:165], v[202:205], v[68:71]
	v_mfma_f32_16x16x32_bf16 v[64:67], v[170:173], v[202:205], v[64:67]
	s_barrier
	s_add_i32 s28, s28, s26
	v_lshl_add_u64 v[206:207], s[22:23], 0, v[208:209]
	s_mov_b32 m0, s28
	s_nop 0
	global_load_lds_dwordx4 v208, s[22:23]
	s_add_i32 m0, s28, 0x2000
	s_add_u32 s52, s22, 0x40000
	v_lshl_add_u64 v[210:211], s[22:23], 0, v[128:129]
	s_addc_u32 s53, s23, 0
	s_add_i32 s28, s29, s26
	global_load_lds_dwordx4 v128, s[22:23]
	s_mov_b32 m0, s28
	v_lshl_add_u64 v[222:223], s[24:25], 0, v[130:131]
	global_load_lds_dwordx4 v208, s[52:53]
	s_add_i32 m0, s28, 0x2000
	s_nop 0
	global_load_lds_dwordx4 v128, s[52:53]
	v_lshl_add_u64 v[212:213], s[24:25], 0, v[132:133]
	s_mov_b32 m0, s21
	s_nop 0
	global_load_lds_dwordx4 v132, s[24:25]
	s_mov_b32 m0, s18
	s_nop 0
	global_load_lds_dwordx4 v130, s[24:25]
	ds_read_b128 v[174:177], v145 offset:16384
	ds_read_b128 v[178:181], v145 offset:17408
	ds_read_b128 v[182:185], v145 offset:18432
	ds_read_b128 v[186:189], v145 offset:19456
	ds_read_b128 v[190:193], v145 offset:20480
	ds_read_b128 v[194:197], v145 offset:21504
	ds_read_b128 v[198:201], v145 offset:22528
	ds_read_b128 v[202:205], v145 offset:23552
	s_waitcnt vmcnt(8)
	s_waitcnt lgkmcnt(0)
	s_barrier
; #define PG8_STAGE(bufoff, gbase, voff) do { _Pragma("unroll") for (int _i = 0; _i < 2; ++_i) \
;         __builtin_amdgcn_global_load_lds((const unsigned*)((const char*)(gbase) + (voff)[_i]), (PG8_LAS unsigned*)(lds + (bufoff) + ldsw + _i * 8192), 16, 0, 0); } while (0)
; #define PG8_LDA(dst, b, h) do { _Pragma("unroll") for (int m = 0; m < 4; ++m) _Pragma("unroll") for (int k = 0; k < 2; ++k) dst[m][k] = *(const PG8_LAS bf16x8*)(lds + PG8_SA(b, h) + aoff + m * 2048 + k * 1024); } while (0)
; #define PG8_LDB(dst, b, h) do { _Pragma("unroll") for (int n = 0; n < 2; ++n) _Pragma("unroll") for (int k = 0; k < 2; ++k) dst[n][k] = *(const PG8_LAS bf16x8*)(lds + PG8_SB(b, h) + boff + n * 2048 + k * 1024); } while (0)
; #define PG8_MMA(ai, bj, At, Bt) do { __builtin_amdgcn_s_setprio(1); _Pragma("unroll") for (int m = 0; m < 4; ++m) _Pragma("unroll") for (int n = 0; n < 2; ++n) _Pragma("unroll") for (int k = 0; k < 2; ++k) \
;         acc[ai][bj][m][n] = __builtin_amdgcn_mfma_f32_16x16x32_bf16(Bt[n][k], At[m][k], acc[ai][bj][m][n], 0, 0, 0); __builtin_amdgcn_s_setprio(0); } while (0)
; #define PG8_WAIT_V(n) asm volatile("s_waitcnt vmcnt(" #n ")" ::: "memory")
; #define PG8_WAIT_L(n) asm volatile("s_waitcnt lgkmcnt(" #n ")" ::: "memory")
; #define PG8_BAR __builtin_amdgcn_s_barrier()
; #define PG8_SCHED __builtin_amdgcn_sched_barrier(0)
; template <class Epi, class Sched, bool ALIGN_EPI = false, bool SP2 = false>
; __device__ __forceinline__ void gemm_phase(PG8_LAS unsigned char* lds, const Gemm g, const Sched& S, const Epi& E) {
;     ...
;             PG8_WAIT_V(8); PG8_WAIT_L(0); PG8_BAR; PG8_MMA(0, 0, At, B0); PG8_MMA(0, 1, At, B1); PG8_BAR; PG8_SCHED;
;             PG8_LDA(At, 0, 1); PG8_STAGE(PG8_SB(0, 0), b2, voffB); PG8_STAGE(PG8_SB(0, 1), b2 + hstepB, voffB); PG8_STAGE(PG8_SA(0, 0), a2, voffA);
;             PG8_WAIT_V(8); PG8_WAIT_L(0); PG8_BAR; PG8_MMA(1, 0, At, B0); PG8_MMA(1, 1, At, B1); PG8_BAR; PG8_SCHED;
;             PG8_LDB(B0, 1, 0); PG8_LDB(B1, 1, 1); PG8_SCHED; PG8_LDA(At, 1, 0); PG8_STAGE(PG8_SA(0, 1), a2 + hstepA, voffA);
;             PG8_WAIT_V(8); PG8_WAIT_L(0); PG8_BAR; PG8_MMA(0, 0, At, B0); PG8_MMA(0, 1, At, B1); PG8_BAR; PG8_SCHED;
	s_waitcnt lgkmcnt(0)
	v_mfma_f32_16x16x32_bf16 v[60:63], v[138:141], v[174:177], v[60:63]
	v_mfma_f32_16x16x32_bf16 v[56:59], v[150:153], v[174:177], v[56:59]
	v_mfma_f32_16x16x32_bf16 v[44:47], v[138:141], v[182:185], v[44:47]
	v_mfma_f32_16x16x32_bf16 v[40:43], v[150:153], v[182:185], v[40:43]
	v_mfma_f32_16x16x32_bf16 v[28:31], v[138:141], v[190:193], v[28:31]
	v_mfma_f32_16x16x32_bf16 v[24:27], v[150:153], v[190:193], v[24:27]
	v_mfma_f32_16x16x32_bf16 v[12:15], v[138:141], v[198:201], v[12:15]
	v_mfma_f32_16x16x32_bf16 v[8:11], v[150:153], v[198:201], v[8:11]
	v_mfma_f32_16x16x32_bf16 v[60:63], v[146:149], v[178:181], v[60:63]
	v_mfma_f32_16x16x32_bf16 v[56:59], v[154:157], v[178:181], v[56:59]
	v_mfma_f32_16x16x32_bf16 v[44:47], v[146:149], v[186:189], v[44:47]
	v_mfma_f32_16x16x32_bf16 v[40:43], v[154:157], v[186:189], v[40:43]
	v_mfma_f32_16x16x32_bf16 v[28:31], v[146:149], v[194:197], v[28:31]
	v_mfma_f32_16x16x32_bf16 v[24:27], v[154:157], v[194:197], v[24:27]
	v_mfma_f32_16x16x32_bf16 v[12:15], v[146:149], v[202:205], v[12:15]
	v_mfma_f32_16x16x32_bf16 v[8:11], v[154:157], v[202:205], v[8:11]
	v_mfma_f32_16x16x32_bf16 v[52:55], v[158:161], v[174:177], v[52:55]
	v_mfma_f32_16x16x32_bf16 v[48:51], v[166:169], v[174:177], v[48:51]
	v_mfma_f32_16x16x32_bf16 v[36:39], v[158:161], v[182:185], v[36:39]
	v_mfma_f32_16x16x32_bf16 v[32:35], v[166:169], v[182:185], v[32:35]
	v_mfma_f32_16x16x32_bf16 v[20:23], v[158:161], v[190:193], v[20:23]
	v_mfma_f32_16x16x32_bf16 v[16:19], v[166:169], v[190:193], v[16:19]
	v_mfma_f32_16x16x32_bf16 v[4:7], v[158:161], v[198:201], v[4:7]
	v_mfma_f32_16x16x32_bf16 v[0:3], v[166:169], v[198:201], v[0:3]
	v_mfma_f32_16x16x32_bf16 v[52:55], v[162:165], v[178:181], v[52:55]
	v_mfma_f32_16x16x32_bf16 v[48:51], v[170:173], v[178:181], v[48:51]
	v_mfma_f32_16x16x32_bf16 v[36:39], v[162:165], v[186:189], v[36:39]
	v_mfma_f32_16x16x32_bf16 v[32:35], v[170:173], v[186:189], v[32:35]
	v_mfma_f32_16x16x32_bf16 v[20:23], v[162:165], v[194:197], v[20:23]
	v_mfma_f32_16x16x32_bf16 v[16:19], v[170:173], v[194:197], v[16:19]
	v_mfma_f32_16x16x32_bf16 v[4:7], v[162:165], v[202:205], v[4:7]
	v_mfma_f32_16x16x32_bf16 v[0:3], v[170:173], v[202:205], v[0:3]
	s_barrier
	s_add_i32 s28, 0, 0x18000
	s_add_i32 s29, 0, 0x1c000
	s_add_u32 s24, s24, 0x40000
	s_addc_u32 s25, s25, 0
	s_mov_b32 m0, s19
	s_nop 0
	global_load_lds_dwordx4 v132, s[24:25]
	v_lshl_add_u64 v[224:225], s[24:25], 0, v[130:131]
	s_mov_b32 m0, s34
	s_nop 0
	global_load_lds_dwordx4 v130, s[24:25]
	v_add_u32_e32 v154, s28, v143
	v_add_u32_e32 v170, s29, v143
	ds_read_b128 v[138:141], v154
	ds_read_b128 v[146:149], v154 offset:1024
	ds_read_b128 v[150:153], v154 offset:2048
	ds_read_b128 v[154:157], v154 offset:3072
	ds_read_b128 v[158:161], v170
	ds_read_b128 v[162:165], v170 offset:1024
	ds_read_b128 v[166:169], v170 offset:2048
	ds_read_b128 v[170:173], v170 offset:3072
	ds_read_b128 v[174:177], v145 offset:32768
	ds_read_b128 v[178:181], v145 offset:33792
	ds_read_b128 v[182:185], v145 offset:34816
	ds_read_b128 v[186:189], v145 offset:35840
	ds_read_b128 v[190:193], v145 offset:36864
	ds_read_b128 v[194:197], v145 offset:37888
	ds_read_b128 v[198:201], v145 offset:38912
	ds_read_b128 v[202:205], v145 offset:39936
	s_waitcnt vmcnt(8)
	s_waitcnt lgkmcnt(0)
	s_barrier
	s_waitcnt lgkmcnt(0)
	v_mfma_f32_16x16x32_bf16 v[124:127], v[138:141], v[174:177], v[124:127]
	v_mfma_f32_16x16x32_bf16 v[120:123], v[150:153], v[174:177], v[120:123]
	v_mfma_f32_16x16x32_bf16 v[108:111], v[138:141], v[182:185], v[108:111]
	v_mfma_f32_16x16x32_bf16 v[104:107], v[150:153], v[182:185], v[104:107]
	v_mfma_f32_16x16x32_bf16 v[92:95], v[138:141], v[190:193], v[92:95]
	v_mfma_f32_16x16x32_bf16 v[88:91], v[150:153], v[190:193], v[88:91]
	v_mfma_f32_16x16x32_bf16 v[76:79], v[138:141], v[198:201], v[76:79]
	v_mfma_f32_16x16x32_bf16 v[72:75], v[150:153], v[198:201], v[72:75]
	v_mfma_f32_16x16x32_bf16 v[124:127], v[146:149], v[178:181], v[124:127]
	v_mfma_f32_16x16x32_bf16 v[120:123], v[154:157], v[178:181], v[120:123]
	v_mfma_f32_16x16x32_bf16 v[108:111], v[146:149], v[186:189], v[108:111]
	v_mfma_f32_16x16x32_bf16 v[104:107], v[154:157], v[186:189], v[104:107]
	v_mfma_f32_16x16x32_bf16 v[92:95], v[146:149], v[194:197], v[92:95]
	v_mfma_f32_16x16x32_bf16 v[88:91], v[154:157], v[194:197], v[88:91]
	v_mfma_f32_16x16x32_bf16 v[76:79], v[146:149], v[202:205], v[76:79]
	v_mfma_f32_16x16x32_bf16 v[72:75], v[154:157], v[202:205], v[72:75]
	v_mfma_f32_16x16x32_bf16 v[116:119], v[158:161], v[174:177], v[116:119]
	v_mfma_f32_16x16x32_bf16 v[112:115], v[166:169], v[174:177], v[112:115]
	v_mfma_f32_16x16x32_bf16 v[100:103], v[158:161], v[182:185], v[100:103]
	v_mfma_f32_16x16x32_bf16 v[96:99], v[166:169], v[182:185], v[96:99]
	v_mfma_f32_16x16x32_bf16 v[84:87], v[158:161], v[190:193], v[84:87]
	v_mfma_f32_16x16x32_bf16 v[80:83], v[166:169], v[190:193], v[80:83]
	v_mfma_f32_16x16x32_bf16 v[68:71], v[158:161], v[198:201], v[68:71]
	v_mfma_f32_16x16x32_bf16 v[64:67], v[166:169], v[198:201], v[64:67]
	v_mfma_f32_16x16x32_bf16 v[116:119], v[162:165], v[178:181], v[116:119]
	v_mfma_f32_16x16x32_bf16 v[112:115], v[170:173], v[178:181], v[112:115]
	v_mfma_f32_16x16x32_bf16 v[100:103], v[162:165], v[186:189], v[100:103]
	v_mfma_f32_16x16x32_bf16 v[96:99], v[170:173], v[186:189], v[96:99]
	v_mfma_f32_16x16x32_bf16 v[84:87], v[162:165], v[194:197], v[84:87]
	v_mfma_f32_16x16x32_bf16 v[80:83], v[170:173], v[194:197], v[80:83]
	v_mfma_f32_16x16x32_bf16 v[68:71], v[162:165], v[202:205], v[68:71]
	v_mfma_f32_16x16x32_bf16 v[64:67], v[170:173], v[202:205], v[64:67]
	s_barrier
; #define PG8_STAGE(bufoff, gbase, voff) do { _Pragma("unroll") for (int _i = 0; _i < 2; ++_i) \
;         __builtin_amdgcn_global_load_lds((const unsigned*)((const char*)(gbase) + (voff)[_i]), (PG8_LAS unsigned*)(lds + (bufoff) + ldsw + _i * 8192), 16, 0, 0); } while (0)
; #define PG8_LDA(dst, b, h) do { _Pragma("unroll") for (int m = 0; m < 4; ++m) _Pragma("unroll") for (int k = 0; k < 2; ++k) dst[m][k] = *(const PG8_LAS bf16x8*)(lds + PG8_SA(b, h) + aoff + m * 2048 + k * 1024); } while (0)
; #define PG8_MMA(ai, bj, At, Bt) do { __builtin_amdgcn_s_setprio(1); _Pragma("unroll") for (int m = 0; m < 4; ++m) _Pragma("unroll") for (int n = 0; n < 2; ++n) _Pragma("unroll") for (int k = 0; k < 2; ++k) \
;         acc[ai][bj][m][n] = __builtin_amdgcn_mfma_f32_16x16x32_bf16(Bt[n][k], At[m][k], acc[ai][bj][m][n], 0, 0, 0); __builtin_amdgcn_s_setprio(0); } while (0)
; #define PG8_WAIT_V(n) asm volatile("s_waitcnt vmcnt(" #n ")" ::: "memory")
; #define PG8_WAIT_L(n) asm volatile("s_waitcnt lgkmcnt(" #n ")" ::: "memory")
; #define PG8_BAR __builtin_amdgcn_s_barrier()
; #define PG8_SCHED __builtin_amdgcn_sched_barrier(0)
; template <class Epi, class Sched, bool ALIGN_EPI = false, bool SP2 = false>
; __device__ __forceinline__ void gemm_phase(PG8_LAS unsigned char* lds, const Gemm g, const Sched& S, const Epi& E) {
;     ...
;             PG8_WAIT_V(8); PG8_WAIT_L(0); PG8_BAR; PG8_MMA(0, 0, At, B0); PG8_MMA(0, 1, At, B1); PG8_BAR; PG8_SCHED;
;             PG8_LDA(At, 1, 1); PG8_STAGE(PG8_SB(1, 0), b3, voffB); PG8_STAGE(PG8_SB(1, 1), b3 + hstepB, voffB); PG8_STAGE(PG8_SA(1, 0), a3, voffA);
;             PG8_WAIT_V(8); PG8_WAIT_L(0); PG8_BAR; PG8_MMA(1, 0, At, B0); PG8_MMA(1, 1, At, B1); PG8_BAR; PG8_SCHED;
;     ...
;         if constexpr (ALIGN_EPI) { if (wr == 0) PG8_BAR; }
	s_add_i32 s24, s28, s26
	v_lshl_add_u64 v[206:207], v[206:207], 0, s[10:11]
	s_mov_b32 m0, s24
	s_nop 0
	global_load_lds_dwordx4 v[206:207], off
	s_add_i32 m0, s24, 0x2000
	s_add_u32 s22, s22, 0x40080
	v_lshl_add_u64 v[206:207], v[210:211], 0, s[10:11]
	s_addc_u32 s23, s23, 0
	s_add_i32 s24, s29, s26
	global_load_lds_dwordx4 v[206:207], off
	s_mov_b32 m0, s24
	s_nop 0
	global_load_lds_dwordx4 v208, s[22:23]
	s_add_i32 m0, s24, 0x2000
	s_nop 0
	global_load_lds_dwordx4 v128, s[22:23]
	v_lshl_add_u64 v[206:207], v[212:213], 0, s[10:11]
	s_mov_b32 m0, s35
	s_nop 0
	global_load_lds_dwordx4 v[206:207], off
	v_lshl_add_u64 v[206:207], v[222:223], 0, s[10:11]
	s_mov_b32 m0, s39
	s_nop 0
	global_load_lds_dwordx4 v[206:207], off
	ds_read_b128 v[174:177], v145 offset:49152
	ds_read_b128 v[178:181], v145 offset:50176
	ds_read_b128 v[182:185], v145 offset:51200
	ds_read_b128 v[186:189], v145 offset:52224
	ds_read_b128 v[190:193], v145 offset:53248
	ds_read_b128 v[194:197], v145 offset:54272
	ds_read_b128 v[198:201], v145 offset:55296
	ds_read_b128 v[202:205], v145 offset:56320
	s_waitcnt vmcnt(8)
	s_waitcnt lgkmcnt(0)
	s_barrier
	s_waitcnt lgkmcnt(0)
	v_mfma_f32_16x16x32_bf16 v[60:63], v[138:141], v[174:177], v[60:63]
	v_mfma_f32_16x16x32_bf16 v[56:59], v[150:153], v[174:177], v[56:59]
	v_mfma_f32_16x16x32_bf16 v[44:47], v[138:141], v[182:185], v[44:47]
	v_mfma_f32_16x16x32_bf16 v[40:43], v[150:153], v[182:185], v[40:43]
	v_mfma_f32_16x16x32_bf16 v[28:31], v[138:141], v[190:193], v[28:31]
	v_mfma_f32_16x16x32_bf16 v[24:27], v[150:153], v[190:193], v[24:27]
	v_mfma_f32_16x16x32_bf16 v[12:15], v[138:141], v[198:201], v[12:15]
	v_mfma_f32_16x16x32_bf16 v[8:11], v[150:153], v[198:201], v[8:11]
	v_mfma_f32_16x16x32_bf16 v[60:63], v[146:149], v[178:181], v[60:63]
	v_mfma_f32_16x16x32_bf16 v[56:59], v[154:157], v[178:181], v[56:59]
	v_mfma_f32_16x16x32_bf16 v[44:47], v[146:149], v[186:189], v[44:47]
	v_mfma_f32_16x16x32_bf16 v[40:43], v[154:157], v[186:189], v[40:43]
	v_mfma_f32_16x16x32_bf16 v[28:31], v[146:149], v[194:197], v[28:31]
	v_mfma_f32_16x16x32_bf16 v[24:27], v[154:157], v[194:197], v[24:27]
	v_mfma_f32_16x16x32_bf16 v[12:15], v[146:149], v[202:205], v[12:15]
	v_mfma_f32_16x16x32_bf16 v[8:11], v[154:157], v[202:205], v[8:11]
	v_mfma_f32_16x16x32_bf16 v[52:55], v[158:161], v[174:177], v[52:55]
	v_mfma_f32_16x16x32_bf16 v[48:51], v[166:169], v[174:177], v[48:51]
	v_mfma_f32_16x16x32_bf16 v[36:39], v[158:161], v[182:185], v[36:39]
	v_mfma_f32_16x16x32_bf16 v[32:35], v[166:169], v[182:185], v[32:35]
	v_mfma_f32_16x16x32_bf16 v[20:23], v[158:161], v[190:193], v[20:23]
	v_mfma_f32_16x16x32_bf16 v[16:19], v[166:169], v[190:193], v[16:19]
	v_mfma_f32_16x16x32_bf16 v[4:7], v[158:161], v[198:201], v[4:7]
	v_mfma_f32_16x16x32_bf16 v[0:3], v[166:169], v[198:201], v[0:3]
	v_mfma_f32_16x16x32_bf16 v[52:55], v[162:165], v[178:181], v[52:55]
	v_mfma_f32_16x16x32_bf16 v[48:51], v[170:173], v[178:181], v[48:51]
	v_mfma_f32_16x16x32_bf16 v[36:39], v[162:165], v[186:189], v[36:39]
	v_mfma_f32_16x16x32_bf16 v[32:35], v[170:173], v[186:189], v[32:35]
	v_mfma_f32_16x16x32_bf16 v[20:23], v[162:165], v[194:197], v[20:23]
	v_mfma_f32_16x16x32_bf16 v[16:19], v[170:173], v[194:197], v[16:19]
	v_mfma_f32_16x16x32_bf16 v[4:7], v[162:165], v[202:205], v[4:7]
	v_mfma_f32_16x16x32_bf16 v[0:3], v[170:173], v[202:205], v[0:3]
	s_barrier
	s_add_i32 s51, s51, 2
	s_add_u32 s0, s0, 0x100
	s_addc_u32 s1, s1, 0
	s_add_u32 s43, s43, 0x100
	s_addc_u32 s50, s50, 0
	s_cmp_gt_u32 s51, 13
	s_cbranch_scc0 .LBB0_607
	s_and_b64 vcc, exec, s[6:7]
	s_cbranch_vccz .LBB0_610
	s_barrier

; #define PG8_STAGE(bufoff, gbase, voff) do { _Pragma("unroll") for (int _i = 0; _i < 2; ++_i) \
;         __builtin_amdgcn_global_load_lds((const unsigned*)((const char*)(gbase) + (voff)[_i]), (PG8_LAS unsigned*)(lds + (bufoff) + ldsw + _i * 8192), 16, 0, 0); } while (0)
; #define PG8_LDA(dst, b, h) do { _Pragma("unroll") for (int m = 0; m < 4; ++m) _Pragma("unroll") for (int k = 0; k < 2; ++k) dst[m][k] = *(const PG8_LAS bf16x8*)(lds + PG8_SA(b, h) + aoff + m * 2048 + k * 1024); } while (0)
; #define PG8_LDB(dst, b, h) do { _Pragma("unroll") for (int n = 0; n < 2; ++n) _Pragma("unroll") for (int k = 0; k < 2; ++k) dst[n][k] = *(const PG8_LAS bf16x8*)(lds + PG8_SB(b, h) + boff + n * 2048 + k * 1024); } while (0)
; #define PG8_MMA(ai, bj, At, Bt) do { __builtin_amdgcn_s_setprio(1); _Pragma("unroll") for (int m = 0; m < 4; ++m) _Pragma("unroll") for (int n = 0; n < 2; ++n) _Pragma("unroll") for (int k = 0; k < 2; ++k) \
;         acc[ai][bj][m][n] = __builtin_amdgcn_mfma_f32_16x16x32_bf16(Bt[n][k], At[m][k], acc[ai][bj][m][n], 0, 0, 0); __builtin_amdgcn_s_setprio(0); } while (0)
; #define PG8_WAIT_V(n) asm volatile("s_waitcnt vmcnt(" #n ")" ::: "memory")
; #define PG8_WAIT_L(n) asm volatile("s_waitcnt lgkmcnt(" #n ")" ::: "memory")
; template <class Epi, class Sched, bool ALIGN_EPI = false, bool SP2 = false>
; __device__ __forceinline__ void gemm_phase(PG8_LAS unsigned char* lds, const Gemm g, const Sched& S, const Epi& E) {
;     ...
;             const bool last = (t == nt - 2);
;             const char* a1 = cA + (size_t)(t + 1) * kstep;
;             const char* a2 = last ? nA : cA + (size_t)(t + 2) * kstep; const char* b2 = last ? nB : cB + (size_t)(t + 2) * kstep;
;             const char* a3 = a2 + kstep; const char* b3 = b2 + kstep;
;             if (last && has_next) S.a_ready(nxt);
;             if constexpr (SP2) {
;             PG8_LDB(B0, 0, 0); PG8_LDB(B1, 0, 1); PG8_SCHED; PG8_LDA(At, 0, 0); PG8_STAGE(PG8_SA(1, 1), a1 + hstepA, voffA);
;             PG8_WAIT_V(8); PG8_WAIT_L(0); PG8_BAR; PG8_MMA(0, 0, At, B0); PG8_MMA(0, 1, At, B1); PG8_BAR; PG8_SCHED;
;             PG8_LDA(At, 0, 1); PG8_STAGE(PG8_SB(0, 0), b2, voffB); PG8_STAGE(PG8_SB(0, 1), b2 + hstepB, voffB); PG8_STAGE(PG8_SA(0, 0), a2, voffA);
;             PG8_WAIT_V(8); PG8_WAIT_L(0); PG8_BAR; PG8_MMA(1, 0, At, B0); PG8_MMA(1, 1, At, B1); PG8_BAR; PG8_SCHED;
.LBB0_690:
	s_add_u32 s4, s0, 0x100
	s_addc_u32 s5, s1, 0
	s_add_i32 s28, 0, 0x10000
	s_cmp_eq_u32 s34, 4
	s_cselect_b32 s23, s49, s5
	s_cselect_b32 s22, s48, s4
	s_cselect_b32 s21, s14, s19
	s_cselect_b32 s20, s15, s18
	s_add_i32 s29, 0, 0x14000
	v_lshl_add_u64 v[202:203], s[0:1], 0, v[198:199]
	s_add_i32 m0, s53, 0xc000
	s_nop 0
	global_load_lds_dwordx4 v[202:203], off
	v_lshl_add_u64 v[202:203], s[0:1], 0, v[200:201]
	s_add_i32 m0, s53, 0xe000
	s_nop 0
	global_load_lds_dwordx4 v[202:203], off
	v_add_u32_e32 v140, s28, v211
	v_add_u32_e32 v156, s29, v211
	ds_read_b128 v[128:131], v140
	ds_read_b128 v[132:135], v140 offset:1024
	ds_read_b128 v[136:139], v140 offset:2048
	ds_read_b128 v[140:143], v140 offset:3072
	ds_read_b128 v[144:147], v156
	ds_read_b128 v[148:151], v156 offset:1024
	ds_read_b128 v[152:155], v156 offset:2048
	ds_read_b128 v[156:159], v156 offset:3072
	ds_read_b128 v[160:163], v231
	ds_read_b128 v[164:167], v231 offset:1024
	ds_read_b128 v[168:171], v231 offset:2048
	ds_read_b128 v[172:175], v231 offset:3072
	ds_read_b128 v[176:179], v231 offset:4096
	ds_read_b128 v[180:183], v231 offset:5120
	ds_read_b128 v[184:187], v231 offset:6144
	ds_read_b128 v[188:191], v231 offset:7168
	s_waitcnt vmcnt(8)
	s_waitcnt lgkmcnt(0)
	s_barrier
	s_waitcnt lgkmcnt(0)
	v_mfma_f32_16x16x32_bf16 v[124:127], v[128:131], v[160:163], v[124:127]
	v_mfma_f32_16x16x32_bf16 v[120:123], v[136:139], v[160:163], v[120:123]
	v_mfma_f32_16x16x32_bf16 v[112:115], v[128:131], v[168:171], v[112:115]
	v_mfma_f32_16x16x32_bf16 v[104:107], v[136:139], v[168:171], v[104:107]
	v_mfma_f32_16x16x32_bf16 v[96:99], v[128:131], v[176:179], v[96:99]
	v_mfma_f32_16x16x32_bf16 v[88:91], v[136:139], v[176:179], v[88:91]
	v_mfma_f32_16x16x32_bf16 v[80:83], v[128:131], v[184:187], v[80:83]
	v_mfma_f32_16x16x32_bf16 v[72:75], v[136:139], v[184:187], v[72:75]
	v_mfma_f32_16x16x32_bf16 v[124:127], v[132:135], v[164:167], v[124:127]
	v_mfma_f32_16x16x32_bf16 v[120:123], v[140:143], v[164:167], v[120:123]
	v_mfma_f32_16x16x32_bf16 v[112:115], v[132:135], v[172:175], v[112:115]
	v_mfma_f32_16x16x32_bf16 v[104:107], v[140:143], v[172:175], v[104:107]
	v_mfma_f32_16x16x32_bf16 v[96:99], v[132:135], v[180:183], v[96:99]
	v_mfma_f32_16x16x32_bf16 v[88:91], v[140:143], v[180:183], v[88:91]
	v_mfma_f32_16x16x32_bf16 v[80:83], v[132:135], v[188:191], v[80:83]
	v_mfma_f32_16x16x32_bf16 v[72:75], v[140:143], v[188:191], v[72:75]
	v_mfma_f32_16x16x32_bf16 v[116:119], v[144:147], v[160:163], v[116:119]
	v_mfma_f32_16x16x32_bf16 v[108:111], v[152:155], v[160:163], v[108:111]
	v_mfma_f32_16x16x32_bf16 v[100:103], v[144:147], v[168:171], v[100:103]
	v_mfma_f32_16x16x32_bf16 v[92:95], v[152:155], v[168:171], v[92:95]
	v_mfma_f32_16x16x32_bf16 v[84:87], v[144:147], v[176:179], v[84:87]
	v_mfma_f32_16x16x32_bf16 v[76:79], v[152:155], v[176:179], v[76:79]
	v_mfma_f32_16x16x32_bf16 v[68:71], v[144:147], v[184:187], v[68:71]
	v_mfma_f32_16x16x32_bf16 v[64:67], v[152:155], v[184:187], v[64:67]
	v_mfma_f32_16x16x32_bf16 v[116:119], v[148:151], v[164:167], v[116:119]
	v_mfma_f32_16x16x32_bf16 v[108:111], v[156:159], v[164:167], v[108:111]
	v_mfma_f32_16x16x32_bf16 v[100:103], v[148:151], v[172:175], v[100:103]
	v_mfma_f32_16x16x32_bf16 v[92:95], v[156:159], v[172:175], v[92:95]
	v_mfma_f32_16x16x32_bf16 v[84:87], v[148:151], v[180:183], v[84:87]
	v_mfma_f32_16x16x32_bf16 v[76:79], v[156:159], v[180:183], v[76:79]
	v_mfma_f32_16x16x32_bf16 v[68:71], v[148:151], v[188:191], v[68:71]
	v_mfma_f32_16x16x32_bf16 v[64:67], v[156:159], v[188:191], v[64:67]
	s_barrier
	s_add_i32 s0, s28, s56
	v_lshl_add_u64 v[202:203], s[20:21], 0, v[208:209]
	s_mov_b32 m0, s0
	s_nop 0
	global_load_lds_dwordx4 v208, s[20:21]
	s_add_i32 m0, s0, 0x2000
	s_add_u32 s0, s20, 0x20000
	v_lshl_add_u64 v[204:205], s[20:21], 0, v[196:197]
	s_addc_u32 s1, s21, 0
	s_add_i32 s28, s29, s56
	global_load_lds_dwordx4 v196, s[20:21]
	s_mov_b32 m0, s28
	v_lshl_add_u64 v[212:213], s[22:23], 0, v[194:195]
	global_load_lds_dwordx4 v208, s[0:1]
	s_add_i32 m0, s28, 0x2000
	s_nop 0
	global_load_lds_dwordx4 v196, s[0:1]
	v_lshl_add_u64 v[206:207], s[22:23], 0, v[192:193]
	s_mov_b32 m0, s53
	s_nop 0
	global_load_lds_dwordx4 v192, s[22:23]
	s_mov_b32 m0, s57
	s_nop 0
	global_load_lds_dwordx4 v194, s[22:23]
	ds_read_b128 v[160:163], v231 offset:16384
	ds_read_b128 v[164:167], v231 offset:17408
	ds_read_b128 v[168:171], v231 offset:18432
	ds_read_b128 v[172:175], v231 offset:19456
	ds_read_b128 v[176:179], v231 offset:20480
	ds_read_b128 v[180:183], v231 offset:21504
	ds_read_b128 v[184:187], v231 offset:22528
	ds_read_b128 v[188:191], v231 offset:23552
	s_waitcnt vmcnt(8)
	s_waitcnt lgkmcnt(0)
	s_barrier
; #define PG8_STAGE(bufoff, gbase, voff) do { _Pragma("unroll") for (int _i = 0; _i < 2; ++_i) \
;         __builtin_amdgcn_global_load_lds((const unsigned*)((const char*)(gbase) + (voff)[_i]), (PG8_LAS unsigned*)(lds + (bufoff) + ldsw + _i * 8192), 16, 0, 0); } while (0)
; #define PG8_LDA(dst, b, h) do { _Pragma("unroll") for (int m = 0; m < 4; ++m) _Pragma("unroll") for (int k = 0; k < 2; ++k) dst[m][k] = *(const PG8_LAS bf16x8*)(lds + PG8_SA(b, h) + aoff + m * 2048 + k * 1024); } while (0)
; #define PG8_LDB(dst, b, h) do { _Pragma("unroll") for (int n = 0; n < 2; ++n) _Pragma("unroll") for (int k = 0; k < 2; ++k) dst[n][k] = *(const PG8_LAS bf16x8*)(lds + PG8_SB(b, h) + boff + n * 2048 + k * 1024); } while (0)
; #define PG8_MMA(ai, bj, At, Bt) do { __builtin_amdgcn_s_setprio(1); _Pragma("unroll") for (int m = 0; m < 4; ++m) _Pragma("unroll") for (int n = 0; n < 2; ++n) _Pragma("unroll") for (int k = 0; k < 2; ++k) \
;         acc[ai][bj][m][n] = __builtin_amdgcn_mfma_f32_16x16x32_bf16(Bt[n][k], At[m][k], acc[ai][bj][m][n], 0, 0, 0); __builtin_amdgcn_s_setprio(0); } while (0)
; #define PG8_WAIT_V(n) asm volatile("s_waitcnt vmcnt(" #n ")" ::: "memory")
; #define PG8_WAIT_L(n) asm volatile("s_waitcnt lgkmcnt(" #n ")" ::: "memory")
; #define PG8_BAR __builtin_amdgcn_s_barrier()
; #define PG8_SCHED __builtin_amdgcn_sched_barrier(0)
; template <class Epi, class Sched, bool ALIGN_EPI = false, bool SP2 = false>
; __device__ __forceinline__ void gemm_phase(PG8_LAS unsigned char* lds, const Gemm g, const Sched& S, const Epi& E) {
;     ...
;             PG8_WAIT_V(8); PG8_WAIT_L(0); PG8_BAR; PG8_MMA(0, 0, At, B0); PG8_MMA(0, 1, At, B1); PG8_BAR; PG8_SCHED;
;             PG8_LDA(At, 0, 1); PG8_STAGE(PG8_SB(0, 0), b2, voffB); PG8_STAGE(PG8_SB(0, 1), b2 + hstepB, voffB); PG8_STAGE(PG8_SA(0, 0), a2, voffA);
;             PG8_WAIT_V(8); PG8_WAIT_L(0); PG8_BAR; PG8_MMA(1, 0, At, B0); PG8_MMA(1, 1, At, B1); PG8_BAR; PG8_SCHED;
;             PG8_LDB(B0, 1, 0); PG8_LDB(B1, 1, 1); PG8_SCHED; PG8_LDA(At, 1, 0); PG8_STAGE(PG8_SA(0, 1), a2 + hstepA, voffA);
;             PG8_WAIT_V(8); PG8_WAIT_L(0); PG8_BAR; PG8_MMA(0, 0, At, B0); PG8_MMA(0, 1, At, B1); PG8_BAR; PG8_SCHED;
	s_waitcnt lgkmcnt(0)
	v_mfma_f32_16x16x32_bf16 v[60:63], v[128:131], v[160:163], v[60:63]
	v_mfma_f32_16x16x32_bf16 v[56:59], v[136:139], v[160:163], v[56:59]
	v_mfma_f32_16x16x32_bf16 v[48:51], v[128:131], v[168:171], v[48:51]
	v_mfma_f32_16x16x32_bf16 v[40:43], v[136:139], v[168:171], v[40:43]
	v_mfma_f32_16x16x32_bf16 v[32:35], v[128:131], v[176:179], v[32:35]
	v_mfma_f32_16x16x32_bf16 v[24:27], v[136:139], v[176:179], v[24:27]
	v_mfma_f32_16x16x32_bf16 v[16:19], v[128:131], v[184:187], v[16:19]
	v_mfma_f32_16x16x32_bf16 v[8:11], v[136:139], v[184:187], v[8:11]
	v_mfma_f32_16x16x32_bf16 v[60:63], v[132:135], v[164:167], v[60:63]
	v_mfma_f32_16x16x32_bf16 v[56:59], v[140:143], v[164:167], v[56:59]
	v_mfma_f32_16x16x32_bf16 v[48:51], v[132:135], v[172:175], v[48:51]
	v_mfma_f32_16x16x32_bf16 v[40:43], v[140:143], v[172:175], v[40:43]
	v_mfma_f32_16x16x32_bf16 v[32:35], v[132:135], v[180:183], v[32:35]
	v_mfma_f32_16x16x32_bf16 v[24:27], v[140:143], v[180:183], v[24:27]
	v_mfma_f32_16x16x32_bf16 v[16:19], v[132:135], v[188:191], v[16:19]
	v_mfma_f32_16x16x32_bf16 v[8:11], v[140:143], v[188:191], v[8:11]
	v_mfma_f32_16x16x32_bf16 v[52:55], v[144:147], v[160:163], v[52:55]
	v_mfma_f32_16x16x32_bf16 v[44:47], v[152:155], v[160:163], v[44:47]
	v_mfma_f32_16x16x32_bf16 v[36:39], v[144:147], v[168:171], v[36:39]
	v_mfma_f32_16x16x32_bf16 v[28:31], v[152:155], v[168:171], v[28:31]
	v_mfma_f32_16x16x32_bf16 v[20:23], v[144:147], v[176:179], v[20:23]
	v_mfma_f32_16x16x32_bf16 v[12:15], v[152:155], v[176:179], v[12:15]
	v_mfma_f32_16x16x32_bf16 v[4:7], v[144:147], v[184:187], v[4:7]
	v_mfma_f32_16x16x32_bf16 v[0:3], v[152:155], v[184:187], v[0:3]
	v_mfma_f32_16x16x32_bf16 v[52:55], v[148:151], v[164:167], v[52:55]
	v_mfma_f32_16x16x32_bf16 v[44:47], v[156:159], v[164:167], v[44:47]
	v_mfma_f32_16x16x32_bf16 v[36:39], v[148:151], v[172:175], v[36:39]
	v_mfma_f32_16x16x32_bf16 v[28:31], v[156:159], v[172:175], v[28:31]
	v_mfma_f32_16x16x32_bf16 v[20:23], v[148:151], v[180:183], v[20:23]
	v_mfma_f32_16x16x32_bf16 v[12:15], v[156:159], v[180:183], v[12:15]
	v_mfma_f32_16x16x32_bf16 v[4:7], v[148:151], v[188:191], v[4:7]
	v_mfma_f32_16x16x32_bf16 v[0:3], v[156:159], v[188:191], v[0:3]
	s_barrier
	s_add_i32 s28, 0, 0x18000
	s_add_i32 s29, 0, 0x1c000
	s_add_u32 s0, s22, 0x60000
	s_addc_u32 s1, s23, 0
	s_mov_b32 m0, s58
	s_nop 0
	global_load_lds_dwordx4 v192, s[0:1]
	s_mov_b32 m0, s59
	s_nop 0
	global_load_lds_dwordx4 v194, s[0:1]
	v_add_u32_e32 v140, s28, v211
	v_add_u32_e32 v156, s29, v211
	ds_read_b128 v[128:131], v140
	ds_read_b128 v[132:135], v140 offset:1024
	ds_read_b128 v[136:139], v140 offset:2048
	ds_read_b128 v[140:143], v140 offset:3072
	ds_read_b128 v[144:147], v156
	ds_read_b128 v[148:151], v156 offset:1024
	ds_read_b128 v[152:155], v156 offset:2048
	ds_read_b128 v[156:159], v156 offset:3072
	ds_read_b128 v[160:163], v231 offset:32768
	ds_read_b128 v[164:167], v231 offset:33792
	ds_read_b128 v[168:171], v231 offset:34816
	ds_read_b128 v[172:175], v231 offset:35840
	ds_read_b128 v[176:179], v231 offset:36864
	ds_read_b128 v[180:183], v231 offset:37888
	ds_read_b128 v[184:187], v231 offset:38912
	ds_read_b128 v[188:191], v231 offset:39936
	s_waitcnt vmcnt(8)
	s_waitcnt lgkmcnt(0)
	s_barrier
	s_waitcnt lgkmcnt(0)
	v_mfma_f32_16x16x32_bf16 v[124:127], v[128:131], v[160:163], v[124:127]
	v_mfma_f32_16x16x32_bf16 v[120:123], v[136:139], v[160:163], v[120:123]
	v_mfma_f32_16x16x32_bf16 v[112:115], v[128:131], v[168:171], v[112:115]
	v_mfma_f32_16x16x32_bf16 v[104:107], v[136:139], v[168:171], v[104:107]
	v_mfma_f32_16x16x32_bf16 v[96:99], v[128:131], v[176:179], v[96:99]
	v_mfma_f32_16x16x32_bf16 v[88:91], v[136:139], v[176:179], v[88:91]
	v_mfma_f32_16x16x32_bf16 v[80:83], v[128:131], v[184:187], v[80:83]
	v_mfma_f32_16x16x32_bf16 v[72:75], v[136:139], v[184:187], v[72:75]
	v_mfma_f32_16x16x32_bf16 v[124:127], v[132:135], v[164:167], v[124:127]
	v_mfma_f32_16x16x32_bf16 v[120:123], v[140:143], v[164:167], v[120:123]
	v_mfma_f32_16x16x32_bf16 v[112:115], v[132:135], v[172:175], v[112:115]
	v_mfma_f32_16x16x32_bf16 v[104:107], v[140:143], v[172:175], v[104:107]
	v_mfma_f32_16x16x32_bf16 v[96:99], v[132:135], v[180:183], v[96:99]
	v_mfma_f32_16x16x32_bf16 v[88:91], v[140:143], v[180:183], v[88:91]
	v_mfma_f32_16x16x32_bf16 v[80:83], v[132:135], v[188:191], v[80:83]
	v_mfma_f32_16x16x32_bf16 v[72:75], v[140:143], v[188:191], v[72:75]
	v_mfma_f32_16x16x32_bf16 v[116:119], v[144:147], v[160:163], v[116:119]
	v_mfma_f32_16x16x32_bf16 v[108:111], v[152:155], v[160:163], v[108:111]
	v_mfma_f32_16x16x32_bf16 v[100:103], v[144:147], v[168:171], v[100:103]
	v_mfma_f32_16x16x32_bf16 v[92:95], v[152:155], v[168:171], v[92:95]
	v_mfma_f32_16x16x32_bf16 v[84:87], v[144:147], v[176:179], v[84:87]
	v_mfma_f32_16x16x32_bf16 v[76:79], v[152:155], v[176:179], v[76:79]
	v_mfma_f32_16x16x32_bf16 v[68:71], v[144:147], v[184:187], v[68:71]
	v_mfma_f32_16x16x32_bf16 v[64:67], v[152:155], v[184:187], v[64:67]
	v_mfma_f32_16x16x32_bf16 v[116:119], v[148:151], v[164:167], v[116:119]
	v_mfma_f32_16x16x32_bf16 v[108:111], v[156:159], v[164:167], v[108:111]
	v_mfma_f32_16x16x32_bf16 v[100:103], v[148:151], v[172:175], v[100:103]
	v_mfma_f32_16x16x32_bf16 v[92:95], v[156:159], v[172:175], v[92:95]
	v_mfma_f32_16x16x32_bf16 v[84:87], v[148:151], v[180:183], v[84:87]
	v_mfma_f32_16x16x32_bf16 v[76:79], v[156:159], v[180:183], v[76:79]
	v_mfma_f32_16x16x32_bf16 v[68:71], v[148:151], v[188:191], v[68:71]
	v_mfma_f32_16x16x32_bf16 v[64:67], v[156:159], v[188:191], v[64:67]
	s_barrier
; #define PG8_STAGE(bufoff, gbase, voff) do { _Pragma("unroll") for (int _i = 0; _i < 2; ++_i) \
;         __builtin_amdgcn_global_load_lds((const unsigned*)((const char*)(gbase) + (voff)[_i]), (PG8_LAS unsigned*)(lds + (bufoff) + ldsw + _i * 8192), 16, 0, 0); } while (0)
; #define PG8_LDA(dst, b, h) do { _Pragma("unroll") for (int m = 0; m < 4; ++m) _Pragma("unroll") for (int k = 0; k < 2; ++k) dst[m][k] = *(const PG8_LAS bf16x8*)(lds + PG8_SA(b, h) + aoff + m * 2048 + k * 1024); } while (0)
; #define PG8_MMA(ai, bj, At, Bt) do { __builtin_amdgcn_s_setprio(1); _Pragma("unroll") for (int m = 0; m < 4; ++m) _Pragma("unroll") for (int n = 0; n < 2; ++n) _Pragma("unroll") for (int k = 0; k < 2; ++k) \
;         acc[ai][bj][m][n] = __builtin_amdgcn_mfma_f32_16x16x32_bf16(Bt[n][k], At[m][k], acc[ai][bj][m][n], 0, 0, 0); __builtin_amdgcn_s_setprio(0); } while (0)
; #define PG8_WAIT_V(n) asm volatile("s_waitcnt vmcnt(" #n ")" ::: "memory")
; #define PG8_WAIT_L(n) asm volatile("s_waitcnt lgkmcnt(" #n ")" ::: "memory")
; #define PG8_BAR __builtin_amdgcn_s_barrier()
; #define PG8_SCHED __builtin_amdgcn_sched_barrier(0)
; template <class Epi, class Sched, bool ALIGN_EPI = false, bool SP2 = false>
; __device__ __forceinline__ void gemm_phase(PG8_LAS unsigned char* lds, const Gemm g, const Sched& S, const Epi& E) {
;     ...
;             PG8_WAIT_V(8); PG8_WAIT_L(0); PG8_BAR; PG8_MMA(0, 0, At, B0); PG8_MMA(0, 1, At, B1); PG8_BAR; PG8_SCHED;
;             PG8_LDA(At, 1, 1); PG8_STAGE(PG8_SB(1, 0), b3, voffB); PG8_STAGE(PG8_SB(1, 1), b3 + hstepB, voffB); PG8_STAGE(PG8_SA(1, 0), a3, voffA);
;             PG8_WAIT_V(8); PG8_WAIT_L(0); PG8_BAR; PG8_MMA(1, 0, At, B0); PG8_MMA(1, 1, At, B1); PG8_BAR; PG8_SCHED;
;     ...
;         if constexpr (ALIGN_EPI) { if (wr == 0) PG8_BAR; }
	s_add_i32 s0, s28, s56
	v_lshl_add_u64 v[202:203], v[202:203], 0, s[10:11]
	s_mov_b32 m0, s0
	s_nop 0
	global_load_lds_dwordx4 v[202:203], off
	s_add_i32 m0, s0, 0x2000
	s_add_u32 s0, s20, 0x20080
	v_lshl_add_u64 v[202:203], v[204:205], 0, s[10:11]
	s_addc_u32 s1, s21, 0
	s_add_i32 s20, s29, s56
	global_load_lds_dwordx4 v[202:203], off
	s_mov_b32 m0, s20
	s_nop 0
	global_load_lds_dwordx4 v208, s[0:1]
	s_add_i32 m0, s20, 0x2000
	s_nop 0
	global_load_lds_dwordx4 v196, s[0:1]
	v_lshl_add_u64 v[202:203], v[206:207], 0, s[10:11]
	s_mov_b32 m0, s61
	s_nop 0
	global_load_lds_dwordx4 v[202:203], off
	v_lshl_add_u64 v[202:203], v[212:213], 0, s[10:11]
	s_mov_b32 m0, s62
	s_nop 0
	global_load_lds_dwordx4 v[202:203], off
	ds_read_b128 v[160:163], v231 offset:49152
	ds_read_b128 v[164:167], v231 offset:50176
	ds_read_b128 v[168:171], v231 offset:51200
	ds_read_b128 v[172:175], v231 offset:52224
	ds_read_b128 v[176:179], v231 offset:53248
	ds_read_b128 v[180:183], v231 offset:54272
	ds_read_b128 v[184:187], v231 offset:55296
	ds_read_b128 v[188:191], v231 offset:56320
	s_waitcnt vmcnt(8)
	s_waitcnt lgkmcnt(0)
	s_barrier
	s_waitcnt lgkmcnt(0)
	v_mfma_f32_16x16x32_bf16 v[60:63], v[128:131], v[160:163], v[60:63]
	v_mfma_f32_16x16x32_bf16 v[56:59], v[136:139], v[160:163], v[56:59]
	v_mfma_f32_16x16x32_bf16 v[48:51], v[128:131], v[168:171], v[48:51]
	v_mfma_f32_16x16x32_bf16 v[40:43], v[136:139], v[168:171], v[40:43]
	v_mfma_f32_16x16x32_bf16 v[32:35], v[128:131], v[176:179], v[32:35]
	v_mfma_f32_16x16x32_bf16 v[24:27], v[136:139], v[176:179], v[24:27]
	v_mfma_f32_16x16x32_bf16 v[16:19], v[128:131], v[184:187], v[16:19]
	v_mfma_f32_16x16x32_bf16 v[8:11], v[136:139], v[184:187], v[8:11]
	v_mfma_f32_16x16x32_bf16 v[60:63], v[132:135], v[164:167], v[60:63]
	v_mfma_f32_16x16x32_bf16 v[56:59], v[140:143], v[164:167], v[56:59]
	v_mfma_f32_16x16x32_bf16 v[48:51], v[132:135], v[172:175], v[48:51]
	v_mfma_f32_16x16x32_bf16 v[40:43], v[140:143], v[172:175], v[40:43]
	v_mfma_f32_16x16x32_bf16 v[32:35], v[132:135], v[180:183], v[32:35]
	v_mfma_f32_16x16x32_bf16 v[24:27], v[140:143], v[180:183], v[24:27]
	v_mfma_f32_16x16x32_bf16 v[16:19], v[132:135], v[188:191], v[16:19]
	v_mfma_f32_16x16x32_bf16 v[8:11], v[140:143], v[188:191], v[8:11]
	v_mfma_f32_16x16x32_bf16 v[52:55], v[144:147], v[160:163], v[52:55]
	v_mfma_f32_16x16x32_bf16 v[44:47], v[152:155], v[160:163], v[44:47]
	v_mfma_f32_16x16x32_bf16 v[36:39], v[144:147], v[168:171], v[36:39]
	v_mfma_f32_16x16x32_bf16 v[28:31], v[152:155], v[168:171], v[28:31]
	v_mfma_f32_16x16x32_bf16 v[20:23], v[144:147], v[176:179], v[20:23]
	v_mfma_f32_16x16x32_bf16 v[12:15], v[152:155], v[176:179], v[12:15]
	v_mfma_f32_16x16x32_bf16 v[4:7], v[144:147], v[184:187], v[4:7]
	v_mfma_f32_16x16x32_bf16 v[0:3], v[152:155], v[184:187], v[0:3]
	v_mfma_f32_16x16x32_bf16 v[52:55], v[148:151], v[164:167], v[52:55]
	v_mfma_f32_16x16x32_bf16 v[44:47], v[156:159], v[164:167], v[44:47]
	v_mfma_f32_16x16x32_bf16 v[36:39], v[148:151], v[172:175], v[36:39]
	v_mfma_f32_16x16x32_bf16 v[28:31], v[156:159], v[172:175], v[28:31]
	v_mfma_f32_16x16x32_bf16 v[20:23], v[148:151], v[180:183], v[20:23]
	v_mfma_f32_16x16x32_bf16 v[12:15], v[156:159], v[180:183], v[12:15]
	v_mfma_f32_16x16x32_bf16 v[4:7], v[148:151], v[188:191], v[4:7]
	v_mfma_f32_16x16x32_bf16 v[0:3], v[156:159], v[188:191], v[0:3]
	s_barrier
	s_add_i32 s34, s34, 2
	s_add_u32 s18, s18, 0x100
	s_addc_u32 s19, s19, 0
	s_cmp_gt_u32 s34, 5
	s_mov_b64 s[0:1], s[4:5]
	s_cbranch_scc0 .LBB0_690
	s_and_b64 vcc, exec, s[44:45]
	s_cbranch_vccz .LBB0_693
	s_barrier

; #define PG8_STAGE(bufoff, gbase, voff) do { _Pragma("unroll") for (int _i = 0; _i < 2; ++_i) \
;         __builtin_amdgcn_global_load_lds((const unsigned*)((const char*)(gbase) + (voff)[_i]), (PG8_LAS unsigned*)(lds + (bufoff) + ldsw + _i * 8192), 16, 0, 0); } while (0)
; #define PG8_LDA(dst, b, h) do { _Pragma("unroll") for (int m = 0; m < 4; ++m) _Pragma("unroll") for (int k = 0; k < 2; ++k) dst[m][k] = *(const PG8_LAS bf16x8*)(lds + PG8_SA(b, h) + aoff + m * 2048 + k * 1024); } while (0)
; #define PG8_LDB(dst, b, h) do { _Pragma("unroll") for (int n = 0; n < 2; ++n) _Pragma("unroll") for (int k = 0; k < 2; ++k) dst[n][k] = *(const PG8_LAS bf16x8*)(lds + PG8_SB(b, h) + boff + n * 2048 + k * 1024); } while (0)
; #define PG8_MMA(ai, bj, At, Bt) do { __builtin_amdgcn_s_setprio(1); _Pragma("unroll") for (int m = 0; m < 4; ++m) _Pragma("unroll") for (int n = 0; n < 2; ++n) _Pragma("unroll") for (int k = 0; k < 2; ++k) \
;         acc[ai][bj][m][n] = __builtin_amdgcn_mfma_f32_16x16x32_bf16(Bt[n][k], At[m][k], acc[ai][bj][m][n], 0, 0, 0); __builtin_amdgcn_s_setprio(0); } while (0)
; #define PG8_WAIT_V(n) asm volatile("s_waitcnt vmcnt(" #n ")" ::: "memory")
; #define PG8_WAIT_L(n) asm volatile("s_waitcnt lgkmcnt(" #n ")" ::: "memory")
; #define PG8_BAR __builtin_amdgcn_s_barrier()
; #define PG8_SCHED __builtin_amdgcn_sched_barrier(0)
; template <class Epi, class Sched, bool ALIGN_EPI = false, bool SP2 = false>
; __device__ __forceinline__ void gemm_phase(PG8_LAS unsigned char* lds, const Gemm g, const Sched& S, const Epi& E) {
;     ...
;             PG8_LDB(B0, 0, 0); PG8_LDB(B1, 0, 1); PG8_SCHED; PG8_LDA(At, 0, 0); PG8_STAGE(PG8_SA(1, 1), a1 + hstepA, voffA);
;             PG8_WAIT_V(8); PG8_WAIT_L(0); PG8_BAR; PG8_MMA(0, 0, At, B0); PG8_MMA(0, 1, At, B1); PG8_BAR; PG8_SCHED;
;             PG8_LDA(At, 0, 1); PG8_STAGE(PG8_SB(0, 0), b2, voffB); PG8_STAGE(PG8_SB(0, 1), b2 + hstepB, voffB); PG8_STAGE(PG8_SA(0, 0), a2, voffA);
.LBB0_797:
	s_add_u32 s22, s0, 0xfffc0080
	s_addc_u32 s23, s1, -1
	s_add_i32 s28, 0, 0x10000
	s_cmp_eq_u32 s51, 12
	s_cselect_b32 s25, s14, s23
	s_cselect_b32 s24, s15, s22
	v_add_u32_e32 v138, s28, v141
	s_cselect_b32 s23, s9, s50
	s_cselect_b32 s22, s38, s43
	s_add_i32 s30, 0, 0x14000
	ds_read_b128 v[134:137], v138
	ds_read_b128 v[144:147], v138 offset:1024
	ds_read_b128 v[148:151], v138 offset:2048
	ds_read_b128 v[152:155], v138 offset:3072
	v_add_u32_e32 v138, s30, v141
	ds_read_b128 v[156:159], v138
	ds_read_b128 v[160:163], v138 offset:1024
	ds_read_b128 v[164:167], v138 offset:2048
	ds_read_b128 v[168:171], v138 offset:3072
	s_add_i32 m0, s21, 0xc000
	ds_read_b128 v[172:175], v143
	ds_read_b128 v[176:179], v143 offset:1024
	ds_read_b128 v[180:183], v143 offset:2048
	ds_read_b128 v[184:187], v143 offset:3072
	ds_read_b128 v[188:191], v143 offset:4096
	ds_read_b128 v[192:195], v143 offset:5120
	ds_read_b128 v[196:199], v143 offset:6144
	ds_read_b128 v[200:203], v143 offset:7168
	global_load_lds_dwordx4 v130, s[0:1]
	s_add_i32 m0, s21, 0xe000
	s_nop 0
	global_load_lds_dwordx4 v132, s[0:1]
	s_waitcnt vmcnt(8)
	s_waitcnt lgkmcnt(0)
	s_barrier
	s_waitcnt lgkmcnt(0)
	v_mfma_f32_16x16x32_bf16 v[124:127], v[134:137], v[172:175], v[124:127]
	v_mfma_f32_16x16x32_bf16 v[120:123], v[148:151], v[172:175], v[120:123]
	v_mfma_f32_16x16x32_bf16 v[116:119], v[134:137], v[180:183], v[116:119]
	v_mfma_f32_16x16x32_bf16 v[112:115], v[148:151], v[180:183], v[112:115]
	v_mfma_f32_16x16x32_bf16 v[108:111], v[134:137], v[188:191], v[108:111]
	v_mfma_f32_16x16x32_bf16 v[100:103], v[148:151], v[188:191], v[100:103]
	v_mfma_f32_16x16x32_bf16 v[92:95], v[134:137], v[196:199], v[92:95]
	v_mfma_f32_16x16x32_bf16 v[80:83], v[148:151], v[196:199], v[80:83]
	v_mfma_f32_16x16x32_bf16 v[124:127], v[144:147], v[176:179], v[124:127]
	v_mfma_f32_16x16x32_bf16 v[120:123], v[152:155], v[176:179], v[120:123]
	v_mfma_f32_16x16x32_bf16 v[116:119], v[144:147], v[184:187], v[116:119]
	v_mfma_f32_16x16x32_bf16 v[112:115], v[152:155], v[184:187], v[112:115]
	v_mfma_f32_16x16x32_bf16 v[108:111], v[144:147], v[192:195], v[108:111]
	v_mfma_f32_16x16x32_bf16 v[100:103], v[152:155], v[192:195], v[100:103]
	v_mfma_f32_16x16x32_bf16 v[92:95], v[144:147], v[200:203], v[92:95]
	v_mfma_f32_16x16x32_bf16 v[80:83], v[152:155], v[200:203], v[80:83]
	v_mfma_f32_16x16x32_bf16 v[104:107], v[156:159], v[172:175], v[104:107]
	v_mfma_f32_16x16x32_bf16 v[96:99], v[164:167], v[172:175], v[96:99]
	v_mfma_f32_16x16x32_bf16 v[88:91], v[156:159], v[180:183], v[88:91]
	v_mfma_f32_16x16x32_bf16 v[84:87], v[164:167], v[180:183], v[84:87]
	v_mfma_f32_16x16x32_bf16 v[76:79], v[156:159], v[188:191], v[76:79]
	v_mfma_f32_16x16x32_bf16 v[72:75], v[164:167], v[188:191], v[72:75]
	v_mfma_f32_16x16x32_bf16 v[68:71], v[156:159], v[196:199], v[68:71]
	v_mfma_f32_16x16x32_bf16 v[64:67], v[164:167], v[196:199], v[64:67]
	v_mfma_f32_16x16x32_bf16 v[104:107], v[160:163], v[176:179], v[104:107]
	v_mfma_f32_16x16x32_bf16 v[96:99], v[168:171], v[176:179], v[96:99]
	v_mfma_f32_16x16x32_bf16 v[88:91], v[160:163], v[184:187], v[88:91]
	v_mfma_f32_16x16x32_bf16 v[84:87], v[168:171], v[184:187], v[84:87]
	v_mfma_f32_16x16x32_bf16 v[76:79], v[160:163], v[192:195], v[76:79]
	v_mfma_f32_16x16x32_bf16 v[72:75], v[168:171], v[192:195], v[72:75]
	v_mfma_f32_16x16x32_bf16 v[68:71], v[160:163], v[200:203], v[68:71]
	v_mfma_f32_16x16x32_bf16 v[64:67], v[168:171], v[200:203], v[64:67]
	s_barrier
	s_add_i32 s28, s28, s19
	v_lshl_add_u64 v[138:139], s[22:23], 0, v[208:209]
	s_mov_b32 m0, s28
	s_nop 0
	global_load_lds_dwordx4 v208, s[22:23]
	s_add_i32 m0, s28, 0x2000
	s_add_u32 s28, s22, 0x40000
	v_lshl_add_u64 v[204:205], s[22:23], 0, v[128:129]
	s_addc_u32 s29, s23, 0
	s_add_i32 s30, s30, s19
	global_load_lds_dwordx4 v128, s[22:23]
	s_mov_b32 m0, s30
	v_lshl_add_u64 v[210:211], s[24:25], 0, v[128:129]
	global_load_lds_dwordx4 v208, s[28:29]
	s_add_i32 m0, s30, 0x2000
	s_nop 0
	global_load_lds_dwordx4 v128, s[28:29]
	v_lshl_add_u64 v[206:207], s[24:25], 0, v[208:209]
	s_mov_b32 m0, s21
	s_nop 0
	global_load_lds_dwordx4 v208, s[24:25]
	s_mov_b32 m0, s26
	s_nop 0
	global_load_lds_dwordx4 v128, s[24:25]
	ds_read_b128 v[172:175], v143 offset:16384
	ds_read_b128 v[176:179], v143 offset:17408
	ds_read_b128 v[180:183], v143 offset:18432
	ds_read_b128 v[184:187], v143 offset:19456
	ds_read_b128 v[188:191], v143 offset:20480
	ds_read_b128 v[192:195], v143 offset:21504
	ds_read_b128 v[196:199], v143 offset:22528
	ds_read_b128 v[200:203], v143 offset:23552
	s_waitcnt vmcnt(8)
	s_waitcnt lgkmcnt(0)
	s_barrier
; #define PG8_STAGE(bufoff, gbase, voff) do { _Pragma("unroll") for (int _i = 0; _i < 2; ++_i) \
;         __builtin_amdgcn_global_load_lds((const unsigned*)((const char*)(gbase) + (voff)[_i]), (PG8_LAS unsigned*)(lds + (bufoff) + ldsw + _i * 8192), 16, 0, 0); } while (0)
; #define PG8_LDA(dst, b, h) do { _Pragma("unroll") for (int m = 0; m < 4; ++m) _Pragma("unroll") for (int k = 0; k < 2; ++k) dst[m][k] = *(const PG8_LAS bf16x8*)(lds + PG8_SA(b, h) + aoff + m * 2048 + k * 1024); } while (0)
; #define PG8_LDB(dst, b, h) do { _Pragma("unroll") for (int n = 0; n < 2; ++n) _Pragma("unroll") for (int k = 0; k < 2; ++k) dst[n][k] = *(const PG8_LAS bf16x8*)(lds + PG8_SB(b, h) + boff + n * 2048 + k * 1024); } while (0)
; #define PG8_MMA(ai, bj, At, Bt) do { __builtin_amdgcn_s_setprio(1); _Pragma("unroll") for (int m = 0; m < 4; ++m) _Pragma("unroll") for (int n = 0; n < 2; ++n) _Pragma("unroll") for (int k = 0; k < 2; ++k) \
;         acc[ai][bj][m][n] = __builtin_amdgcn_mfma_f32_16x16x32_bf16(Bt[n][k], At[m][k], acc[ai][bj][m][n], 0, 0, 0); __builtin_amdgcn_s_setprio(0); } while (0)
; #define PG8_WAIT_V(n) asm volatile("s_waitcnt vmcnt(" #n ")" ::: "memory")
; #define PG8_WAIT_L(n) asm volatile("s_waitcnt lgkmcnt(" #n ")" ::: "memory")
; #define PG8_BAR __builtin_amdgcn_s_barrier()
; #define PG8_SCHED __builtin_amdgcn_sched_barrier(0)
; template <class Epi, class Sched, bool ALIGN_EPI = false, bool SP2 = false>
; __device__ __forceinline__ void gemm_phase(PG8_LAS unsigned char* lds, const Gemm g, const Sched& S, const Epi& E) {
;     ...
;             PG8_WAIT_V(8); PG8_WAIT_L(0); PG8_BAR; PG8_MMA(1, 0, At, B0); PG8_MMA(1, 1, At, B1); PG8_BAR; PG8_SCHED;
;             PG8_LDB(B0, 1, 0); PG8_LDB(B1, 1, 1); PG8_SCHED; PG8_LDA(At, 1, 0); PG8_STAGE(PG8_SA(0, 1), a2 + hstepA, voffA);
;             PG8_WAIT_V(8); PG8_WAIT_L(0); PG8_BAR; PG8_MMA(0, 0, At, B0); PG8_MMA(0, 1, At, B1); PG8_BAR; PG8_SCHED;
	s_waitcnt lgkmcnt(0)
	v_mfma_f32_16x16x32_bf16 v[60:63], v[134:137], v[172:175], v[60:63]
	v_mfma_f32_16x16x32_bf16 v[56:59], v[148:151], v[172:175], v[56:59]
	v_mfma_f32_16x16x32_bf16 v[52:55], v[134:137], v[180:183], v[52:55]
	v_mfma_f32_16x16x32_bf16 v[48:51], v[148:151], v[180:183], v[48:51]
	v_mfma_f32_16x16x32_bf16 v[44:47], v[134:137], v[188:191], v[44:47]
	v_mfma_f32_16x16x32_bf16 v[32:35], v[148:151], v[188:191], v[32:35]
	v_mfma_f32_16x16x32_bf16 v[16:19], v[134:137], v[196:199], v[16:19]
	v_mfma_f32_16x16x32_bf16 v[8:11], v[148:151], v[196:199], v[8:11]
	v_mfma_f32_16x16x32_bf16 v[60:63], v[144:147], v[176:179], v[60:63]
	v_mfma_f32_16x16x32_bf16 v[56:59], v[152:155], v[176:179], v[56:59]
	v_mfma_f32_16x16x32_bf16 v[52:55], v[144:147], v[184:187], v[52:55]
	v_mfma_f32_16x16x32_bf16 v[48:51], v[152:155], v[184:187], v[48:51]
	v_mfma_f32_16x16x32_bf16 v[44:47], v[144:147], v[192:195], v[44:47]
	v_mfma_f32_16x16x32_bf16 v[32:35], v[152:155], v[192:195], v[32:35]
	v_mfma_f32_16x16x32_bf16 v[16:19], v[144:147], v[200:203], v[16:19]
	v_mfma_f32_16x16x32_bf16 v[8:11], v[152:155], v[200:203], v[8:11]
	v_mfma_f32_16x16x32_bf16 v[40:43], v[156:159], v[172:175], v[40:43]
	v_mfma_f32_16x16x32_bf16 v[36:39], v[164:167], v[172:175], v[36:39]
	v_mfma_f32_16x16x32_bf16 v[28:31], v[156:159], v[180:183], v[28:31]
	v_mfma_f32_16x16x32_bf16 v[24:27], v[164:167], v[180:183], v[24:27]
	v_mfma_f32_16x16x32_bf16 v[20:23], v[156:159], v[188:191], v[20:23]
	v_mfma_f32_16x16x32_bf16 v[12:15], v[164:167], v[188:191], v[12:15]
	v_mfma_f32_16x16x32_bf16 v[4:7], v[156:159], v[196:199], v[4:7]
	v_mfma_f32_16x16x32_bf16 v[0:3], v[164:167], v[196:199], v[0:3]
	v_mfma_f32_16x16x32_bf16 v[40:43], v[160:163], v[176:179], v[40:43]
	v_mfma_f32_16x16x32_bf16 v[36:39], v[168:171], v[176:179], v[36:39]
	v_mfma_f32_16x16x32_bf16 v[28:31], v[160:163], v[184:187], v[28:31]
	v_mfma_f32_16x16x32_bf16 v[24:27], v[168:171], v[184:187], v[24:27]
	v_mfma_f32_16x16x32_bf16 v[20:23], v[160:163], v[192:195], v[20:23]
	v_mfma_f32_16x16x32_bf16 v[12:15], v[168:171], v[192:195], v[12:15]
	v_mfma_f32_16x16x32_bf16 v[4:7], v[160:163], v[200:203], v[4:7]
	v_mfma_f32_16x16x32_bf16 v[0:3], v[168:171], v[200:203], v[0:3]
	s_barrier
	s_add_i32 s28, 0, 0x18000
	s_add_i32 s29, 0, 0x1c000
	s_add_u32 s24, s24, 0x40000
	s_addc_u32 s25, s25, 0
	s_mov_b32 m0, s34
	s_nop 0
	global_load_lds_dwordx4 v208, s[24:25]
	s_mov_b32 m0, s35
	s_nop 0
	global_load_lds_dwordx4 v128, s[24:25]
	v_add_u32_e32 v152, s28, v141
	v_add_u32_e32 v168, s29, v141
	ds_read_b128 v[134:137], v152
	ds_read_b128 v[144:147], v152 offset:1024
	ds_read_b128 v[148:151], v152 offset:2048
	ds_read_b128 v[152:155], v152 offset:3072
	ds_read_b128 v[156:159], v168
	ds_read_b128 v[160:163], v168 offset:1024
	ds_read_b128 v[164:167], v168 offset:2048
	ds_read_b128 v[168:171], v168 offset:3072
	ds_read_b128 v[172:175], v143 offset:32768
	ds_read_b128 v[176:179], v143 offset:33792
	ds_read_b128 v[180:183], v143 offset:34816
	ds_read_b128 v[184:187], v143 offset:35840
	ds_read_b128 v[188:191], v143 offset:36864
	ds_read_b128 v[192:195], v143 offset:37888
	ds_read_b128 v[196:199], v143 offset:38912
	ds_read_b128 v[200:203], v143 offset:39936
	s_waitcnt vmcnt(8)
	s_waitcnt lgkmcnt(0)
	s_barrier
	s_waitcnt lgkmcnt(0)
	v_mfma_f32_16x16x32_bf16 v[124:127], v[134:137], v[172:175], v[124:127]
	v_mfma_f32_16x16x32_bf16 v[120:123], v[148:151], v[172:175], v[120:123]
	v_mfma_f32_16x16x32_bf16 v[116:119], v[134:137], v[180:183], v[116:119]
	v_mfma_f32_16x16x32_bf16 v[112:115], v[148:151], v[180:183], v[112:115]
	v_mfma_f32_16x16x32_bf16 v[108:111], v[134:137], v[188:191], v[108:111]
	v_mfma_f32_16x16x32_bf16 v[100:103], v[148:151], v[188:191], v[100:103]
	v_mfma_f32_16x16x32_bf16 v[92:95], v[134:137], v[196:199], v[92:95]
	v_mfma_f32_16x16x32_bf16 v[80:83], v[148:151], v[196:199], v[80:83]
	v_mfma_f32_16x16x32_bf16 v[124:127], v[144:147], v[176:179], v[124:127]
	v_mfma_f32_16x16x32_bf16 v[120:123], v[152:155], v[176:179], v[120:123]
	v_mfma_f32_16x16x32_bf16 v[116:119], v[144:147], v[184:187], v[116:119]
	v_mfma_f32_16x16x32_bf16 v[112:115], v[152:155], v[184:187], v[112:115]
	v_mfma_f32_16x16x32_bf16 v[108:111], v[144:147], v[192:195], v[108:111]
	v_mfma_f32_16x16x32_bf16 v[100:103], v[152:155], v[192:195], v[100:103]
	v_mfma_f32_16x16x32_bf16 v[92:95], v[144:147], v[200:203], v[92:95]
	v_mfma_f32_16x16x32_bf16 v[80:83], v[152:155], v[200:203], v[80:83]
	v_mfma_f32_16x16x32_bf16 v[104:107], v[156:159], v[172:175], v[104:107]
	v_mfma_f32_16x16x32_bf16 v[96:99], v[164:167], v[172:175], v[96:99]
	v_mfma_f32_16x16x32_bf16 v[88:91], v[156:159], v[180:183], v[88:91]
	v_mfma_f32_16x16x32_bf16 v[84:87], v[164:167], v[180:183], v[84:87]
	v_mfma_f32_16x16x32_bf16 v[76:79], v[156:159], v[188:191], v[76:79]
	v_mfma_f32_16x16x32_bf16 v[72:75], v[164:167], v[188:191], v[72:75]
	v_mfma_f32_16x16x32_bf16 v[68:71], v[156:159], v[196:199], v[68:71]
	v_mfma_f32_16x16x32_bf16 v[64:67], v[164:167], v[196:199], v[64:67]
	v_mfma_f32_16x16x32_bf16 v[104:107], v[160:163], v[176:179], v[104:107]
	v_mfma_f32_16x16x32_bf16 v[96:99], v[168:171], v[176:179], v[96:99]
	v_mfma_f32_16x16x32_bf16 v[88:91], v[160:163], v[184:187], v[88:91]
	v_mfma_f32_16x16x32_bf16 v[84:87], v[168:171], v[184:187], v[84:87]
	v_mfma_f32_16x16x32_bf16 v[76:79], v[160:163], v[192:195], v[76:79]
	v_mfma_f32_16x16x32_bf16 v[72:75], v[168:171], v[192:195], v[72:75]
	v_mfma_f32_16x16x32_bf16 v[68:71], v[160:163], v[200:203], v[68:71]
	v_mfma_f32_16x16x32_bf16 v[64:67], v[168:171], v[200:203], v[64:67]
	s_barrier
; #define PG8_STAGE(bufoff, gbase, voff) do { _Pragma("unroll") for (int _i = 0; _i < 2; ++_i) \
;         __builtin_amdgcn_global_load_lds((const unsigned*)((const char*)(gbase) + (voff)[_i]), (PG8_LAS unsigned*)(lds + (bufoff) + ldsw + _i * 8192), 16, 0, 0); } while (0)
; #define PG8_LDA(dst, b, h) do { _Pragma("unroll") for (int m = 0; m < 4; ++m) _Pragma("unroll") for (int k = 0; k < 2; ++k) dst[m][k] = *(const PG8_LAS bf16x8*)(lds + PG8_SA(b, h) + aoff + m * 2048 + k * 1024); } while (0)
; #define PG8_MMA(ai, bj, At, Bt) do { __builtin_amdgcn_s_setprio(1); _Pragma("unroll") for (int m = 0; m < 4; ++m) _Pragma("unroll") for (int n = 0; n < 2; ++n) _Pragma("unroll") for (int k = 0; k < 2; ++k) \
;         acc[ai][bj][m][n] = __builtin_amdgcn_mfma_f32_16x16x32_bf16(Bt[n][k], At[m][k], acc[ai][bj][m][n], 0, 0, 0); __builtin_amdgcn_s_setprio(0); } while (0)
; #define PG8_WAIT_V(n) asm volatile("s_waitcnt vmcnt(" #n ")" ::: "memory")
; #define PG8_WAIT_L(n) asm volatile("s_waitcnt lgkmcnt(" #n ")" ::: "memory")
; #define PG8_BAR __builtin_amdgcn_s_barrier()
; #define PG8_SCHED __builtin_amdgcn_sched_barrier(0)
; template <class Epi, class Sched, bool ALIGN_EPI = false, bool SP2 = false>
; __device__ __forceinline__ void gemm_phase(PG8_LAS unsigned char* lds, const Gemm g, const Sched& S, const Epi& E) {
;     ...
;             PG8_LDA(At, 1, 1); PG8_STAGE(PG8_SB(1, 0), b3, voffB); PG8_STAGE(PG8_SB(1, 1), b3 + hstepB, voffB); PG8_STAGE(PG8_SA(1, 0), a3, voffA);
;             PG8_WAIT_V(8); PG8_WAIT_L(0); PG8_BAR; PG8_MMA(1, 0, At, B0); PG8_MMA(1, 1, At, B1); PG8_BAR; PG8_SCHED;
	s_add_i32 s24, s28, s19
	v_lshl_add_u64 v[138:139], v[138:139], 0, s[10:11]
	s_mov_b32 m0, s24
	s_nop 0
	global_load_lds_dwordx4 v[138:139], off
	s_add_i32 m0, s24, 0x2000
	s_add_u32 s22, s22, 0x40080
	v_lshl_add_u64 v[138:139], v[204:205], 0, s[10:11]
	s_addc_u32 s23, s23, 0
	s_add_i32 s24, s29, s19
	global_load_lds_dwordx4 v[138:139], off
	s_mov_b32 m0, s24
	s_nop 0
	global_load_lds_dwordx4 v208, s[22:23]
	s_add_i32 m0, s24, 0x2000
	s_nop 0
	global_load_lds_dwordx4 v128, s[22:23]
	v_lshl_add_u64 v[138:139], v[206:207], 0, s[10:11]
	s_mov_b32 m0, s39
	s_nop 0
	global_load_lds_dwordx4 v[138:139], off
	v_lshl_add_u64 v[138:139], v[210:211], 0, s[10:11]
	s_mov_b32 m0, s48
	s_nop 0
	global_load_lds_dwordx4 v[138:139], off
	ds_read_b128 v[172:175], v143 offset:49152
	ds_read_b128 v[176:179], v143 offset:50176
	ds_read_b128 v[180:183], v143 offset:51200
	ds_read_b128 v[184:187], v143 offset:52224
	ds_read_b128 v[188:191], v143 offset:53248
	ds_read_b128 v[192:195], v143 offset:54272
	ds_read_b128 v[196:199], v143 offset:55296
	ds_read_b128 v[200:203], v143 offset:56320
	s_waitcnt vmcnt(8)
	s_waitcnt lgkmcnt(0)
	s_barrier
	s_waitcnt lgkmcnt(0)
	v_mfma_f32_16x16x32_bf16 v[60:63], v[134:137], v[172:175], v[60:63]
	v_mfma_f32_16x16x32_bf16 v[56:59], v[148:151], v[172:175], v[56:59]
	v_mfma_f32_16x16x32_bf16 v[52:55], v[134:137], v[180:183], v[52:55]
	v_mfma_f32_16x16x32_bf16 v[48:51], v[148:151], v[180:183], v[48:51]
	v_mfma_f32_16x16x32_bf16 v[44:47], v[134:137], v[188:191], v[44:47]
	v_mfma_f32_16x16x32_bf16 v[32:35], v[148:151], v[188:191], v[32:35]
	v_mfma_f32_16x16x32_bf16 v[16:19], v[134:137], v[196:199], v[16:19]
	v_mfma_f32_16x16x32_bf16 v[8:11], v[148:151], v[196:199], v[8:11]
	v_mfma_f32_16x16x32_bf16 v[60:63], v[144:147], v[176:179], v[60:63]
	v_mfma_f32_16x16x32_bf16 v[56:59], v[152:155], v[176:179], v[56:59]
	v_mfma_f32_16x16x32_bf16 v[52:55], v[144:147], v[184:187], v[52:55]
	v_mfma_f32_16x16x32_bf16 v[48:51], v[152:155], v[184:187], v[48:51]
	v_mfma_f32_16x16x32_bf16 v[44:47], v[144:147], v[192:195], v[44:47]
	v_mfma_f32_16x16x32_bf16 v[32:35], v[152:155], v[192:195], v[32:35]
	v_mfma_f32_16x16x32_bf16 v[16:19], v[144:147], v[200:203], v[16:19]
	v_mfma_f32_16x16x32_bf16 v[8:11], v[152:155], v[200:203], v[8:11]
	v_mfma_f32_16x16x32_bf16 v[40:43], v[156:159], v[172:175], v[40:43]
	v_mfma_f32_16x16x32_bf16 v[36:39], v[164:167], v[172:175], v[36:39]
	v_mfma_f32_16x16x32_bf16 v[28:31], v[156:159], v[180:183], v[28:31]
	v_mfma_f32_16x16x32_bf16 v[24:27], v[164:167], v[180:183], v[24:27]
	v_mfma_f32_16x16x32_bf16 v[20:23], v[156:159], v[188:191], v[20:23]
	v_mfma_f32_16x16x32_bf16 v[12:15], v[164:167], v[188:191], v[12:15]
	v_mfma_f32_16x16x32_bf16 v[4:7], v[156:159], v[196:199], v[4:7]
	v_mfma_f32_16x16x32_bf16 v[0:3], v[164:167], v[196:199], v[0:3]
	v_mfma_f32_16x16x32_bf16 v[40:43], v[160:163], v[176:179], v[40:43]
	v_mfma_f32_16x16x32_bf16 v[36:39], v[168:171], v[176:179], v[36:39]
	v_mfma_f32_16x16x32_bf16 v[28:31], v[160:163], v[184:187], v[28:31]
	v_mfma_f32_16x16x32_bf16 v[24:27], v[168:171], v[184:187], v[24:27]
	v_mfma_f32_16x16x32_bf16 v[20:23], v[160:163], v[192:195], v[20:23]
	v_mfma_f32_16x16x32_bf16 v[12:15], v[168:171], v[192:195], v[12:15]
	v_mfma_f32_16x16x32_bf16 v[4:7], v[160:163], v[200:203], v[4:7]
	v_mfma_f32_16x16x32_bf16 v[0:3], v[168:171], v[200:203], v[0:3]
	s_barrier
	s_add_i32 s51, s51, 2
	s_add_u32 s0, s0, 0x100
	s_addc_u32 s1, s1, 0
	s_add_u32 s43, s43, 0x100
	s_addc_u32 s50, s50, 0
	s_cmp_gt_u32 s51, 13
	s_cbranch_scc0 .LBB0_797
	s_and_b64 vcc, exec, s[6:7]
	s_cbranch_vccz .LBB0_800
	s_barrier

; #define PG8_STAGE(bufoff, gbase, voff) do { _Pragma("unroll") for (int _i = 0; _i < 2; ++_i) \
;         __builtin_amdgcn_global_load_lds((const unsigned*)((const char*)(gbase) + (voff)[_i]), (PG8_LAS unsigned*)(lds + (bufoff) + ldsw + _i * 8192), 16, 0, 0); } while (0)
; #define PG8_LDA(dst, b, h) do { _Pragma("unroll") for (int m = 0; m < 4; ++m) _Pragma("unroll") for (int k = 0; k < 2; ++k) dst[m][k] = *(const PG8_LAS bf16x8*)(lds + PG8_SA(b, h) + aoff + m * 2048 + k * 1024); } while (0)
; #define PG8_LDB(dst, b, h) do { _Pragma("unroll") for (int n = 0; n < 2; ++n) _Pragma("unroll") for (int k = 0; k < 2; ++k) dst[n][k] = *(const PG8_LAS bf16x8*)(lds + PG8_SB(b, h) + boff + n * 2048 + k * 1024); } while (0)
; #define PG8_MMA(ai, bj, At, Bt) do { __builtin_amdgcn_s_setprio(1); _Pragma("unroll") for (int m = 0; m < 4; ++m) _Pragma("unroll") for (int n = 0; n < 2; ++n) _Pragma("unroll") for (int k = 0; k < 2; ++k) \
;         acc[ai][bj][m][n] = __builtin_amdgcn_mfma_f32_16x16x32_bf16(Bt[n][k], At[m][k], acc[ai][bj][m][n], 0, 0, 0); __builtin_amdgcn_s_setprio(0); } while (0)
; #define PG8_WAIT_V(n) asm volatile("s_waitcnt vmcnt(" #n ")" ::: "memory")
; #define PG8_WAIT_L(n) asm volatile("s_waitcnt lgkmcnt(" #n ")" ::: "memory")
; #define PG8_BAR __builtin_amdgcn_s_barrier()
; #define PG8_SCHED __builtin_amdgcn_sched_barrier(0)
; template <class Epi, class Sched, bool ALIGN_EPI = false, bool SP2 = false>
; __device__ __forceinline__ void gemm_phase(PG8_LAS unsigned char* lds, const Gemm g, const Sched& S, const Epi& E) {
;     ...
;             PG8_LDB(B0, 0, 0); PG8_LDB(B1, 0, 1); PG8_SCHED; PG8_LDA(At, 0, 0); PG8_STAGE(PG8_SA(1, 1), a1 + hstepA, voffA);
;             PG8_WAIT_V(8); PG8_WAIT_L(0); PG8_BAR; PG8_MMA(0, 0, At, B0); PG8_MMA(0, 1, At, B1); PG8_BAR; PG8_SCHED;
;             PG8_LDA(At, 0, 1); PG8_STAGE(PG8_SB(0, 0), b2, voffB); PG8_STAGE(PG8_SB(0, 1), b2 + hstepB, voffB); PG8_STAGE(PG8_SA(0, 0), a2, voffA);
.LBB0_920:
	s_add_u32 s22, s0, 0xfffc0080
	s_addc_u32 s23, s1, -1
	s_add_i32 s28, 0, 0x10000
	s_cmp_eq_u32 s51, 12
	s_cselect_b32 s25, s14, s23
	s_cselect_b32 s24, s15, s22
	v_add_u32_e32 v138, s28, v141
	s_cselect_b32 s23, s9, s50
	s_cselect_b32 s22, s38, s43
	s_add_i32 s30, 0, 0x14000
	ds_read_b128 v[144:147], v138
	ds_read_b128 v[148:151], v138 offset:1024
	ds_read_b128 v[152:155], v138 offset:2048
	ds_read_b128 v[156:159], v138 offset:3072
	v_add_u32_e32 v138, s30, v141
	ds_read_b128 v[160:163], v138
	ds_read_b128 v[164:167], v138 offset:1024
	ds_read_b128 v[168:171], v138 offset:2048
	ds_read_b128 v[172:175], v138 offset:3072
	s_add_i32 m0, s21, 0xc000
	ds_read_b128 v[176:179], v143
	ds_read_b128 v[180:183], v143 offset:1024
	ds_read_b128 v[184:187], v143 offset:2048
	ds_read_b128 v[188:191], v143 offset:3072
	ds_read_b128 v[192:195], v143 offset:4096
	ds_read_b128 v[196:199], v143 offset:5120
	ds_read_b128 v[200:203], v143 offset:6144
	ds_read_b128 v[204:207], v143 offset:7168
	global_load_lds_dwordx4 v134, s[0:1]
	s_add_i32 m0, s21, 0xe000
	s_nop 0
	global_load_lds_dwordx4 v136, s[0:1]
	s_waitcnt vmcnt(8)
	s_waitcnt lgkmcnt(0)
	s_barrier
	s_waitcnt lgkmcnt(0)
	v_mfma_f32_16x16x32_bf16 v[124:127], v[144:147], v[176:179], v[124:127]
	v_mfma_f32_16x16x32_bf16 v[120:123], v[152:155], v[176:179], v[120:123]
	v_mfma_f32_16x16x32_bf16 v[108:111], v[144:147], v[184:187], v[108:111]
	v_mfma_f32_16x16x32_bf16 v[104:107], v[152:155], v[184:187], v[104:107]
	v_mfma_f32_16x16x32_bf16 v[92:95], v[144:147], v[192:195], v[92:95]
	v_mfma_f32_16x16x32_bf16 v[88:91], v[152:155], v[192:195], v[88:91]
	v_mfma_f32_16x16x32_bf16 v[76:79], v[144:147], v[200:203], v[76:79]
	v_mfma_f32_16x16x32_bf16 v[72:75], v[152:155], v[200:203], v[72:75]
	v_mfma_f32_16x16x32_bf16 v[124:127], v[148:151], v[180:183], v[124:127]
	v_mfma_f32_16x16x32_bf16 v[120:123], v[156:159], v[180:183], v[120:123]
	v_mfma_f32_16x16x32_bf16 v[108:111], v[148:151], v[188:191], v[108:111]
	v_mfma_f32_16x16x32_bf16 v[104:107], v[156:159], v[188:191], v[104:107]
	v_mfma_f32_16x16x32_bf16 v[92:95], v[148:151], v[196:199], v[92:95]
	v_mfma_f32_16x16x32_bf16 v[88:91], v[156:159], v[196:199], v[88:91]
	v_mfma_f32_16x16x32_bf16 v[76:79], v[148:151], v[204:207], v[76:79]
	v_mfma_f32_16x16x32_bf16 v[72:75], v[156:159], v[204:207], v[72:75]
	v_mfma_f32_16x16x32_bf16 v[116:119], v[160:163], v[176:179], v[116:119]
	v_mfma_f32_16x16x32_bf16 v[112:115], v[168:171], v[176:179], v[112:115]
	v_mfma_f32_16x16x32_bf16 v[100:103], v[160:163], v[184:187], v[100:103]
	v_mfma_f32_16x16x32_bf16 v[96:99], v[168:171], v[184:187], v[96:99]
	v_mfma_f32_16x16x32_bf16 v[84:87], v[160:163], v[192:195], v[84:87]
	v_mfma_f32_16x16x32_bf16 v[80:83], v[168:171], v[192:195], v[80:83]
	v_mfma_f32_16x16x32_bf16 v[68:71], v[160:163], v[200:203], v[68:71]
	v_mfma_f32_16x16x32_bf16 v[64:67], v[168:171], v[200:203], v[64:67]
	v_mfma_f32_16x16x32_bf16 v[116:119], v[164:167], v[180:183], v[116:119]
	v_mfma_f32_16x16x32_bf16 v[112:115], v[172:175], v[180:183], v[112:115]
	v_mfma_f32_16x16x32_bf16 v[100:103], v[164:167], v[188:191], v[100:103]
	v_mfma_f32_16x16x32_bf16 v[96:99], v[172:175], v[188:191], v[96:99]
	v_mfma_f32_16x16x32_bf16 v[84:87], v[164:167], v[196:199], v[84:87]
	v_mfma_f32_16x16x32_bf16 v[80:83], v[172:175], v[196:199], v[80:83]
	v_mfma_f32_16x16x32_bf16 v[68:71], v[164:167], v[204:207], v[68:71]
	v_mfma_f32_16x16x32_bf16 v[64:67], v[172:175], v[204:207], v[64:67]
	s_barrier
	s_add_i32 s28, s28, s18
	v_lshl_add_u64 v[138:139], s[22:23], 0, v[208:209]
	s_mov_b32 m0, s28
	s_nop 0
	global_load_lds_dwordx4 v208, s[22:23]
	s_add_i32 m0, s28, 0x2000
	s_add_u32 s28, s22, 0x40000
	v_lshl_add_u64 v[210:211], s[22:23], 0, v[128:129]
	s_addc_u32 s29, s23, 0
	s_add_i32 s30, s30, s18
	global_load_lds_dwordx4 v128, s[22:23]
	s_mov_b32 m0, s30
	v_lshl_add_u64 v[222:223], s[24:25], 0, v[130:131]
	global_load_lds_dwordx4 v208, s[28:29]
	s_add_i32 m0, s30, 0x2000
	s_nop 0
	global_load_lds_dwordx4 v128, s[28:29]
	v_lshl_add_u64 v[212:213], s[24:25], 0, v[132:133]
	s_mov_b32 m0, s21
	s_nop 0
	global_load_lds_dwordx4 v132, s[24:25]
	s_mov_b32 m0, s26
	s_nop 0
	global_load_lds_dwordx4 v130, s[24:25]
	ds_read_b128 v[176:179], v143 offset:16384
	ds_read_b128 v[180:183], v143 offset:17408
	ds_read_b128 v[184:187], v143 offset:18432
	ds_read_b128 v[188:191], v143 offset:19456
	ds_read_b128 v[192:195], v143 offset:20480
	ds_read_b128 v[196:199], v143 offset:21504
	ds_read_b128 v[200:203], v143 offset:22528
	ds_read_b128 v[204:207], v143 offset:23552
	s_waitcnt vmcnt(8)
	s_waitcnt lgkmcnt(0)
	s_barrier
; #define PG8_STAGE(bufoff, gbase, voff) do { _Pragma("unroll") for (int _i = 0; _i < 2; ++_i) \
;         __builtin_amdgcn_global_load_lds((const unsigned*)((const char*)(gbase) + (voff)[_i]), (PG8_LAS unsigned*)(lds + (bufoff) + ldsw + _i * 8192), 16, 0, 0); } while (0)
; #define PG8_LDA(dst, b, h) do { _Pragma("unroll") for (int m = 0; m < 4; ++m) _Pragma("unroll") for (int k = 0; k < 2; ++k) dst[m][k] = *(const PG8_LAS bf16x8*)(lds + PG8_SA(b, h) + aoff + m * 2048 + k * 1024); } while (0)
; #define PG8_LDB(dst, b, h) do { _Pragma("unroll") for (int n = 0; n < 2; ++n) _Pragma("unroll") for (int k = 0; k < 2; ++k) dst[n][k] = *(const PG8_LAS bf16x8*)(lds + PG8_SB(b, h) + boff + n * 2048 + k * 1024); } while (0)
; #define PG8_MMA(ai, bj, At, Bt) do { __builtin_amdgcn_s_setprio(1); _Pragma("unroll") for (int m = 0; m < 4; ++m) _Pragma("unroll") for (int n = 0; n < 2; ++n) _Pragma("unroll") for (int k = 0; k < 2; ++k) \
;         acc[ai][bj][m][n] = __builtin_amdgcn_mfma_f32_16x16x32_bf16(Bt[n][k], At[m][k], acc[ai][bj][m][n], 0, 0, 0); __builtin_amdgcn_s_setprio(0); } while (0)
; #define PG8_WAIT_V(n) asm volatile("s_waitcnt vmcnt(" #n ")" ::: "memory")
; #define PG8_WAIT_L(n) asm volatile("s_waitcnt lgkmcnt(" #n ")" ::: "memory")
; #define PG8_BAR __builtin_amdgcn_s_barrier()
; #define PG8_SCHED __builtin_amdgcn_sched_barrier(0)
; template <class Epi, class Sched, bool ALIGN_EPI = false, bool SP2 = false>
; __device__ __forceinline__ void gemm_phase(PG8_LAS unsigned char* lds, const Gemm g, const Sched& S, const Epi& E) {
;     ...
;             PG8_WAIT_V(8); PG8_WAIT_L(0); PG8_BAR; PG8_MMA(1, 0, At, B0); PG8_MMA(1, 1, At, B1); PG8_BAR; PG8_SCHED;
;             PG8_LDB(B0, 1, 0); PG8_LDB(B1, 1, 1); PG8_SCHED; PG8_LDA(At, 1, 0); PG8_STAGE(PG8_SA(0, 1), a2 + hstepA, voffA);
;             PG8_WAIT_V(8); PG8_WAIT_L(0); PG8_BAR; PG8_MMA(0, 0, At, B0); PG8_MMA(0, 1, At, B1); PG8_BAR; PG8_SCHED;
	s_waitcnt lgkmcnt(0)
	v_mfma_f32_16x16x32_bf16 v[60:63], v[144:147], v[176:179], v[60:63]
	v_mfma_f32_16x16x32_bf16 v[56:59], v[152:155], v[176:179], v[56:59]
	v_mfma_f32_16x16x32_bf16 v[44:47], v[144:147], v[184:187], v[44:47]
	v_mfma_f32_16x16x32_bf16 v[40:43], v[152:155], v[184:187], v[40:43]
	v_mfma_f32_16x16x32_bf16 v[28:31], v[144:147], v[192:195], v[28:31]
	v_mfma_f32_16x16x32_bf16 v[24:27], v[152:155], v[192:195], v[24:27]
	v_mfma_f32_16x16x32_bf16 v[12:15], v[144:147], v[200:203], v[12:15]
	v_mfma_f32_16x16x32_bf16 v[8:11], v[152:155], v[200:203], v[8:11]
	v_mfma_f32_16x16x32_bf16 v[60:63], v[148:151], v[180:183], v[60:63]
	v_mfma_f32_16x16x32_bf16 v[56:59], v[156:159], v[180:183], v[56:59]
	v_mfma_f32_16x16x32_bf16 v[44:47], v[148:151], v[188:191], v[44:47]
	v_mfma_f32_16x16x32_bf16 v[40:43], v[156:159], v[188:191], v[40:43]
	v_mfma_f32_16x16x32_bf16 v[28:31], v[148:151], v[196:199], v[28:31]
	v_mfma_f32_16x16x32_bf16 v[24:27], v[156:159], v[196:199], v[24:27]
	v_mfma_f32_16x16x32_bf16 v[12:15], v[148:151], v[204:207], v[12:15]
	v_mfma_f32_16x16x32_bf16 v[8:11], v[156:159], v[204:207], v[8:11]
	v_mfma_f32_16x16x32_bf16 v[52:55], v[160:163], v[176:179], v[52:55]
	v_mfma_f32_16x16x32_bf16 v[48:51], v[168:171], v[176:179], v[48:51]
	v_mfma_f32_16x16x32_bf16 v[36:39], v[160:163], v[184:187], v[36:39]
	v_mfma_f32_16x16x32_bf16 v[32:35], v[168:171], v[184:187], v[32:35]
	v_mfma_f32_16x16x32_bf16 v[20:23], v[160:163], v[192:195], v[20:23]
	v_mfma_f32_16x16x32_bf16 v[16:19], v[168:171], v[192:195], v[16:19]
	v_mfma_f32_16x16x32_bf16 v[4:7], v[160:163], v[200:203], v[4:7]
	v_mfma_f32_16x16x32_bf16 v[0:3], v[168:171], v[200:203], v[0:3]
	v_mfma_f32_16x16x32_bf16 v[52:55], v[164:167], v[180:183], v[52:55]
	v_mfma_f32_16x16x32_bf16 v[48:51], v[172:175], v[180:183], v[48:51]
	v_mfma_f32_16x16x32_bf16 v[36:39], v[164:167], v[188:191], v[36:39]
	v_mfma_f32_16x16x32_bf16 v[32:35], v[172:175], v[188:191], v[32:35]
	v_mfma_f32_16x16x32_bf16 v[20:23], v[164:167], v[196:199], v[20:23]
	v_mfma_f32_16x16x32_bf16 v[16:19], v[172:175], v[196:199], v[16:19]
	v_mfma_f32_16x16x32_bf16 v[4:7], v[164:167], v[204:207], v[4:7]
	v_mfma_f32_16x16x32_bf16 v[0:3], v[172:175], v[204:207], v[0:3]
	s_barrier
	s_add_i32 s28, 0, 0x18000
	s_add_i32 s29, 0, 0x1c000
	s_add_u32 s24, s24, 0x40000
	s_addc_u32 s25, s25, 0
	s_mov_b32 m0, s34
	s_nop 0
	global_load_lds_dwordx4 v132, s[24:25]
	v_lshl_add_u64 v[224:225], s[24:25], 0, v[130:131]
	s_mov_b32 m0, s35
	s_nop 0
	global_load_lds_dwordx4 v130, s[24:25]
	v_add_u32_e32 v156, s28, v141
	v_add_u32_e32 v172, s29, v141
	ds_read_b128 v[144:147], v156
	ds_read_b128 v[148:151], v156 offset:1024
	ds_read_b128 v[152:155], v156 offset:2048
	ds_read_b128 v[156:159], v156 offset:3072
	ds_read_b128 v[160:163], v172
	ds_read_b128 v[164:167], v172 offset:1024
	ds_read_b128 v[168:171], v172 offset:2048
	ds_read_b128 v[172:175], v172 offset:3072
	ds_read_b128 v[176:179], v143 offset:32768
	ds_read_b128 v[180:183], v143 offset:33792
	ds_read_b128 v[184:187], v143 offset:34816
	ds_read_b128 v[188:191], v143 offset:35840
	ds_read_b128 v[192:195], v143 offset:36864
	ds_read_b128 v[196:199], v143 offset:37888
	ds_read_b128 v[200:203], v143 offset:38912
	ds_read_b128 v[204:207], v143 offset:39936
	s_waitcnt vmcnt(8)
	s_waitcnt lgkmcnt(0)
	s_barrier
	s_waitcnt lgkmcnt(0)
	v_mfma_f32_16x16x32_bf16 v[124:127], v[144:147], v[176:179], v[124:127]
	v_mfma_f32_16x16x32_bf16 v[120:123], v[152:155], v[176:179], v[120:123]
	v_mfma_f32_16x16x32_bf16 v[108:111], v[144:147], v[184:187], v[108:111]
	v_mfma_f32_16x16x32_bf16 v[104:107], v[152:155], v[184:187], v[104:107]
	v_mfma_f32_16x16x32_bf16 v[92:95], v[144:147], v[192:195], v[92:95]
	v_mfma_f32_16x16x32_bf16 v[88:91], v[152:155], v[192:195], v[88:91]
	v_mfma_f32_16x16x32_bf16 v[76:79], v[144:147], v[200:203], v[76:79]
	v_mfma_f32_16x16x32_bf16 v[72:75], v[152:155], v[200:203], v[72:75]
	v_mfma_f32_16x16x32_bf16 v[124:127], v[148:151], v[180:183], v[124:127]
	v_mfma_f32_16x16x32_bf16 v[120:123], v[156:159], v[180:183], v[120:123]
	v_mfma_f32_16x16x32_bf16 v[108:111], v[148:151], v[188:191], v[108:111]
	v_mfma_f32_16x16x32_bf16 v[104:107], v[156:159], v[188:191], v[104:107]
	v_mfma_f32_16x16x32_bf16 v[92:95], v[148:151], v[196:199], v[92:95]
	v_mfma_f32_16x16x32_bf16 v[88:91], v[156:159], v[196:199], v[88:91]
	v_mfma_f32_16x16x32_bf16 v[76:79], v[148:151], v[204:207], v[76:79]
	v_mfma_f32_16x16x32_bf16 v[72:75], v[156:159], v[204:207], v[72:75]
	v_mfma_f32_16x16x32_bf16 v[116:119], v[160:163], v[176:179], v[116:119]
	v_mfma_f32_16x16x32_bf16 v[112:115], v[168:171], v[176:179], v[112:115]
	v_mfma_f32_16x16x32_bf16 v[100:103], v[160:163], v[184:187], v[100:103]
	v_mfma_f32_16x16x32_bf16 v[96:99], v[168:171], v[184:187], v[96:99]
	v_mfma_f32_16x16x32_bf16 v[84:87], v[160:163], v[192:195], v[84:87]
	v_mfma_f32_16x16x32_bf16 v[80:83], v[168:171], v[192:195], v[80:83]
	v_mfma_f32_16x16x32_bf16 v[68:71], v[160:163], v[200:203], v[68:71]
	v_mfma_f32_16x16x32_bf16 v[64:67], v[168:171], v[200:203], v[64:67]
	v_mfma_f32_16x16x32_bf16 v[116:119], v[164:167], v[180:183], v[116:119]
	v_mfma_f32_16x16x32_bf16 v[112:115], v[172:175], v[180:183], v[112:115]
	v_mfma_f32_16x16x32_bf16 v[100:103], v[164:167], v[188:191], v[100:103]
	v_mfma_f32_16x16x32_bf16 v[96:99], v[172:175], v[188:191], v[96:99]
	v_mfma_f32_16x16x32_bf16 v[84:87], v[164:167], v[196:199], v[84:87]
	v_mfma_f32_16x16x32_bf16 v[80:83], v[172:175], v[196:199], v[80:83]
	v_mfma_f32_16x16x32_bf16 v[68:71], v[164:167], v[204:207], v[68:71]
	v_mfma_f32_16x16x32_bf16 v[64:67], v[172:175], v[204:207], v[64:67]
	s_barrier
; #define PG8_STAGE(bufoff, gbase, voff) do { _Pragma("unroll") for (int _i = 0; _i < 2; ++_i) \
;         __builtin_amdgcn_global_load_lds((const unsigned*)((const char*)(gbase) + (voff)[_i]), (PG8_LAS unsigned*)(lds + (bufoff) + ldsw + _i * 8192), 16, 0, 0); } while (0)
; #define PG8_LDA(dst, b, h) do { _Pragma("unroll") for (int m = 0; m < 4; ++m) _Pragma("unroll") for (int k = 0; k < 2; ++k) dst[m][k] = *(const PG8_LAS bf16x8*)(lds + PG8_SA(b, h) + aoff + m * 2048 + k * 1024); } while (0)
; #define PG8_MMA(ai, bj, At, Bt) do { __builtin_amdgcn_s_setprio(1); _Pragma("unroll") for (int m = 0; m < 4; ++m) _Pragma("unroll") for (int n = 0; n < 2; ++n) _Pragma("unroll") for (int k = 0; k < 2; ++k) \
;         acc[ai][bj][m][n] = __builtin_amdgcn_mfma_f32_16x16x32_bf16(Bt[n][k], At[m][k], acc[ai][bj][m][n], 0, 0, 0); __builtin_amdgcn_s_setprio(0); } while (0)
; #define PG8_WAIT_V(n) asm volatile("s_waitcnt vmcnt(" #n ")" ::: "memory")
; #define PG8_WAIT_L(n) asm volatile("s_waitcnt lgkmcnt(" #n ")" ::: "memory")
; #define PG8_BAR __builtin_amdgcn_s_barrier()
; #define PG8_SCHED __builtin_amdgcn_sched_barrier(0)
; template <class Epi, class Sched, bool ALIGN_EPI = false, bool SP2 = false>
; __device__ __forceinline__ void gemm_phase(PG8_LAS unsigned char* lds, const Gemm g, const Sched& S, const Epi& E) {
;     ...
;             PG8_LDA(At, 1, 1); PG8_STAGE(PG8_SB(1, 0), b3, voffB); PG8_STAGE(PG8_SB(1, 1), b3 + hstepB, voffB); PG8_STAGE(PG8_SA(1, 0), a3, voffA);
;             PG8_WAIT_V(8); PG8_WAIT_L(0); PG8_BAR; PG8_MMA(1, 0, At, B0); PG8_MMA(1, 1, At, B1); PG8_BAR; PG8_SCHED;
	s_add_i32 s24, s28, s18
	v_lshl_add_u64 v[138:139], v[138:139], 0, s[10:11]
	s_mov_b32 m0, s24
	s_nop 0
	global_load_lds_dwordx4 v[138:139], off
	s_add_i32 m0, s24, 0x2000
	s_add_u32 s22, s22, 0x40080
	v_lshl_add_u64 v[138:139], v[210:211], 0, s[10:11]
	s_addc_u32 s23, s23, 0
	s_add_i32 s24, s29, s18
	global_load_lds_dwordx4 v[138:139], off
	s_mov_b32 m0, s24
	s_nop 0
	global_load_lds_dwordx4 v208, s[22:23]
	s_add_i32 m0, s24, 0x2000
	s_nop 0
	global_load_lds_dwordx4 v128, s[22:23]
	v_lshl_add_u64 v[138:139], v[212:213], 0, s[10:11]
	s_mov_b32 m0, s39
	s_nop 0
	global_load_lds_dwordx4 v[138:139], off
	v_lshl_add_u64 v[138:139], v[222:223], 0, s[10:11]
	s_mov_b32 m0, s48
	s_nop 0
	global_load_lds_dwordx4 v[138:139], off
	ds_read_b128 v[176:179], v143 offset:49152
	ds_read_b128 v[180:183], v143 offset:50176
	ds_read_b128 v[184:187], v143 offset:51200
	ds_read_b128 v[188:191], v143 offset:52224
	ds_read_b128 v[192:195], v143 offset:53248
	ds_read_b128 v[196:199], v143 offset:54272
	ds_read_b128 v[200:203], v143 offset:55296
	ds_read_b128 v[204:207], v143 offset:56320
	s_waitcnt vmcnt(8)
	s_waitcnt lgkmcnt(0)
	s_barrier
	s_waitcnt lgkmcnt(0)
	v_mfma_f32_16x16x32_bf16 v[60:63], v[144:147], v[176:179], v[60:63]
	v_mfma_f32_16x16x32_bf16 v[56:59], v[152:155], v[176:179], v[56:59]
	v_mfma_f32_16x16x32_bf16 v[44:47], v[144:147], v[184:187], v[44:47]
	v_mfma_f32_16x16x32_bf16 v[40:43], v[152:155], v[184:187], v[40:43]
	v_mfma_f32_16x16x32_bf16 v[28:31], v[144:147], v[192:195], v[28:31]
	v_mfma_f32_16x16x32_bf16 v[24:27], v[152:155], v[192:195], v[24:27]
	v_mfma_f32_16x16x32_bf16 v[12:15], v[144:147], v[200:203], v[12:15]
	v_mfma_f32_16x16x32_bf16 v[8:11], v[152:155], v[200:203], v[8:11]
	v_mfma_f32_16x16x32_bf16 v[60:63], v[148:151], v[180:183], v[60:63]
	v_mfma_f32_16x16x32_bf16 v[56:59], v[156:159], v[180:183], v[56:59]
	v_mfma_f32_16x16x32_bf16 v[44:47], v[148:151], v[188:191], v[44:47]
	v_mfma_f32_16x16x32_bf16 v[40:43], v[156:159], v[188:191], v[40:43]
	v_mfma_f32_16x16x32_bf16 v[28:31], v[148:151], v[196:199], v[28:31]
	v_mfma_f32_16x16x32_bf16 v[24:27], v[156:159], v[196:199], v[24:27]
	v_mfma_f32_16x16x32_bf16 v[12:15], v[148:151], v[204:207], v[12:15]
	v_mfma_f32_16x16x32_bf16 v[8:11], v[156:159], v[204:207], v[8:11]
	v_mfma_f32_16x16x32_bf16 v[52:55], v[160:163], v[176:179], v[52:55]
	v_mfma_f32_16x16x32_bf16 v[48:51], v[168:171], v[176:179], v[48:51]
	v_mfma_f32_16x16x32_bf16 v[36:39], v[160:163], v[184:187], v[36:39]
	v_mfma_f32_16x16x32_bf16 v[32:35], v[168:171], v[184:187], v[32:35]
	v_mfma_f32_16x16x32_bf16 v[20:23], v[160:163], v[192:195], v[20:23]
	v_mfma_f32_16x16x32_bf16 v[16:19], v[168:171], v[192:195], v[16:19]
	v_mfma_f32_16x16x32_bf16 v[4:7], v[160:163], v[200:203], v[4:7]
	v_mfma_f32_16x16x32_bf16 v[0:3], v[168:171], v[200:203], v[0:3]
	v_mfma_f32_16x16x32_bf16 v[52:55], v[164:167], v[180:183], v[52:55]
	v_mfma_f32_16x16x32_bf16 v[48:51], v[172:175], v[180:183], v[48:51]
	v_mfma_f32_16x16x32_bf16 v[36:39], v[164:167], v[188:191], v[36:39]
	v_mfma_f32_16x16x32_bf16 v[32:35], v[172:175], v[188:191], v[32:35]
	v_mfma_f32_16x16x32_bf16 v[20:23], v[164:167], v[196:199], v[20:23]
	v_mfma_f32_16x16x32_bf16 v[16:19], v[172:175], v[196:199], v[16:19]
	v_mfma_f32_16x16x32_bf16 v[4:7], v[164:167], v[204:207], v[4:7]
	v_mfma_f32_16x16x32_bf16 v[0:3], v[172:175], v[204:207], v[0:3]
	s_barrier
	s_add_i32 s51, s51, 2
	s_add_u32 s0, s0, 0x100
	s_addc_u32 s1, s1, 0
	s_add_u32 s43, s43, 0x100
	s_addc_u32 s50, s50, 0
	s_cmp_gt_u32 s51, 13
	s_cbranch_scc0 .LBB0_920
	s_and_b64 vcc, exec, s[6:7]
	s_cbranch_vccz .LBB0_923
	s_barrier

; #define PG8_STAGE(bufoff, gbase, voff) do { _Pragma("unroll") for (int _i = 0; _i < 2; ++_i) \
;         __builtin_amdgcn_global_load_lds((const unsigned*)((const char*)(gbase) + (voff)[_i]), (PG8_LAS unsigned*)(lds + (bufoff) + ldsw + _i * 8192), 16, 0, 0); } while (0)
; #define PG8_LDA(dst, b, h) do { _Pragma("unroll") for (int m = 0; m < 4; ++m) _Pragma("unroll") for (int k = 0; k < 2; ++k) dst[m][k] = *(const PG8_LAS bf16x8*)(lds + PG8_SA(b, h) + aoff + m * 2048 + k * 1024); } while (0)
; #define PG8_LDB(dst, b, h) do { _Pragma("unroll") for (int n = 0; n < 2; ++n) _Pragma("unroll") for (int k = 0; k < 2; ++k) dst[n][k] = *(const PG8_LAS bf16x8*)(lds + PG8_SB(b, h) + boff + n * 2048 + k * 1024); } while (0)
; #define PG8_MMA(ai, bj, At, Bt) do { __builtin_amdgcn_s_setprio(1); _Pragma("unroll") for (int m = 0; m < 4; ++m) _Pragma("unroll") for (int n = 0; n < 2; ++n) _Pragma("unroll") for (int k = 0; k < 2; ++k) \
;         acc[ai][bj][m][n] = __builtin_amdgcn_mfma_f32_16x16x32_bf16(Bt[n][k], At[m][k], acc[ai][bj][m][n], 0, 0, 0); __builtin_amdgcn_s_setprio(0); } while (0)
; #define PG8_WAIT_V(n) asm volatile("s_waitcnt vmcnt(" #n ")" ::: "memory")
; #define PG8_WAIT_L(n) asm volatile("s_waitcnt lgkmcnt(" #n ")" ::: "memory")
; #define PG8_BAR __builtin_amdgcn_s_barrier()
; #define PG8_SCHED __builtin_amdgcn_sched_barrier(0)
; template <class Epi, class Sched, bool ALIGN_EPI = false, bool SP2 = false>
; __device__ __forceinline__ void gemm_phase(PG8_LAS unsigned char* lds, const Gemm g, const Sched& S, const Epi& E) {
;     ...
;             PG8_LDB(B0, 0, 0); PG8_LDB(B1, 0, 1); PG8_SCHED; PG8_LDA(At, 0, 0); PG8_STAGE(PG8_SA(1, 1), a1 + hstepA, voffA);
;             PG8_WAIT_V(8); PG8_WAIT_L(0); PG8_BAR; PG8_MMA(0, 0, At, B0); PG8_MMA(0, 1, At, B1); PG8_BAR; PG8_SCHED;
;             PG8_LDA(At, 0, 1); PG8_STAGE(PG8_SB(0, 0), b2, voffB); PG8_STAGE(PG8_SB(0, 1), b2 + hstepB, voffB); PG8_STAGE(PG8_SA(0, 0), a2, voffA);
.LBB0_1000:
	s_add_u32 s20, s0, 0x100
	s_addc_u32 s21, s1, 0
	s_add_i32 s28, 0, 0x10000
	s_cmp_eq_u32 s49, 40
	s_cselect_b32 s25, s5, s21
	s_cselect_b32 s24, s4, s20
	v_add_u32_e32 v138, s28, v141
	s_cselect_b32 s23, s43, s15
	s_cselect_b32 s22, s42, s14
	s_add_i32 s29, 0, 0x14000
	ds_read_b128 v[134:137], v138
	ds_read_b128 v[144:147], v138 offset:1024
	ds_read_b128 v[148:151], v138 offset:2048
	ds_read_b128 v[152:155], v138 offset:3072
	v_add_u32_e32 v138, s29, v141
	ds_read_b128 v[156:159], v138
	ds_read_b128 v[160:163], v138 offset:1024
	ds_read_b128 v[164:167], v138 offset:2048
	ds_read_b128 v[168:171], v138 offset:3072
	v_lshl_add_u64 v[138:139], s[0:1], 0, v[130:131]
	s_add_i32 m0, s26, 0xc000
	ds_read_b128 v[172:175], v143
	ds_read_b128 v[176:179], v143 offset:1024
	ds_read_b128 v[180:183], v143 offset:2048
	ds_read_b128 v[184:187], v143 offset:3072
	ds_read_b128 v[188:191], v143 offset:4096
	ds_read_b128 v[192:195], v143 offset:5120
	ds_read_b128 v[196:199], v143 offset:6144
	ds_read_b128 v[200:203], v143 offset:7168
	global_load_lds_dwordx4 v[138:139], off
	v_lshl_add_u64 v[138:139], s[0:1], 0, v[132:133]
	s_add_i32 m0, s26, 0xe000
	s_nop 0
	global_load_lds_dwordx4 v[138:139], off
	s_waitcnt vmcnt(8)
	s_waitcnt lgkmcnt(0)
	s_barrier
	s_waitcnt lgkmcnt(0)
	v_mfma_f32_16x16x32_bf16 v[124:127], v[134:137], v[172:175], v[124:127]
	v_mfma_f32_16x16x32_bf16 v[120:123], v[148:151], v[172:175], v[120:123]
	v_mfma_f32_16x16x32_bf16 v[116:119], v[134:137], v[180:183], v[116:119]
	v_mfma_f32_16x16x32_bf16 v[112:115], v[148:151], v[180:183], v[112:115]
	v_mfma_f32_16x16x32_bf16 v[108:111], v[134:137], v[188:191], v[108:111]
	v_mfma_f32_16x16x32_bf16 v[100:103], v[148:151], v[188:191], v[100:103]
	v_mfma_f32_16x16x32_bf16 v[92:95], v[134:137], v[196:199], v[92:95]
	v_mfma_f32_16x16x32_bf16 v[80:83], v[148:151], v[196:199], v[80:83]
	v_mfma_f32_16x16x32_bf16 v[124:127], v[144:147], v[176:179], v[124:127]
	v_mfma_f32_16x16x32_bf16 v[120:123], v[152:155], v[176:179], v[120:123]
	v_mfma_f32_16x16x32_bf16 v[116:119], v[144:147], v[184:187], v[116:119]
	v_mfma_f32_16x16x32_bf16 v[112:115], v[152:155], v[184:187], v[112:115]
	v_mfma_f32_16x16x32_bf16 v[108:111], v[144:147], v[192:195], v[108:111]
	v_mfma_f32_16x16x32_bf16 v[100:103], v[152:155], v[192:195], v[100:103]
	v_mfma_f32_16x16x32_bf16 v[92:95], v[144:147], v[200:203], v[92:95]
	v_mfma_f32_16x16x32_bf16 v[80:83], v[152:155], v[200:203], v[80:83]
	v_mfma_f32_16x16x32_bf16 v[104:107], v[156:159], v[172:175], v[104:107]
	v_mfma_f32_16x16x32_bf16 v[96:99], v[164:167], v[172:175], v[96:99]
	v_mfma_f32_16x16x32_bf16 v[88:91], v[156:159], v[180:183], v[88:91]
	v_mfma_f32_16x16x32_bf16 v[84:87], v[164:167], v[180:183], v[84:87]
	v_mfma_f32_16x16x32_bf16 v[76:79], v[156:159], v[188:191], v[76:79]
	v_mfma_f32_16x16x32_bf16 v[72:75], v[164:167], v[188:191], v[72:75]
	v_mfma_f32_16x16x32_bf16 v[68:71], v[156:159], v[196:199], v[68:71]
	v_mfma_f32_16x16x32_bf16 v[64:67], v[164:167], v[196:199], v[64:67]
	v_mfma_f32_16x16x32_bf16 v[104:107], v[160:163], v[176:179], v[104:107]
	v_mfma_f32_16x16x32_bf16 v[96:99], v[168:171], v[176:179], v[96:99]
	v_mfma_f32_16x16x32_bf16 v[88:91], v[160:163], v[184:187], v[88:91]
	v_mfma_f32_16x16x32_bf16 v[84:87], v[168:171], v[184:187], v[84:87]
	v_mfma_f32_16x16x32_bf16 v[76:79], v[160:163], v[192:195], v[76:79]
	v_mfma_f32_16x16x32_bf16 v[72:75], v[168:171], v[192:195], v[72:75]
	v_mfma_f32_16x16x32_bf16 v[68:71], v[160:163], v[200:203], v[68:71]
	v_mfma_f32_16x16x32_bf16 v[64:67], v[168:171], v[200:203], v[64:67]
	s_barrier
	s_add_i32 s0, s28, s19
	v_lshl_add_u64 v[138:139], s[22:23], 0, v[208:209]
	s_mov_b32 m0, s0
	s_nop 0
	global_load_lds_dwordx4 v208, s[22:23]
	s_add_i32 m0, s0, 0x2000
	s_add_u32 s0, s22, 0xb0000
	v_lshl_add_u64 v[204:205], s[22:23], 0, v[128:129]
	s_addc_u32 s1, s23, 0
	s_add_i32 s28, s29, s19
	global_load_lds_dwordx4 v128, s[22:23]
	s_mov_b32 m0, s28
	v_lshl_add_u64 v[210:211], s[24:25], 0, v[128:129]
	global_load_lds_dwordx4 v208, s[0:1]
	s_add_i32 m0, s28, 0x2000
	s_nop 0
	global_load_lds_dwordx4 v128, s[0:1]
	v_lshl_add_u64 v[206:207], s[24:25], 0, v[208:209]
	s_mov_b32 m0, s26
	s_nop 0
	global_load_lds_dwordx4 v208, s[24:25]
	s_mov_b32 m0, s34
	s_nop 0
	global_load_lds_dwordx4 v128, s[24:25]
	ds_read_b128 v[172:175], v143 offset:16384
	ds_read_b128 v[176:179], v143 offset:17408
	ds_read_b128 v[180:183], v143 offset:18432
	ds_read_b128 v[184:187], v143 offset:19456
	ds_read_b128 v[188:191], v143 offset:20480
	ds_read_b128 v[192:195], v143 offset:21504
	ds_read_b128 v[196:199], v143 offset:22528
	ds_read_b128 v[200:203], v143 offset:23552
	s_waitcnt vmcnt(8)
	s_waitcnt lgkmcnt(0)
	s_barrier
; #define PG8_STAGE(bufoff, gbase, voff) do { _Pragma("unroll") for (int _i = 0; _i < 2; ++_i) \
;         __builtin_amdgcn_global_load_lds((const unsigned*)((const char*)(gbase) + (voff)[_i]), (PG8_LAS unsigned*)(lds + (bufoff) + ldsw + _i * 8192), 16, 0, 0); } while (0)
; #define PG8_LDA(dst, b, h) do { _Pragma("unroll") for (int m = 0; m < 4; ++m) _Pragma("unroll") for (int k = 0; k < 2; ++k) dst[m][k] = *(const PG8_LAS bf16x8*)(lds + PG8_SA(b, h) + aoff + m * 2048 + k * 1024); } while (0)
; #define PG8_LDB(dst, b, h) do { _Pragma("unroll") for (int n = 0; n < 2; ++n) _Pragma("unroll") for (int k = 0; k < 2; ++k) dst[n][k] = *(const PG8_LAS bf16x8*)(lds + PG8_SB(b, h) + boff + n * 2048 + k * 1024); } while (0)
; #define PG8_MMA(ai, bj, At, Bt) do { __builtin_amdgcn_s_setprio(1); _Pragma("unroll") for (int m = 0; m < 4; ++m) _Pragma("unroll") for (int n = 0; n < 2; ++n) _Pragma("unroll") for (int k = 0; k < 2; ++k) \
;         acc[ai][bj][m][n] = __builtin_amdgcn_mfma_f32_16x16x32_bf16(Bt[n][k], At[m][k], acc[ai][bj][m][n], 0, 0, 0); __builtin_amdgcn_s_setprio(0); } while (0)
; #define PG8_WAIT_V(n) asm volatile("s_waitcnt vmcnt(" #n ")" ::: "memory")
; #define PG8_WAIT_L(n) asm volatile("s_waitcnt lgkmcnt(" #n ")" ::: "memory")
; #define PG8_BAR __builtin_amdgcn_s_barrier()
; #define PG8_SCHED __builtin_amdgcn_sched_barrier(0)
; template <class Epi, class Sched, bool ALIGN_EPI = false, bool SP2 = false>
; __device__ __forceinline__ void gemm_phase(PG8_LAS unsigned char* lds, const Gemm g, const Sched& S, const Epi& E) {
;     ...
;             PG8_WAIT_V(8); PG8_WAIT_L(0); PG8_BAR; PG8_MMA(1, 0, At, B0); PG8_MMA(1, 1, At, B1); PG8_BAR; PG8_SCHED;
;             PG8_LDB(B0, 1, 0); PG8_LDB(B1, 1, 1); PG8_SCHED; PG8_LDA(At, 1, 0); PG8_STAGE(PG8_SA(0, 1), a2 + hstepA, voffA);
;             PG8_WAIT_V(8); PG8_WAIT_L(0); PG8_BAR; PG8_MMA(0, 0, At, B0); PG8_MMA(0, 1, At, B1); PG8_BAR; PG8_SCHED;
	s_waitcnt lgkmcnt(0)
	v_mfma_f32_16x16x32_bf16 v[60:63], v[134:137], v[172:175], v[60:63]
	v_mfma_f32_16x16x32_bf16 v[56:59], v[148:151], v[172:175], v[56:59]
	v_mfma_f32_16x16x32_bf16 v[52:55], v[134:137], v[180:183], v[52:55]
	v_mfma_f32_16x16x32_bf16 v[48:51], v[148:151], v[180:183], v[48:51]
	v_mfma_f32_16x16x32_bf16 v[44:47], v[134:137], v[188:191], v[44:47]
	v_mfma_f32_16x16x32_bf16 v[32:35], v[148:151], v[188:191], v[32:35]
	v_mfma_f32_16x16x32_bf16 v[16:19], v[134:137], v[196:199], v[16:19]
	v_mfma_f32_16x16x32_bf16 v[8:11], v[148:151], v[196:199], v[8:11]
	v_mfma_f32_16x16x32_bf16 v[60:63], v[144:147], v[176:179], v[60:63]
	v_mfma_f32_16x16x32_bf16 v[56:59], v[152:155], v[176:179], v[56:59]
	v_mfma_f32_16x16x32_bf16 v[52:55], v[144:147], v[184:187], v[52:55]
	v_mfma_f32_16x16x32_bf16 v[48:51], v[152:155], v[184:187], v[48:51]
	v_mfma_f32_16x16x32_bf16 v[44:47], v[144:147], v[192:195], v[44:47]
	v_mfma_f32_16x16x32_bf16 v[32:35], v[152:155], v[192:195], v[32:35]
	v_mfma_f32_16x16x32_bf16 v[16:19], v[144:147], v[200:203], v[16:19]
	v_mfma_f32_16x16x32_bf16 v[8:11], v[152:155], v[200:203], v[8:11]
	v_mfma_f32_16x16x32_bf16 v[40:43], v[156:159], v[172:175], v[40:43]
	v_mfma_f32_16x16x32_bf16 v[36:39], v[164:167], v[172:175], v[36:39]
	v_mfma_f32_16x16x32_bf16 v[28:31], v[156:159], v[180:183], v[28:31]
	v_mfma_f32_16x16x32_bf16 v[24:27], v[164:167], v[180:183], v[24:27]
	v_mfma_f32_16x16x32_bf16 v[20:23], v[156:159], v[188:191], v[20:23]
	v_mfma_f32_16x16x32_bf16 v[12:15], v[164:167], v[188:191], v[12:15]
	v_mfma_f32_16x16x32_bf16 v[4:7], v[156:159], v[196:199], v[4:7]
	v_mfma_f32_16x16x32_bf16 v[0:3], v[164:167], v[196:199], v[0:3]
	v_mfma_f32_16x16x32_bf16 v[40:43], v[160:163], v[176:179], v[40:43]
	v_mfma_f32_16x16x32_bf16 v[36:39], v[168:171], v[176:179], v[36:39]
	v_mfma_f32_16x16x32_bf16 v[28:31], v[160:163], v[184:187], v[28:31]
	v_mfma_f32_16x16x32_bf16 v[24:27], v[168:171], v[184:187], v[24:27]
	v_mfma_f32_16x16x32_bf16 v[20:23], v[160:163], v[192:195], v[20:23]
	v_mfma_f32_16x16x32_bf16 v[12:15], v[168:171], v[192:195], v[12:15]
	v_mfma_f32_16x16x32_bf16 v[4:7], v[160:163], v[200:203], v[4:7]
	v_mfma_f32_16x16x32_bf16 v[0:3], v[168:171], v[200:203], v[0:3]
	s_barrier
	s_add_i32 s28, 0, 0x18000
	s_add_i32 s29, 0, 0x1c000
	s_add_u32 s0, s24, 0xb0000
	s_addc_u32 s1, s25, 0
	s_mov_b32 m0, s35
	s_nop 0
	global_load_lds_dwordx4 v208, s[0:1]
	s_mov_b32 m0, s39
	s_nop 0
	global_load_lds_dwordx4 v128, s[0:1]
	v_add_u32_e32 v152, s28, v141
	v_add_u32_e32 v168, s29, v141
	ds_read_b128 v[134:137], v152
	ds_read_b128 v[144:147], v152 offset:1024
	ds_read_b128 v[148:151], v152 offset:2048
	ds_read_b128 v[152:155], v152 offset:3072
	ds_read_b128 v[156:159], v168
	ds_read_b128 v[160:163], v168 offset:1024
	ds_read_b128 v[164:167], v168 offset:2048
	ds_read_b128 v[168:171], v168 offset:3072
	ds_read_b128 v[172:175], v143 offset:32768
	ds_read_b128 v[176:179], v143 offset:33792
	ds_read_b128 v[180:183], v143 offset:34816
	ds_read_b128 v[184:187], v143 offset:35840
	ds_read_b128 v[188:191], v143 offset:36864
	ds_read_b128 v[192:195], v143 offset:37888
	ds_read_b128 v[196:199], v143 offset:38912
	ds_read_b128 v[200:203], v143 offset:39936
	s_waitcnt vmcnt(8)
	s_waitcnt lgkmcnt(0)
	s_barrier
	s_waitcnt lgkmcnt(0)
	v_mfma_f32_16x16x32_bf16 v[124:127], v[134:137], v[172:175], v[124:127]
	v_mfma_f32_16x16x32_bf16 v[120:123], v[148:151], v[172:175], v[120:123]
	v_mfma_f32_16x16x32_bf16 v[116:119], v[134:137], v[180:183], v[116:119]
	v_mfma_f32_16x16x32_bf16 v[112:115], v[148:151], v[180:183], v[112:115]
	v_mfma_f32_16x16x32_bf16 v[108:111], v[134:137], v[188:191], v[108:111]
	v_mfma_f32_16x16x32_bf16 v[100:103], v[148:151], v[188:191], v[100:103]
	v_mfma_f32_16x16x32_bf16 v[92:95], v[134:137], v[196:199], v[92:95]
	v_mfma_f32_16x16x32_bf16 v[80:83], v[148:151], v[196:199], v[80:83]
	v_mfma_f32_16x16x32_bf16 v[124:127], v[144:147], v[176:179], v[124:127]
	v_mfma_f32_16x16x32_bf16 v[120:123], v[152:155], v[176:179], v[120:123]
	v_mfma_f32_16x16x32_bf16 v[116:119], v[144:147], v[184:187], v[116:119]
	v_mfma_f32_16x16x32_bf16 v[112:115], v[152:155], v[184:187], v[112:115]
	v_mfma_f32_16x16x32_bf16 v[108:111], v[144:147], v[192:195], v[108:111]
	v_mfma_f32_16x16x32_bf16 v[100:103], v[152:155], v[192:195], v[100:103]
	v_mfma_f32_16x16x32_bf16 v[92:95], v[144:147], v[200:203], v[92:95]
	v_mfma_f32_16x16x32_bf16 v[80:83], v[152:155], v[200:203], v[80:83]
	v_mfma_f32_16x16x32_bf16 v[104:107], v[156:159], v[172:175], v[104:107]
	v_mfma_f32_16x16x32_bf16 v[96:99], v[164:167], v[172:175], v[96:99]
	v_mfma_f32_16x16x32_bf16 v[88:91], v[156:159], v[180:183], v[88:91]
	v_mfma_f32_16x16x32_bf16 v[84:87], v[164:167], v[180:183], v[84:87]
	v_mfma_f32_16x16x32_bf16 v[76:79], v[156:159], v[188:191], v[76:79]
	v_mfma_f32_16x16x32_bf16 v[72:75], v[164:167], v[188:191], v[72:75]
	v_mfma_f32_16x16x32_bf16 v[68:71], v[156:159], v[196:199], v[68:71]
	v_mfma_f32_16x16x32_bf16 v[64:67], v[164:167], v[196:199], v[64:67]
	v_mfma_f32_16x16x32_bf16 v[104:107], v[160:163], v[176:179], v[104:107]
	v_mfma_f32_16x16x32_bf16 v[96:99], v[168:171], v[176:179], v[96:99]
	v_mfma_f32_16x16x32_bf16 v[88:91], v[160:163], v[184:187], v[88:91]
	v_mfma_f32_16x16x32_bf16 v[84:87], v[168:171], v[184:187], v[84:87]
	v_mfma_f32_16x16x32_bf16 v[76:79], v[160:163], v[192:195], v[76:79]
	v_mfma_f32_16x16x32_bf16 v[72:75], v[168:171], v[192:195], v[72:75]
	v_mfma_f32_16x16x32_bf16 v[68:71], v[160:163], v[200:203], v[68:71]
	v_mfma_f32_16x16x32_bf16 v[64:67], v[168:171], v[200:203], v[64:67]
	s_barrier
; #define PG8_STAGE(bufoff, gbase, voff) do { _Pragma("unroll") for (int _i = 0; _i < 2; ++_i) \
;         __builtin_amdgcn_global_load_lds((const unsigned*)((const char*)(gbase) + (voff)[_i]), (PG8_LAS unsigned*)(lds + (bufoff) + ldsw + _i * 8192), 16, 0, 0); } while (0)
; #define PG8_LDA(dst, b, h) do { _Pragma("unroll") for (int m = 0; m < 4; ++m) _Pragma("unroll") for (int k = 0; k < 2; ++k) dst[m][k] = *(const PG8_LAS bf16x8*)(lds + PG8_SA(b, h) + aoff + m * 2048 + k * 1024); } while (0)
; #define PG8_MMA(ai, bj, At, Bt) do { __builtin_amdgcn_s_setprio(1); _Pragma("unroll") for (int m = 0; m < 4; ++m) _Pragma("unroll") for (int n = 0; n < 2; ++n) _Pragma("unroll") for (int k = 0; k < 2; ++k) \
;         acc[ai][bj][m][n] = __builtin_amdgcn_mfma_f32_16x16x32_bf16(Bt[n][k], At[m][k], acc[ai][bj][m][n], 0, 0, 0); __builtin_amdgcn_s_setprio(0); } while (0)
; #define PG8_WAIT_V(n) asm volatile("s_waitcnt vmcnt(" #n ")" ::: "memory")
; #define PG8_WAIT_L(n) asm volatile("s_waitcnt lgkmcnt(" #n ")" ::: "memory")
; #define PG8_BAR __builtin_amdgcn_s_barrier()
; #define PG8_SCHED __builtin_amdgcn_sched_barrier(0)
; template <class Epi, class Sched, bool ALIGN_EPI = false, bool SP2 = false>
; __device__ __forceinline__ void gemm_phase(PG8_LAS unsigned char* lds, const Gemm g, const Sched& S, const Epi& E) {
;     ...
;             PG8_LDA(At, 1, 1); PG8_STAGE(PG8_SB(1, 0), b3, voffB); PG8_STAGE(PG8_SB(1, 1), b3 + hstepB, voffB); PG8_STAGE(PG8_SA(1, 0), a3, voffA);
;             PG8_WAIT_V(8); PG8_WAIT_L(0); PG8_BAR; PG8_MMA(1, 0, At, B0); PG8_MMA(1, 1, At, B1); PG8_BAR; PG8_SCHED;
	s_add_i32 s0, s28, s19
	v_lshl_add_u64 v[138:139], v[138:139], 0, s[10:11]
	s_mov_b32 m0, s0
	s_nop 0
	global_load_lds_dwordx4 v[138:139], off
	s_add_i32 m0, s0, 0x2000
	s_add_u32 s0, s22, 0xb0080
	v_lshl_add_u64 v[138:139], v[204:205], 0, s[10:11]
	s_addc_u32 s1, s23, 0
	s_add_i32 s22, s29, s19
	global_load_lds_dwordx4 v[138:139], off
	s_mov_b32 m0, s22
	s_nop 0
	global_load_lds_dwordx4 v208, s[0:1]
	s_add_i32 m0, s22, 0x2000
	s_nop 0
	global_load_lds_dwordx4 v128, s[0:1]
	v_lshl_add_u64 v[138:139], v[206:207], 0, s[10:11]
	s_mov_b32 m0, s44
	s_nop 0
	global_load_lds_dwordx4 v[138:139], off
	v_lshl_add_u64 v[138:139], v[210:211], 0, s[10:11]
	s_mov_b32 m0, s45
	s_nop 0
	global_load_lds_dwordx4 v[138:139], off
	ds_read_b128 v[172:175], v143 offset:49152
	ds_read_b128 v[176:179], v143 offset:50176
	ds_read_b128 v[180:183], v143 offset:51200
	ds_read_b128 v[184:187], v143 offset:52224
	ds_read_b128 v[188:191], v143 offset:53248
	ds_read_b128 v[192:195], v143 offset:54272
	ds_read_b128 v[196:199], v143 offset:55296
	ds_read_b128 v[200:203], v143 offset:56320
	s_waitcnt vmcnt(8)
	s_waitcnt lgkmcnt(0)
	s_barrier
	s_waitcnt lgkmcnt(0)
	v_mfma_f32_16x16x32_bf16 v[60:63], v[134:137], v[172:175], v[60:63]
	v_mfma_f32_16x16x32_bf16 v[56:59], v[148:151], v[172:175], v[56:59]
	v_mfma_f32_16x16x32_bf16 v[52:55], v[134:137], v[180:183], v[52:55]
	v_mfma_f32_16x16x32_bf16 v[48:51], v[148:151], v[180:183], v[48:51]
	v_mfma_f32_16x16x32_bf16 v[44:47], v[134:137], v[188:191], v[44:47]
	v_mfma_f32_16x16x32_bf16 v[32:35], v[148:151], v[188:191], v[32:35]
	v_mfma_f32_16x16x32_bf16 v[16:19], v[134:137], v[196:199], v[16:19]
	v_mfma_f32_16x16x32_bf16 v[8:11], v[148:151], v[196:199], v[8:11]
	v_mfma_f32_16x16x32_bf16 v[60:63], v[144:147], v[176:179], v[60:63]
	v_mfma_f32_16x16x32_bf16 v[56:59], v[152:155], v[176:179], v[56:59]
	v_mfma_f32_16x16x32_bf16 v[52:55], v[144:147], v[184:187], v[52:55]
	v_mfma_f32_16x16x32_bf16 v[48:51], v[152:155], v[184:187], v[48:51]
	v_mfma_f32_16x16x32_bf16 v[44:47], v[144:147], v[192:195], v[44:47]
	v_mfma_f32_16x16x32_bf16 v[32:35], v[152:155], v[192:195], v[32:35]
	v_mfma_f32_16x16x32_bf16 v[16:19], v[144:147], v[200:203], v[16:19]
	v_mfma_f32_16x16x32_bf16 v[8:11], v[152:155], v[200:203], v[8:11]
	v_mfma_f32_16x16x32_bf16 v[40:43], v[156:159], v[172:175], v[40:43]
	v_mfma_f32_16x16x32_bf16 v[36:39], v[164:167], v[172:175], v[36:39]
	v_mfma_f32_16x16x32_bf16 v[28:31], v[156:159], v[180:183], v[28:31]
	v_mfma_f32_16x16x32_bf16 v[24:27], v[164:167], v[180:183], v[24:27]
	v_mfma_f32_16x16x32_bf16 v[20:23], v[156:159], v[188:191], v[20:23]
	v_mfma_f32_16x16x32_bf16 v[12:15], v[164:167], v[188:191], v[12:15]
	v_mfma_f32_16x16x32_bf16 v[4:7], v[156:159], v[196:199], v[4:7]
	v_mfma_f32_16x16x32_bf16 v[0:3], v[164:167], v[196:199], v[0:3]
	v_mfma_f32_16x16x32_bf16 v[40:43], v[160:163], v[176:179], v[40:43]
	v_mfma_f32_16x16x32_bf16 v[36:39], v[168:171], v[176:179], v[36:39]
	v_mfma_f32_16x16x32_bf16 v[28:31], v[160:163], v[184:187], v[28:31]
	v_mfma_f32_16x16x32_bf16 v[24:27], v[168:171], v[184:187], v[24:27]
	v_mfma_f32_16x16x32_bf16 v[20:23], v[160:163], v[192:195], v[20:23]
	v_mfma_f32_16x16x32_bf16 v[12:15], v[168:171], v[192:195], v[12:15]
	v_mfma_f32_16x16x32_bf16 v[4:7], v[160:163], v[200:203], v[4:7]
	v_mfma_f32_16x16x32_bf16 v[0:3], v[168:171], v[200:203], v[0:3]
	s_barrier
	s_add_i32 s49, s49, 2
	s_add_u32 s14, s14, 0x100
	s_addc_u32 s15, s15, 0
	s_cmp_gt_u32 s49, 41
	s_mov_b64 s[0:1], s[20:21]
	s_cbranch_scc0 .LBB0_1000
	s_and_b64 vcc, exec, s[8:9]
	s_cbranch_vccz .LBB0_1003
	s_barrier
